# v48: v36 + phase A part 1 remapped: its P tile runs as a third tile on blocks 0..31 (none on 128..159), so all 128 sample-stream prep items are claimed at t=0 and the (critical) sample scans start ~13
# speedup vs baseline: 1.0105x; 1.0071x over previous
.La1_mine:
	s_cmpk_ge_u32 s2, 0x80
	s_cbranch_scc1 .LBB0_420
	v_mov_b32_e32 v238, 0x200f0
	ds_read_b64 v[236:237], v238
	s_waitcnt lgkmcnt(0)
	v_readfirstlane_b32 s20, v236
	v_readfirstlane_b32 s21, v237
	s_barrier
	v_and_b32_e32 v236, 63, v0
	v_lshrrev_b32_e32 v237, 6, v0
	v_lshrrev_b32_e32 v238, 3, v236
	v_lshrrev_b32_e32 v239, 4, v236
	s_nop 0
	v_readfirstlane_b32 s0, v237
	v_add_u32_e32 v200, 0, v239
	v_xor_b32_e32 v200, v200, v236
	v_and_b32_e32 v200, 7, v200
	v_lshlrev_b32_e32 v200, 4, v200
	v_lshl_add_u32 v130, v237, 5, v238
	v_add_u32_e32 v130, 0, v130
	v_mul_u32_u24_e32 v130, 0x800, v130
	v_add_u32_e32 v200, v200, v130
	v_add_u32_e32 v201, 4, v239
	v_xor_b32_e32 v201, v201, v236
	v_and_b32_e32 v201, 7, v201
	v_lshlrev_b32_e32 v201, 4, v201
	v_lshl_add_u32 v130, v237, 5, v238
	v_add_u32_e32 v130, 8, v130
	v_mul_u32_u24_e32 v130, 0x800, v130
	v_add_u32_e32 v201, v201, v130
	v_add_u32_e32 v202, 8, v239
	v_xor_b32_e32 v202, v202, v236
	v_and_b32_e32 v202, 7, v202
	v_lshlrev_b32_e32 v202, 4, v202
	v_lshl_add_u32 v130, v237, 5, v238
	v_add_u32_e32 v130, 16, v130
	v_mul_u32_u24_e32 v130, 0x800, v130
	v_add_u32_e32 v202, v202, v130
	v_add_u32_e32 v203, 12, v239
	v_xor_b32_e32 v203, v203, v236
	v_and_b32_e32 v203, 7, v203
	v_lshlrev_b32_e32 v203, 4, v203
	v_lshl_add_u32 v130, v237, 5, v238
	v_add_u32_e32 v130, 24, v130
	v_mul_u32_u24_e32 v130, 0x800, v130
	v_add_u32_e32 v203, v203, v130
	v_add_u32_e32 v204, 0, v239
	v_xor_b32_e32 v204, v204, v236
	v_and_b32_e32 v204, 7, v204
	v_lshlrev_b32_e32 v204, 4, v204
	v_lshl_add_u32 v130, v237, 4, v238
	v_add_u32_e32 v130, 0, v130
	v_mul_u32_u24_e32 v130, 0x800, v130
	v_add_u32_e32 v204, v204, v130
	v_add_u32_e32 v205, 4, v239
	v_xor_b32_e32 v205, v205, v236
	v_and_b32_e32 v205, 7, v205
	v_lshlrev_b32_e32 v205, 4, v205
	v_lshl_add_u32 v130, v237, 4, v238
	v_add_u32_e32 v130, 8, v130
	v_mul_u32_u24_e32 v130, 0x800, v130
	v_add_u32_e32 v205, v205, v130
	v_and_b32_e32 v238, 15, v236
	v_lshrrev_b32_e32 v130, 1, v238
	v_xor_b32_e32 v130, v130, v239
	v_lshlrev_b32_e32 v130, 4, v130
	v_lshrrev_b32_e32 v236, 1, v237
	v_lshl_add_u32 v236, v236, 6, v238
	v_lshl_add_u32 v236, v236, 7, v130
	v_and_b32_e32 v237, 1, v237
	v_lshl_add_u32 v237, v237, 6, v238
	v_lshl_add_u32 v237, v237, 7, v130
	v_add_u32_e32 v218, 0x100, v236
	v_xor_b32_e32 v225, 64, v218
	v_add_u32_e32 v230, 0x8100, v237
	v_xor_b32_e32 v233, 64, v230
	v_add_u32_e32 v219, 0xc100, v236
	v_xor_b32_e32 v228, 64, v219
	v_add_u32_e32 v231, 0x14100, v237
	v_xor_b32_e32 v234, 64, v231
	v_add_u32_e32 v224, 0x18100, v236
	v_xor_b32_e32 v229, 64, v224
	v_add_u32_e32 v232, 0x20100, v237
	v_xor_b32_e32 v235, 64, v232
	s_lshl_b32 s1, s0, 12
	s_add_u32 s8, s1, 0x100
	s_lshl_b32 s1, s0, 11
	s_add_u32 s9, s1, 0x8100
	v_and_b32_e32 v238, 63, v0
	v_lshrrev_b32_e32 v239, 6, v0
	v_and_b32_e32 v1, 15, v238
	v_lshrrev_b32_e32 v238, 4, v238
	v_lshrrev_b32_e32 v130, 1, v239
	v_lshl_add_u32 v1, v130, 6, v1
	v_and_b32_e32 v239, 1, v239
	v_lshlrev_b32_e32 v236, 11, v1
	v_lshl_add_u32 v236, v239, 7, v236
	v_lshl_add_u32 v236, v238, 3, v236
	v_mul_u32_u24_e32 v237, 0x2200, v1
	v_lshl_add_u32 v237, v239, 8, v237
	v_lshl_add_u32 v237, v238, 4, v237
	s_and_b32 s1, s2, 31
	s_lshr_b32 s22, s2, 5
	s_lshl_b32 s23, s1, 19
	s_add_u32 s4, s26, s23
	s_addc_u32 s5, s27, 0
	v_readlane_b32 s6, v254, 57
	v_readlane_b32 s7, v254, 58
	s_lshl_b32 s50, s22, 1
	s_add_u32 s50, s50, 1
	s_cmp_eq_u32 s22, 0
	s_cselect_b32 s50, 0, s50
	s_lshl_b32 s51, s50, 18
	s_add_u32 s51, s51, 0x400000
	s_add_u32 s6, s6, s51
	s_addc_u32 s7, s7, 0
	s_mov_b32 s12, 0xbfb8aa3b
	s_add_u32 s52, s28, 0x4400000
	s_addc_u32 s53, s29, 0
	s_add_u32 s52, s52, s23
	s_addc_u32 s53, s53, 0
	s_lshl_b32 s51, s22, 9
	s_add_u32 s54, s52, s51
	s_addc_u32 s55, s53, 0
	s_cmp_eq_u32 s22, 0
	s_cbranch_scc1 .La1_p
.La1_zz:
	s_mov_b32 m0, s8
	s_nop 0
	global_load_lds_dwordx4 v200, s[4:5]
	s_add_u32 m0, s8, 0x400
	s_nop 0
	global_load_lds_dwordx4 v201, s[4:5]
	s_add_u32 m0, s8, 0x800
	s_nop 0
	global_load_lds_dwordx4 v202, s[4:5]
	s_add_u32 m0, s8, 0xc00
	s_nop 0
	global_load_lds_dwordx4 v203, s[4:5]
	s_mov_b32 m0, s9
	s_nop 0
	global_load_lds_dwordx4 v204, s[6:7]
	s_add_u32 m0, s9, 0x400
	s_nop 0
	global_load_lds_dwordx4 v205, s[6:7]
	s_add_u32 s4, s4, 0x80
	s_addc_u32 s5, s5, 0
	s_add_u32 s6, s6, 0x80
	s_addc_u32 s7, s7, 0
	s_add_u32 m0, s8, 0xc000
	s_nop 0
	global_load_lds_dwordx4 v200, s[4:5]
	s_add_u32 m0, s8, 0xc400
	s_nop 0
	global_load_lds_dwordx4 v201, s[4:5]
	s_add_u32 m0, s8, 0xc800
	s_nop 0
	global_load_lds_dwordx4 v202, s[4:5]
	s_add_u32 m0, s8, 0xcc00
	s_nop 0
	global_load_lds_dwordx4 v203, s[4:5]
	s_add_u32 m0, s9, 0xc000
	s_nop 0
	global_load_lds_dwordx4 v204, s[6:7]
	s_add_u32 m0, s9, 0xc400
	s_nop 0
	global_load_lds_dwordx4 v205, s[6:7]
	s_add_u32 s4, s4, 0x80
	s_addc_u32 s5, s5, 0
	s_add_u32 s6, s6, 0x80
	s_addc_u32 s7, s7, 0
	s_add_u32 m0, s8, 0x18000
	s_nop 0
	global_load_lds_dwordx4 v200, s[4:5]
	s_add_u32 m0, s8, 0x18400
	s_nop 0
	global_load_lds_dwordx4 v201, s[4:5]
	s_add_u32 m0, s8, 0x18800
	s_nop 0
	global_load_lds_dwordx4 v202, s[4:5]
	s_add_u32 m0, s8, 0x18c00
	s_nop 0
	global_load_lds_dwordx4 v203, s[4:5]
	s_add_u32 m0, s9, 0x18000
	s_nop 0
	global_load_lds_dwordx4 v204, s[6:7]
	s_add_u32 m0, s9, 0x18400
	s_nop 0
	global_load_lds_dwordx4 v205, s[6:7]
	s_add_u32 s4, s4, 0x80
	s_addc_u32 s5, s5, 0
	s_add_u32 s6, s6, 0x80
	s_addc_u32 s7, s7, 0
	s_waitcnt vmcnt(12)
	s_barrier
	ds_read_b128 v[136:139], v218 offset:0
	ds_read_b128 v[140:143], v218 offset:2048
	ds_read_b128 v[144:147], v218 offset:4096
	ds_read_b128 v[148:151], v218 offset:6144
	ds_read_b128 v[152:155], v230 offset:0
	ds_read_b128 v[156:159], v230 offset:2048
	ds_read_b128 v[160:163], v230 offset:4096
	ds_read_b128 v[164:167], v230 offset:6144
	s_waitcnt lgkmcnt(0)
	v_mfma_f32_16x16x32_bf16 v[2:5], v[152:155], v[136:139], 0
	ds_read_b128 v[168:171], v225 offset:0
	v_mfma_f32_16x16x32_bf16 v[6:9], v[156:159], v[136:139], 0
	ds_read_b128 v[172:175], v225 offset:2048
	v_mfma_f32_16x16x32_bf16 v[10:13], v[160:163], v[136:139], 0
	ds_read_b128 v[176:179], v225 offset:4096
	v_mfma_f32_16x16x32_bf16 v[14:17], v[164:167], v[136:139], 0
	ds_read_b128 v[180:183], v225 offset:6144
	v_mfma_f32_16x16x32_bf16 v[18:21], v[152:155], v[140:143], 0
	ds_read_b128 v[184:187], v233 offset:0
	v_mfma_f32_16x16x32_bf16 v[22:25], v[156:159], v[140:143], 0
	ds_read_b128 v[188:191], v233 offset:2048
	v_mfma_f32_16x16x32_bf16 v[26:29], v[160:163], v[140:143], 0
	ds_read_b128 v[192:195], v233 offset:4096
	v_mfma_f32_16x16x32_bf16 v[30:33], v[164:167], v[140:143], 0
	ds_read_b128 v[196:199], v233 offset:6144
	v_mfma_f32_16x16x32_bf16 v[34:37], v[152:155], v[144:147], 0
	v_mfma_f32_16x16x32_bf16 v[38:41], v[156:159], v[144:147], 0
	v_mfma_f32_16x16x32_bf16 v[42:45], v[160:163], v[144:147], 0
	v_mfma_f32_16x16x32_bf16 v[46:49], v[164:167], v[144:147], 0
	v_mfma_f32_16x16x32_bf16 v[50:53], v[152:155], v[148:151], 0
	v_mfma_f32_16x16x32_bf16 v[54:57], v[156:159], v[148:151], 0
	v_mfma_f32_16x16x32_bf16 v[58:61], v[160:163], v[148:151], 0
	v_mfma_f32_16x16x32_bf16 v[62:65], v[164:167], v[148:151], 0
	s_waitcnt vmcnt(6) lgkmcnt(0)
	s_barrier
	v_mfma_f32_16x16x32_bf16 v[2:5], v[184:187], v[168:171], v[2:5]
	ds_read_b128 v[136:139], v219 offset:0
	v_mfma_f32_16x16x32_bf16 v[6:9], v[188:191], v[168:171], v[6:9]
	ds_read_b128 v[140:143], v219 offset:2048
	v_mfma_f32_16x16x32_bf16 v[10:13], v[192:195], v[168:171], v[10:13]
	ds_read_b128 v[144:147], v219 offset:4096
	v_mfma_f32_16x16x32_bf16 v[14:17], v[196:199], v[168:171], v[14:17]
	ds_read_b128 v[148:151], v219 offset:6144
	v_mfma_f32_16x16x32_bf16 v[18:21], v[184:187], v[172:175], v[18:21]
	ds_read_b128 v[152:155], v231 offset:0
	v_mfma_f32_16x16x32_bf16 v[22:25], v[188:191], v[172:175], v[22:25]
	ds_read_b128 v[156:159], v231 offset:2048
	v_mfma_f32_16x16x32_bf16 v[26:29], v[192:195], v[172:175], v[26:29]
	ds_read_b128 v[160:163], v231 offset:4096
	v_mfma_f32_16x16x32_bf16 v[30:33], v[196:199], v[172:175], v[30:33]
	ds_read_b128 v[164:167], v231 offset:6144
	s_mov_b32 m0, s8
	v_mfma_f32_16x16x32_bf16 v[34:37], v[184:187], v[176:179], v[34:37]
	global_load_lds_dwordx4 v200, s[4:5]
	s_add_u32 m0, s8, 0x400
	v_mfma_f32_16x16x32_bf16 v[38:41], v[188:191], v[176:179], v[38:41]
	global_load_lds_dwordx4 v201, s[4:5]
	s_add_u32 m0, s8, 0x800
	v_mfma_f32_16x16x32_bf16 v[42:45], v[192:195], v[176:179], v[42:45]
	global_load_lds_dwordx4 v202, s[4:5]
	s_add_u32 m0, s8, 0xc00
	v_mfma_f32_16x16x32_bf16 v[46:49], v[196:199], v[176:179], v[46:49]
	global_load_lds_dwordx4 v203, s[4:5]
	s_mov_b32 m0, s9
	v_mfma_f32_16x16x32_bf16 v[50:53], v[184:187], v[180:183], v[50:53]
	global_load_lds_dwordx4 v204, s[6:7]
	s_add_u32 m0, s9, 0x400
	v_mfma_f32_16x16x32_bf16 v[54:57], v[188:191], v[180:183], v[54:57]
	global_load_lds_dwordx4 v205, s[6:7]
	v_mfma_f32_16x16x32_bf16 v[58:61], v[192:195], v[180:183], v[58:61]
	s_add_u32 s4, s4, 0x80
	s_addc_u32 s5, s5, 0
	v_mfma_f32_16x16x32_bf16 v[62:65], v[196:199], v[180:183], v[62:65]
	s_add_u32 s6, s6, 0x80
	s_addc_u32 s7, s7, 0
	s_waitcnt lgkmcnt(0)
	v_mfma_f32_16x16x32_bf16 v[2:5], v[152:155], v[136:139], v[2:5]
	ds_read_b128 v[168:171], v228 offset:0
	v_mfma_f32_16x16x32_bf16 v[6:9], v[156:159], v[136:139], v[6:9]
	ds_read_b128 v[172:175], v228 offset:2048
	v_mfma_f32_16x16x32_bf16 v[10:13], v[160:163], v[136:139], v[10:13]
	ds_read_b128 v[176:179], v228 offset:4096
	v_mfma_f32_16x16x32_bf16 v[14:17], v[164:167], v[136:139], v[14:17]
	ds_read_b128 v[180:183], v228 offset:6144
	v_mfma_f32_16x16x32_bf16 v[18:21], v[152:155], v[140:143], v[18:21]
	ds_read_b128 v[184:187], v234 offset:0
	v_mfma_f32_16x16x32_bf16 v[22:25], v[156:159], v[140:143], v[22:25]
	ds_read_b128 v[188:191], v234 offset:2048
	v_mfma_f32_16x16x32_bf16 v[26:29], v[160:163], v[140:143], v[26:29]
	ds_read_b128 v[192:195], v234 offset:4096
	v_mfma_f32_16x16x32_bf16 v[30:33], v[164:167], v[140:143], v[30:33]
	ds_read_b128 v[196:199], v234 offset:6144
	v_mfma_f32_16x16x32_bf16 v[34:37], v[152:155], v[144:147], v[34:37]
	v_mfma_f32_16x16x32_bf16 v[38:41], v[156:159], v[144:147], v[38:41]
	v_mfma_f32_16x16x32_bf16 v[42:45], v[160:163], v[144:147], v[42:45]
	v_mfma_f32_16x16x32_bf16 v[46:49], v[164:167], v[144:147], v[46:49]
	v_mfma_f32_16x16x32_bf16 v[50:53], v[152:155], v[148:151], v[50:53]
	v_mfma_f32_16x16x32_bf16 v[54:57], v[156:159], v[148:151], v[54:57]
	v_mfma_f32_16x16x32_bf16 v[58:61], v[160:163], v[148:151], v[58:61]
	v_mfma_f32_16x16x32_bf16 v[62:65], v[164:167], v[148:151], v[62:65]
	s_waitcnt vmcnt(6) lgkmcnt(0)
	s_barrier
	v_mfma_f32_16x16x32_bf16 v[2:5], v[184:187], v[168:171], v[2:5]
	ds_read_b128 v[136:139], v224 offset:0
	v_mfma_f32_16x16x32_bf16 v[6:9], v[188:191], v[168:171], v[6:9]
	ds_read_b128 v[140:143], v224 offset:2048
	v_mfma_f32_16x16x32_bf16 v[10:13], v[192:195], v[168:171], v[10:13]
	ds_read_b128 v[144:147], v224 offset:4096
	v_mfma_f32_16x16x32_bf16 v[14:17], v[196:199], v[168:171], v[14:17]
	ds_read_b128 v[148:151], v224 offset:6144
	v_mfma_f32_16x16x32_bf16 v[18:21], v[184:187], v[172:175], v[18:21]
	ds_read_b128 v[152:155], v232 offset:0
	v_mfma_f32_16x16x32_bf16 v[22:25], v[188:191], v[172:175], v[22:25]
	ds_read_b128 v[156:159], v232 offset:2048
	v_mfma_f32_16x16x32_bf16 v[26:29], v[192:195], v[172:175], v[26:29]
	ds_read_b128 v[160:163], v232 offset:4096
	v_mfma_f32_16x16x32_bf16 v[30:33], v[196:199], v[172:175], v[30:33]
	ds_read_b128 v[164:167], v232 offset:6144
	s_add_u32 m0, s8, 0xc000
	v_mfma_f32_16x16x32_bf16 v[34:37], v[184:187], v[176:179], v[34:37]
	global_load_lds_dwordx4 v200, s[4:5]
	s_add_u32 m0, s8, 0xc400
	v_mfma_f32_16x16x32_bf16 v[38:41], v[188:191], v[176:179], v[38:41]
	global_load_lds_dwordx4 v201, s[4:5]
	s_add_u32 m0, s8, 0xc800
	v_mfma_f32_16x16x32_bf16 v[42:45], v[192:195], v[176:179], v[42:45]
	global_load_lds_dwordx4 v202, s[4:5]
	s_add_u32 m0, s8, 0xcc00
	v_mfma_f32_16x16x32_bf16 v[46:49], v[196:199], v[176:179], v[46:49]
	global_load_lds_dwordx4 v203, s[4:5]
	s_add_u32 m0, s9, 0xc000
	v_mfma_f32_16x16x32_bf16 v[50:53], v[184:187], v[180:183], v[50:53]
	global_load_lds_dwordx4 v204, s[6:7]
	s_add_u32 m0, s9, 0xc400
	v_mfma_f32_16x16x32_bf16 v[54:57], v[188:191], v[180:183], v[54:57]
	global_load_lds_dwordx4 v205, s[6:7]
	v_mfma_f32_16x16x32_bf16 v[58:61], v[192:195], v[180:183], v[58:61]
	s_add_u32 s4, s4, 0x80
	s_addc_u32 s5, s5, 0
	v_mfma_f32_16x16x32_bf16 v[62:65], v[196:199], v[180:183], v[62:65]
	s_add_u32 s6, s6, 0x80
	s_addc_u32 s7, s7, 0
	s_waitcnt lgkmcnt(0)
	v_mfma_f32_16x16x32_bf16 v[2:5], v[152:155], v[136:139], v[2:5]
	ds_read_b128 v[168:171], v229 offset:0
	v_mfma_f32_16x16x32_bf16 v[6:9], v[156:159], v[136:139], v[6:9]
	ds_read_b128 v[172:175], v229 offset:2048
	v_mfma_f32_16x16x32_bf16 v[10:13], v[160:163], v[136:139], v[10:13]
	ds_read_b128 v[176:179], v229 offset:4096
	v_mfma_f32_16x16x32_bf16 v[14:17], v[164:167], v[136:139], v[14:17]
	ds_read_b128 v[180:183], v229 offset:6144
	v_mfma_f32_16x16x32_bf16 v[18:21], v[152:155], v[140:143], v[18:21]
	ds_read_b128 v[184:187], v235 offset:0
	v_mfma_f32_16x16x32_bf16 v[22:25], v[156:159], v[140:143], v[22:25]
	ds_read_b128 v[188:191], v235 offset:2048
	v_mfma_f32_16x16x32_bf16 v[26:29], v[160:163], v[140:143], v[26:29]
	ds_read_b128 v[192:195], v235 offset:4096
	v_mfma_f32_16x16x32_bf16 v[30:33], v[164:167], v[140:143], v[30:33]
	ds_read_b128 v[196:199], v235 offset:6144
	v_mfma_f32_16x16x32_bf16 v[34:37], v[152:155], v[144:147], v[34:37]
	v_mfma_f32_16x16x32_bf16 v[38:41], v[156:159], v[144:147], v[38:41]
	v_mfma_f32_16x16x32_bf16 v[42:45], v[160:163], v[144:147], v[42:45]
	v_mfma_f32_16x16x32_bf16 v[46:49], v[164:167], v[144:147], v[46:49]
	v_mfma_f32_16x16x32_bf16 v[50:53], v[152:155], v[148:151], v[50:53]
	v_mfma_f32_16x16x32_bf16 v[54:57], v[156:159], v[148:151], v[54:57]
	v_mfma_f32_16x16x32_bf16 v[58:61], v[160:163], v[148:151], v[58:61]
	v_mfma_f32_16x16x32_bf16 v[62:65], v[164:167], v[148:151], v[62:65]
	s_waitcnt vmcnt(6) lgkmcnt(0)
	s_barrier
	v_mfma_f32_16x16x32_bf16 v[2:5], v[184:187], v[168:171], v[2:5]
	ds_read_b128 v[136:139], v218 offset:0
	v_mfma_f32_16x16x32_bf16 v[6:9], v[188:191], v[168:171], v[6:9]
	ds_read_b128 v[140:143], v218 offset:2048
	v_mfma_f32_16x16x32_bf16 v[10:13], v[192:195], v[168:171], v[10:13]
	ds_read_b128 v[144:147], v218 offset:4096
	v_mfma_f32_16x16x32_bf16 v[14:17], v[196:199], v[168:171], v[14:17]
	ds_read_b128 v[148:151], v218 offset:6144
	v_mfma_f32_16x16x32_bf16 v[18:21], v[184:187], v[172:175], v[18:21]
	ds_read_b128 v[152:155], v230 offset:0
	v_mfma_f32_16x16x32_bf16 v[22:25], v[188:191], v[172:175], v[22:25]
	ds_read_b128 v[156:159], v230 offset:2048
	v_mfma_f32_16x16x32_bf16 v[26:29], v[192:195], v[172:175], v[26:29]
	ds_read_b128 v[160:163], v230 offset:4096
	v_mfma_f32_16x16x32_bf16 v[30:33], v[196:199], v[172:175], v[30:33]
	ds_read_b128 v[164:167], v230 offset:6144
	s_add_u32 m0, s8, 0x18000
	v_mfma_f32_16x16x32_bf16 v[34:37], v[184:187], v[176:179], v[34:37]
	global_load_lds_dwordx4 v200, s[4:5]
	s_add_u32 m0, s8, 0x18400
	v_mfma_f32_16x16x32_bf16 v[38:41], v[188:191], v[176:179], v[38:41]
	global_load_lds_dwordx4 v201, s[4:5]
	s_add_u32 m0, s8, 0x18800
	v_mfma_f32_16x16x32_bf16 v[42:45], v[192:195], v[176:179], v[42:45]
	global_load_lds_dwordx4 v202, s[4:5]
	s_add_u32 m0, s8, 0x18c00
	v_mfma_f32_16x16x32_bf16 v[46:49], v[196:199], v[176:179], v[46:49]
	global_load_lds_dwordx4 v203, s[4:5]
	s_add_u32 m0, s9, 0x18000
	v_mfma_f32_16x16x32_bf16 v[50:53], v[184:187], v[180:183], v[50:53]
	global_load_lds_dwordx4 v204, s[6:7]
	s_add_u32 m0, s9, 0x18400
	v_mfma_f32_16x16x32_bf16 v[54:57], v[188:191], v[180:183], v[54:57]
	global_load_lds_dwordx4 v205, s[6:7]
	v_mfma_f32_16x16x32_bf16 v[58:61], v[192:195], v[180:183], v[58:61]
	s_add_u32 s4, s4, 0x80
	s_addc_u32 s5, s5, 0
	v_mfma_f32_16x16x32_bf16 v[62:65], v[196:199], v[180:183], v[62:65]
	s_add_u32 s6, s6, 0x80
	s_addc_u32 s7, s7, 0
	s_waitcnt lgkmcnt(0)
	v_mfma_f32_16x16x32_bf16 v[2:5], v[152:155], v[136:139], v[2:5]
	ds_read_b128 v[168:171], v225 offset:0
	v_mfma_f32_16x16x32_bf16 v[6:9], v[156:159], v[136:139], v[6:9]
	ds_read_b128 v[172:175], v225 offset:2048
	v_mfma_f32_16x16x32_bf16 v[10:13], v[160:163], v[136:139], v[10:13]
	ds_read_b128 v[176:179], v225 offset:4096
	v_mfma_f32_16x16x32_bf16 v[14:17], v[164:167], v[136:139], v[14:17]
	ds_read_b128 v[180:183], v225 offset:6144
	v_mfma_f32_16x16x32_bf16 v[18:21], v[152:155], v[140:143], v[18:21]
	ds_read_b128 v[184:187], v233 offset:0
	v_mfma_f32_16x16x32_bf16 v[22:25], v[156:159], v[140:143], v[22:25]
	ds_read_b128 v[188:191], v233 offset:2048
	v_mfma_f32_16x16x32_bf16 v[26:29], v[160:163], v[140:143], v[26:29]
	ds_read_b128 v[192:195], v233 offset:4096
	v_mfma_f32_16x16x32_bf16 v[30:33], v[164:167], v[140:143], v[30:33]
	ds_read_b128 v[196:199], v233 offset:6144
	v_mfma_f32_16x16x32_bf16 v[34:37], v[152:155], v[144:147], v[34:37]
	v_mfma_f32_16x16x32_bf16 v[38:41], v[156:159], v[144:147], v[38:41]
	v_mfma_f32_16x16x32_bf16 v[42:45], v[160:163], v[144:147], v[42:45]
	v_mfma_f32_16x16x32_bf16 v[46:49], v[164:167], v[144:147], v[46:49]
	v_mfma_f32_16x16x32_bf16 v[50:53], v[152:155], v[148:151], v[50:53]
	v_mfma_f32_16x16x32_bf16 v[54:57], v[156:159], v[148:151], v[54:57]
	v_mfma_f32_16x16x32_bf16 v[58:61], v[160:163], v[148:151], v[58:61]
	v_mfma_f32_16x16x32_bf16 v[62:65], v[164:167], v[148:151], v[62:65]
	s_waitcnt vmcnt(6) lgkmcnt(0)
	s_barrier
	v_mfma_f32_16x16x32_bf16 v[2:5], v[184:187], v[168:171], v[2:5]
	ds_read_b128 v[136:139], v219 offset:0
	v_mfma_f32_16x16x32_bf16 v[6:9], v[188:191], v[168:171], v[6:9]
	ds_read_b128 v[140:143], v219 offset:2048
	v_mfma_f32_16x16x32_bf16 v[10:13], v[192:195], v[168:171], v[10:13]
	ds_read_b128 v[144:147], v219 offset:4096
	v_mfma_f32_16x16x32_bf16 v[14:17], v[196:199], v[168:171], v[14:17]
	ds_read_b128 v[148:151], v219 offset:6144
	v_mfma_f32_16x16x32_bf16 v[18:21], v[184:187], v[172:175], v[18:21]
	ds_read_b128 v[152:155], v231 offset:0
	v_mfma_f32_16x16x32_bf16 v[22:25], v[188:191], v[172:175], v[22:25]
	ds_read_b128 v[156:159], v231 offset:2048
	v_mfma_f32_16x16x32_bf16 v[26:29], v[192:195], v[172:175], v[26:29]
	ds_read_b128 v[160:163], v231 offset:4096
	v_mfma_f32_16x16x32_bf16 v[30:33], v[196:199], v[172:175], v[30:33]
	ds_read_b128 v[164:167], v231 offset:6144
	s_mov_b32 m0, s8
	v_mfma_f32_16x16x32_bf16 v[34:37], v[184:187], v[176:179], v[34:37]
	global_load_lds_dwordx4 v200, s[4:5]
	s_add_u32 m0, s8, 0x400
	v_mfma_f32_16x16x32_bf16 v[38:41], v[188:191], v[176:179], v[38:41]
	global_load_lds_dwordx4 v201, s[4:5]
	s_add_u32 m0, s8, 0x800
	v_mfma_f32_16x16x32_bf16 v[42:45], v[192:195], v[176:179], v[42:45]
	global_load_lds_dwordx4 v202, s[4:5]
	s_add_u32 m0, s8, 0xc00
	v_mfma_f32_16x16x32_bf16 v[46:49], v[196:199], v[176:179], v[46:49]
	global_load_lds_dwordx4 v203, s[4:5]
	s_mov_b32 m0, s9
	v_mfma_f32_16x16x32_bf16 v[50:53], v[184:187], v[180:183], v[50:53]
	global_load_lds_dwordx4 v204, s[6:7]
	s_add_u32 m0, s9, 0x400
	v_mfma_f32_16x16x32_bf16 v[54:57], v[188:191], v[180:183], v[54:57]
	global_load_lds_dwordx4 v205, s[6:7]
	v_mfma_f32_16x16x32_bf16 v[58:61], v[192:195], v[180:183], v[58:61]
	s_add_u32 s4, s4, 0x80
	s_addc_u32 s5, s5, 0
	v_mfma_f32_16x16x32_bf16 v[62:65], v[196:199], v[180:183], v[62:65]
	s_add_u32 s6, s6, 0x80
	s_addc_u32 s7, s7, 0
	s_waitcnt lgkmcnt(0)
	v_mfma_f32_16x16x32_bf16 v[2:5], v[152:155], v[136:139], v[2:5]
	ds_read_b128 v[168:171], v228 offset:0
	v_mfma_f32_16x16x32_bf16 v[6:9], v[156:159], v[136:139], v[6:9]
	ds_read_b128 v[172:175], v228 offset:2048
	v_mfma_f32_16x16x32_bf16 v[10:13], v[160:163], v[136:139], v[10:13]
	ds_read_b128 v[176:179], v228 offset:4096
	v_mfma_f32_16x16x32_bf16 v[14:17], v[164:167], v[136:139], v[14:17]
	ds_read_b128 v[180:183], v228 offset:6144
	v_mfma_f32_16x16x32_bf16 v[18:21], v[152:155], v[140:143], v[18:21]
	ds_read_b128 v[184:187], v234 offset:0
	v_mfma_f32_16x16x32_bf16 v[22:25], v[156:159], v[140:143], v[22:25]
	ds_read_b128 v[188:191], v234 offset:2048
	v_mfma_f32_16x16x32_bf16 v[26:29], v[160:163], v[140:143], v[26:29]
	ds_read_b128 v[192:195], v234 offset:4096
	v_mfma_f32_16x16x32_bf16 v[30:33], v[164:167], v[140:143], v[30:33]
	ds_read_b128 v[196:199], v234 offset:6144
	v_mfma_f32_16x16x32_bf16 v[34:37], v[152:155], v[144:147], v[34:37]
	v_mfma_f32_16x16x32_bf16 v[38:41], v[156:159], v[144:147], v[38:41]
	v_mfma_f32_16x16x32_bf16 v[42:45], v[160:163], v[144:147], v[42:45]
	v_mfma_f32_16x16x32_bf16 v[46:49], v[164:167], v[144:147], v[46:49]
	v_mfma_f32_16x16x32_bf16 v[50:53], v[152:155], v[148:151], v[50:53]
	v_mfma_f32_16x16x32_bf16 v[54:57], v[156:159], v[148:151], v[54:57]
	v_mfma_f32_16x16x32_bf16 v[58:61], v[160:163], v[148:151], v[58:61]
	v_mfma_f32_16x16x32_bf16 v[62:65], v[164:167], v[148:151], v[62:65]
	s_waitcnt vmcnt(6) lgkmcnt(0)
	s_barrier
	v_mfma_f32_16x16x32_bf16 v[2:5], v[184:187], v[168:171], v[2:5]
	ds_read_b128 v[136:139], v224 offset:0
	v_mfma_f32_16x16x32_bf16 v[6:9], v[188:191], v[168:171], v[6:9]
	ds_read_b128 v[140:143], v224 offset:2048
	v_mfma_f32_16x16x32_bf16 v[10:13], v[192:195], v[168:171], v[10:13]
	ds_read_b128 v[144:147], v224 offset:4096
	v_mfma_f32_16x16x32_bf16 v[14:17], v[196:199], v[168:171], v[14:17]
	ds_read_b128 v[148:151], v224 offset:6144
	v_mfma_f32_16x16x32_bf16 v[18:21], v[184:187], v[172:175], v[18:21]
	ds_read_b128 v[152:155], v232 offset:0
	v_mfma_f32_16x16x32_bf16 v[22:25], v[188:191], v[172:175], v[22:25]
	ds_read_b128 v[156:159], v232 offset:2048
	v_mfma_f32_16x16x32_bf16 v[26:29], v[192:195], v[172:175], v[26:29]
	ds_read_b128 v[160:163], v232 offset:4096
	v_mfma_f32_16x16x32_bf16 v[30:33], v[196:199], v[172:175], v[30:33]
	ds_read_b128 v[164:167], v232 offset:6144
	s_add_u32 m0, s8, 0xc000
	v_mfma_f32_16x16x32_bf16 v[34:37], v[184:187], v[176:179], v[34:37]
	global_load_lds_dwordx4 v200, s[4:5]
	s_add_u32 m0, s8, 0xc400
	v_mfma_f32_16x16x32_bf16 v[38:41], v[188:191], v[176:179], v[38:41]
	global_load_lds_dwordx4 v201, s[4:5]
	s_add_u32 m0, s8, 0xc800
	v_mfma_f32_16x16x32_bf16 v[42:45], v[192:195], v[176:179], v[42:45]
	global_load_lds_dwordx4 v202, s[4:5]
	s_add_u32 m0, s8, 0xcc00
	v_mfma_f32_16x16x32_bf16 v[46:49], v[196:199], v[176:179], v[46:49]
	global_load_lds_dwordx4 v203, s[4:5]
	s_add_u32 m0, s9, 0xc000
	v_mfma_f32_16x16x32_bf16 v[50:53], v[184:187], v[180:183], v[50:53]
	global_load_lds_dwordx4 v204, s[6:7]
	s_add_u32 m0, s9, 0xc400
	v_mfma_f32_16x16x32_bf16 v[54:57], v[188:191], v[180:183], v[54:57]
	global_load_lds_dwordx4 v205, s[6:7]
	v_mfma_f32_16x16x32_bf16 v[58:61], v[192:195], v[180:183], v[58:61]
	s_add_u32 s4, s4, 0x80
	s_addc_u32 s5, s5, 0
	v_mfma_f32_16x16x32_bf16 v[62:65], v[196:199], v[180:183], v[62:65]
	s_add_u32 s6, s6, 0x80
	s_addc_u32 s7, s7, 0
	s_waitcnt lgkmcnt(0)
	v_mfma_f32_16x16x32_bf16 v[2:5], v[152:155], v[136:139], v[2:5]
	ds_read_b128 v[168:171], v229 offset:0
	v_mfma_f32_16x16x32_bf16 v[6:9], v[156:159], v[136:139], v[6:9]
	ds_read_b128 v[172:175], v229 offset:2048
	v_mfma_f32_16x16x32_bf16 v[10:13], v[160:163], v[136:139], v[10:13]
	ds_read_b128 v[176:179], v229 offset:4096
	v_mfma_f32_16x16x32_bf16 v[14:17], v[164:167], v[136:139], v[14:17]
	ds_read_b128 v[180:183], v229 offset:6144
	v_mfma_f32_16x16x32_bf16 v[18:21], v[152:155], v[140:143], v[18:21]
	ds_read_b128 v[184:187], v235 offset:0
	v_mfma_f32_16x16x32_bf16 v[22:25], v[156:159], v[140:143], v[22:25]
	ds_read_b128 v[188:191], v235 offset:2048
	v_mfma_f32_16x16x32_bf16 v[26:29], v[160:163], v[140:143], v[26:29]
	ds_read_b128 v[192:195], v235 offset:4096
	v_mfma_f32_16x16x32_bf16 v[30:33], v[164:167], v[140:143], v[30:33]
	ds_read_b128 v[196:199], v235 offset:6144
	v_mfma_f32_16x16x32_bf16 v[34:37], v[152:155], v[144:147], v[34:37]
	v_mfma_f32_16x16x32_bf16 v[38:41], v[156:159], v[144:147], v[38:41]
	v_mfma_f32_16x16x32_bf16 v[42:45], v[160:163], v[144:147], v[42:45]
	v_mfma_f32_16x16x32_bf16 v[46:49], v[164:167], v[144:147], v[46:49]
	v_mfma_f32_16x16x32_bf16 v[50:53], v[152:155], v[148:151], v[50:53]
	v_mfma_f32_16x16x32_bf16 v[54:57], v[156:159], v[148:151], v[54:57]
	v_mfma_f32_16x16x32_bf16 v[58:61], v[160:163], v[148:151], v[58:61]
	v_mfma_f32_16x16x32_bf16 v[62:65], v[164:167], v[148:151], v[62:65]
	s_waitcnt vmcnt(6) lgkmcnt(0)
	s_barrier
	v_mfma_f32_16x16x32_bf16 v[2:5], v[184:187], v[168:171], v[2:5]
	ds_read_b128 v[136:139], v218 offset:0
	v_mfma_f32_16x16x32_bf16 v[6:9], v[188:191], v[168:171], v[6:9]
	ds_read_b128 v[140:143], v218 offset:2048
	v_mfma_f32_16x16x32_bf16 v[10:13], v[192:195], v[168:171], v[10:13]
	ds_read_b128 v[144:147], v218 offset:4096
	v_mfma_f32_16x16x32_bf16 v[14:17], v[196:199], v[168:171], v[14:17]
	ds_read_b128 v[148:151], v218 offset:6144
	v_mfma_f32_16x16x32_bf16 v[18:21], v[184:187], v[172:175], v[18:21]
	ds_read_b128 v[152:155], v230 offset:0
	v_mfma_f32_16x16x32_bf16 v[22:25], v[188:191], v[172:175], v[22:25]
	ds_read_b128 v[156:159], v230 offset:2048
	v_mfma_f32_16x16x32_bf16 v[26:29], v[192:195], v[172:175], v[26:29]
	ds_read_b128 v[160:163], v230 offset:4096
	v_mfma_f32_16x16x32_bf16 v[30:33], v[196:199], v[172:175], v[30:33]
	ds_read_b128 v[164:167], v230 offset:6144
	s_add_u32 m0, s8, 0x18000
	v_mfma_f32_16x16x32_bf16 v[34:37], v[184:187], v[176:179], v[34:37]
	global_load_lds_dwordx4 v200, s[4:5]
	s_add_u32 m0, s8, 0x18400
	v_mfma_f32_16x16x32_bf16 v[38:41], v[188:191], v[176:179], v[38:41]
	global_load_lds_dwordx4 v201, s[4:5]
	s_add_u32 m0, s8, 0x18800
	v_mfma_f32_16x16x32_bf16 v[42:45], v[192:195], v[176:179], v[42:45]
	global_load_lds_dwordx4 v202, s[4:5]
	s_add_u32 m0, s8, 0x18c00
	v_mfma_f32_16x16x32_bf16 v[46:49], v[196:199], v[176:179], v[46:49]
	global_load_lds_dwordx4 v203, s[4:5]
	s_add_u32 m0, s9, 0x18000
	v_mfma_f32_16x16x32_bf16 v[50:53], v[184:187], v[180:183], v[50:53]
	global_load_lds_dwordx4 v204, s[6:7]
	s_add_u32 m0, s9, 0x18400
	v_mfma_f32_16x16x32_bf16 v[54:57], v[188:191], v[180:183], v[54:57]
	global_load_lds_dwordx4 v205, s[6:7]
	v_mfma_f32_16x16x32_bf16 v[58:61], v[192:195], v[180:183], v[58:61]
	s_add_u32 s4, s4, 0x80
	s_addc_u32 s5, s5, 0
	v_mfma_f32_16x16x32_bf16 v[62:65], v[196:199], v[180:183], v[62:65]
	s_add_u32 s6, s6, 0x80
	s_addc_u32 s7, s7, 0
	s_waitcnt lgkmcnt(0)
	v_mfma_f32_16x16x32_bf16 v[2:5], v[152:155], v[136:139], v[2:5]
	ds_read_b128 v[168:171], v225 offset:0
	v_mfma_f32_16x16x32_bf16 v[6:9], v[156:159], v[136:139], v[6:9]
	ds_read_b128 v[172:175], v225 offset:2048
	v_mfma_f32_16x16x32_bf16 v[10:13], v[160:163], v[136:139], v[10:13]
	ds_read_b128 v[176:179], v225 offset:4096
	v_mfma_f32_16x16x32_bf16 v[14:17], v[164:167], v[136:139], v[14:17]
	ds_read_b128 v[180:183], v225 offset:6144
	v_mfma_f32_16x16x32_bf16 v[18:21], v[152:155], v[140:143], v[18:21]
	ds_read_b128 v[184:187], v233 offset:0
	v_mfma_f32_16x16x32_bf16 v[22:25], v[156:159], v[140:143], v[22:25]
	ds_read_b128 v[188:191], v233 offset:2048
	v_mfma_f32_16x16x32_bf16 v[26:29], v[160:163], v[140:143], v[26:29]
	ds_read_b128 v[192:195], v233 offset:4096
	v_mfma_f32_16x16x32_bf16 v[30:33], v[164:167], v[140:143], v[30:33]
	ds_read_b128 v[196:199], v233 offset:6144
	v_mfma_f32_16x16x32_bf16 v[34:37], v[152:155], v[144:147], v[34:37]
	v_mfma_f32_16x16x32_bf16 v[38:41], v[156:159], v[144:147], v[38:41]
	v_mfma_f32_16x16x32_bf16 v[42:45], v[160:163], v[144:147], v[42:45]
	v_mfma_f32_16x16x32_bf16 v[46:49], v[164:167], v[144:147], v[46:49]
	v_mfma_f32_16x16x32_bf16 v[50:53], v[152:155], v[148:151], v[50:53]
	v_mfma_f32_16x16x32_bf16 v[54:57], v[156:159], v[148:151], v[54:57]
	v_mfma_f32_16x16x32_bf16 v[58:61], v[160:163], v[148:151], v[58:61]
	v_mfma_f32_16x16x32_bf16 v[62:65], v[164:167], v[148:151], v[62:65]
	s_waitcnt vmcnt(6) lgkmcnt(0)
	s_barrier
	v_mfma_f32_16x16x32_bf16 v[2:5], v[184:187], v[168:171], v[2:5]
	ds_read_b128 v[136:139], v219 offset:0
	v_mfma_f32_16x16x32_bf16 v[6:9], v[188:191], v[168:171], v[6:9]
	ds_read_b128 v[140:143], v219 offset:2048
	v_mfma_f32_16x16x32_bf16 v[10:13], v[192:195], v[168:171], v[10:13]
	ds_read_b128 v[144:147], v219 offset:4096
	v_mfma_f32_16x16x32_bf16 v[14:17], v[196:199], v[168:171], v[14:17]
	ds_read_b128 v[148:151], v219 offset:6144
	v_mfma_f32_16x16x32_bf16 v[18:21], v[184:187], v[172:175], v[18:21]
	ds_read_b128 v[152:155], v231 offset:0
	v_mfma_f32_16x16x32_bf16 v[22:25], v[188:191], v[172:175], v[22:25]
	ds_read_b128 v[156:159], v231 offset:2048
	v_mfma_f32_16x16x32_bf16 v[26:29], v[192:195], v[172:175], v[26:29]
	ds_read_b128 v[160:163], v231 offset:4096
	v_mfma_f32_16x16x32_bf16 v[30:33], v[196:199], v[172:175], v[30:33]
	ds_read_b128 v[164:167], v231 offset:6144
	s_mov_b32 m0, s8
	v_mfma_f32_16x16x32_bf16 v[34:37], v[184:187], v[176:179], v[34:37]
	global_load_lds_dwordx4 v200, s[4:5]
	s_add_u32 m0, s8, 0x400
	v_mfma_f32_16x16x32_bf16 v[38:41], v[188:191], v[176:179], v[38:41]
	global_load_lds_dwordx4 v201, s[4:5]
	s_add_u32 m0, s8, 0x800
	v_mfma_f32_16x16x32_bf16 v[42:45], v[192:195], v[176:179], v[42:45]
	global_load_lds_dwordx4 v202, s[4:5]
	s_add_u32 m0, s8, 0xc00
	v_mfma_f32_16x16x32_bf16 v[46:49], v[196:199], v[176:179], v[46:49]
	global_load_lds_dwordx4 v203, s[4:5]
	s_mov_b32 m0, s9
	v_mfma_f32_16x16x32_bf16 v[50:53], v[184:187], v[180:183], v[50:53]
	global_load_lds_dwordx4 v204, s[6:7]
	s_add_u32 m0, s9, 0x400
	v_mfma_f32_16x16x32_bf16 v[54:57], v[188:191], v[180:183], v[54:57]
	global_load_lds_dwordx4 v205, s[6:7]
	v_mfma_f32_16x16x32_bf16 v[58:61], v[192:195], v[180:183], v[58:61]
	s_add_u32 s4, s4, 0x80
	s_addc_u32 s5, s5, 0
	v_mfma_f32_16x16x32_bf16 v[62:65], v[196:199], v[180:183], v[62:65]
	s_add_u32 s6, s6, 0x80
	s_addc_u32 s7, s7, 0
	s_waitcnt lgkmcnt(0)
	v_mfma_f32_16x16x32_bf16 v[2:5], v[152:155], v[136:139], v[2:5]
	ds_read_b128 v[168:171], v228 offset:0
	v_mfma_f32_16x16x32_bf16 v[6:9], v[156:159], v[136:139], v[6:9]
	ds_read_b128 v[172:175], v228 offset:2048
	v_mfma_f32_16x16x32_bf16 v[10:13], v[160:163], v[136:139], v[10:13]
	ds_read_b128 v[176:179], v228 offset:4096
	v_mfma_f32_16x16x32_bf16 v[14:17], v[164:167], v[136:139], v[14:17]
	ds_read_b128 v[180:183], v228 offset:6144
	v_mfma_f32_16x16x32_bf16 v[18:21], v[152:155], v[140:143], v[18:21]
	ds_read_b128 v[184:187], v234 offset:0
	v_mfma_f32_16x16x32_bf16 v[22:25], v[156:159], v[140:143], v[22:25]
	ds_read_b128 v[188:191], v234 offset:2048
	v_mfma_f32_16x16x32_bf16 v[26:29], v[160:163], v[140:143], v[26:29]
	ds_read_b128 v[192:195], v234 offset:4096
	v_mfma_f32_16x16x32_bf16 v[30:33], v[164:167], v[140:143], v[30:33]
	ds_read_b128 v[196:199], v234 offset:6144
	v_mfma_f32_16x16x32_bf16 v[34:37], v[152:155], v[144:147], v[34:37]
	v_mfma_f32_16x16x32_bf16 v[38:41], v[156:159], v[144:147], v[38:41]
	v_mfma_f32_16x16x32_bf16 v[42:45], v[160:163], v[144:147], v[42:45]
	v_mfma_f32_16x16x32_bf16 v[46:49], v[164:167], v[144:147], v[46:49]
	v_mfma_f32_16x16x32_bf16 v[50:53], v[152:155], v[148:151], v[50:53]
	v_mfma_f32_16x16x32_bf16 v[54:57], v[156:159], v[148:151], v[54:57]
	v_mfma_f32_16x16x32_bf16 v[58:61], v[160:163], v[148:151], v[58:61]
	v_mfma_f32_16x16x32_bf16 v[62:65], v[164:167], v[148:151], v[62:65]
	s_waitcnt vmcnt(6) lgkmcnt(0)
	s_barrier
	v_mfma_f32_16x16x32_bf16 v[2:5], v[184:187], v[168:171], v[2:5]
	ds_read_b128 v[136:139], v224 offset:0
	v_mfma_f32_16x16x32_bf16 v[6:9], v[188:191], v[168:171], v[6:9]
	ds_read_b128 v[140:143], v224 offset:2048
	v_mfma_f32_16x16x32_bf16 v[10:13], v[192:195], v[168:171], v[10:13]
	ds_read_b128 v[144:147], v224 offset:4096
	v_mfma_f32_16x16x32_bf16 v[14:17], v[196:199], v[168:171], v[14:17]
	ds_read_b128 v[148:151], v224 offset:6144
	v_mfma_f32_16x16x32_bf16 v[18:21], v[184:187], v[172:175], v[18:21]
	ds_read_b128 v[152:155], v232 offset:0
	v_mfma_f32_16x16x32_bf16 v[22:25], v[188:191], v[172:175], v[22:25]
	ds_read_b128 v[156:159], v232 offset:2048
	v_mfma_f32_16x16x32_bf16 v[26:29], v[192:195], v[172:175], v[26:29]
	ds_read_b128 v[160:163], v232 offset:4096
	v_mfma_f32_16x16x32_bf16 v[30:33], v[196:199], v[172:175], v[30:33]
	ds_read_b128 v[164:167], v232 offset:6144
	s_add_u32 m0, s8, 0xc000
	v_mfma_f32_16x16x32_bf16 v[34:37], v[184:187], v[176:179], v[34:37]
	global_load_lds_dwordx4 v200, s[4:5]
	s_add_u32 m0, s8, 0xc400
	v_mfma_f32_16x16x32_bf16 v[38:41], v[188:191], v[176:179], v[38:41]
	global_load_lds_dwordx4 v201, s[4:5]
	s_add_u32 m0, s8, 0xc800
	v_mfma_f32_16x16x32_bf16 v[42:45], v[192:195], v[176:179], v[42:45]
	global_load_lds_dwordx4 v202, s[4:5]
	s_add_u32 m0, s8, 0xcc00
	v_mfma_f32_16x16x32_bf16 v[46:49], v[196:199], v[176:179], v[46:49]
	global_load_lds_dwordx4 v203, s[4:5]
	s_add_u32 m0, s9, 0xc000
	v_mfma_f32_16x16x32_bf16 v[50:53], v[184:187], v[180:183], v[50:53]
	global_load_lds_dwordx4 v204, s[6:7]
	s_add_u32 m0, s9, 0xc400
	v_mfma_f32_16x16x32_bf16 v[54:57], v[188:191], v[180:183], v[54:57]
	global_load_lds_dwordx4 v205, s[6:7]
	v_mfma_f32_16x16x32_bf16 v[58:61], v[192:195], v[180:183], v[58:61]
	s_add_u32 s4, s4, 0x80
	s_addc_u32 s5, s5, 0
	v_mfma_f32_16x16x32_bf16 v[62:65], v[196:199], v[180:183], v[62:65]
	s_add_u32 s6, s6, 0x80
	s_addc_u32 s7, s7, 0
	s_waitcnt lgkmcnt(0)
	v_mfma_f32_16x16x32_bf16 v[2:5], v[152:155], v[136:139], v[2:5]
	ds_read_b128 v[168:171], v229 offset:0
	v_mfma_f32_16x16x32_bf16 v[6:9], v[156:159], v[136:139], v[6:9]
	ds_read_b128 v[172:175], v229 offset:2048
	v_mfma_f32_16x16x32_bf16 v[10:13], v[160:163], v[136:139], v[10:13]
	ds_read_b128 v[176:179], v229 offset:4096
	v_mfma_f32_16x16x32_bf16 v[14:17], v[164:167], v[136:139], v[14:17]
	ds_read_b128 v[180:183], v229 offset:6144
	v_mfma_f32_16x16x32_bf16 v[18:21], v[152:155], v[140:143], v[18:21]
	ds_read_b128 v[184:187], v235 offset:0
	v_mfma_f32_16x16x32_bf16 v[22:25], v[156:159], v[140:143], v[22:25]
	ds_read_b128 v[188:191], v235 offset:2048
	v_mfma_f32_16x16x32_bf16 v[26:29], v[160:163], v[140:143], v[26:29]
	ds_read_b128 v[192:195], v235 offset:4096
	v_mfma_f32_16x16x32_bf16 v[30:33], v[164:167], v[140:143], v[30:33]
	ds_read_b128 v[196:199], v235 offset:6144
	v_mfma_f32_16x16x32_bf16 v[34:37], v[152:155], v[144:147], v[34:37]
	v_mfma_f32_16x16x32_bf16 v[38:41], v[156:159], v[144:147], v[38:41]
	v_mfma_f32_16x16x32_bf16 v[42:45], v[160:163], v[144:147], v[42:45]
	v_mfma_f32_16x16x32_bf16 v[46:49], v[164:167], v[144:147], v[46:49]
	v_mfma_f32_16x16x32_bf16 v[50:53], v[152:155], v[148:151], v[50:53]
	v_mfma_f32_16x16x32_bf16 v[54:57], v[156:159], v[148:151], v[54:57]
	v_mfma_f32_16x16x32_bf16 v[58:61], v[160:163], v[148:151], v[58:61]
	v_mfma_f32_16x16x32_bf16 v[62:65], v[164:167], v[148:151], v[62:65]
	s_waitcnt vmcnt(6) lgkmcnt(0)
	s_barrier
	v_mfma_f32_16x16x32_bf16 v[2:5], v[184:187], v[168:171], v[2:5]
	ds_read_b128 v[136:139], v218 offset:0
	v_mfma_f32_16x16x32_bf16 v[6:9], v[188:191], v[168:171], v[6:9]
	ds_read_b128 v[140:143], v218 offset:2048
	v_mfma_f32_16x16x32_bf16 v[10:13], v[192:195], v[168:171], v[10:13]
	ds_read_b128 v[144:147], v218 offset:4096
	v_mfma_f32_16x16x32_bf16 v[14:17], v[196:199], v[168:171], v[14:17]
	ds_read_b128 v[148:151], v218 offset:6144
	v_mfma_f32_16x16x32_bf16 v[18:21], v[184:187], v[172:175], v[18:21]
	ds_read_b128 v[152:155], v230 offset:0
	v_mfma_f32_16x16x32_bf16 v[22:25], v[188:191], v[172:175], v[22:25]
	ds_read_b128 v[156:159], v230 offset:2048
	v_mfma_f32_16x16x32_bf16 v[26:29], v[192:195], v[172:175], v[26:29]
	ds_read_b128 v[160:163], v230 offset:4096
	v_mfma_f32_16x16x32_bf16 v[30:33], v[196:199], v[172:175], v[30:33]
	ds_read_b128 v[164:167], v230 offset:6144
	s_add_u32 m0, s8, 0x18000
	v_mfma_f32_16x16x32_bf16 v[34:37], v[184:187], v[176:179], v[34:37]
	global_load_lds_dwordx4 v200, s[4:5]
	s_add_u32 m0, s8, 0x18400
	v_mfma_f32_16x16x32_bf16 v[38:41], v[188:191], v[176:179], v[38:41]
	global_load_lds_dwordx4 v201, s[4:5]
	s_add_u32 m0, s8, 0x18800
	v_mfma_f32_16x16x32_bf16 v[42:45], v[192:195], v[176:179], v[42:45]
	global_load_lds_dwordx4 v202, s[4:5]
	s_add_u32 m0, s8, 0x18c00
	v_mfma_f32_16x16x32_bf16 v[46:49], v[196:199], v[176:179], v[46:49]
	global_load_lds_dwordx4 v203, s[4:5]
	s_add_u32 m0, s9, 0x18000
	v_mfma_f32_16x16x32_bf16 v[50:53], v[184:187], v[180:183], v[50:53]
	global_load_lds_dwordx4 v204, s[6:7]
	s_add_u32 m0, s9, 0x18400
	v_mfma_f32_16x16x32_bf16 v[54:57], v[188:191], v[180:183], v[54:57]
	global_load_lds_dwordx4 v205, s[6:7]
	v_mfma_f32_16x16x32_bf16 v[58:61], v[192:195], v[180:183], v[58:61]
	s_add_u32 s4, s4, 0x80
	s_addc_u32 s5, s5, 0
	v_mfma_f32_16x16x32_bf16 v[62:65], v[196:199], v[180:183], v[62:65]
	s_add_u32 s6, s6, 0x80
	s_addc_u32 s7, s7, 0
	s_waitcnt lgkmcnt(0)
	v_mfma_f32_16x16x32_bf16 v[2:5], v[152:155], v[136:139], v[2:5]
	ds_read_b128 v[168:171], v225 offset:0
	v_mfma_f32_16x16x32_bf16 v[6:9], v[156:159], v[136:139], v[6:9]
	ds_read_b128 v[172:175], v225 offset:2048
	v_mfma_f32_16x16x32_bf16 v[10:13], v[160:163], v[136:139], v[10:13]
	ds_read_b128 v[176:179], v225 offset:4096
	v_mfma_f32_16x16x32_bf16 v[14:17], v[164:167], v[136:139], v[14:17]
	ds_read_b128 v[180:183], v225 offset:6144
	v_mfma_f32_16x16x32_bf16 v[18:21], v[152:155], v[140:143], v[18:21]
	ds_read_b128 v[184:187], v233 offset:0
	v_mfma_f32_16x16x32_bf16 v[22:25], v[156:159], v[140:143], v[22:25]
	ds_read_b128 v[188:191], v233 offset:2048
	v_mfma_f32_16x16x32_bf16 v[26:29], v[160:163], v[140:143], v[26:29]
	ds_read_b128 v[192:195], v233 offset:4096
	v_mfma_f32_16x16x32_bf16 v[30:33], v[164:167], v[140:143], v[30:33]
	ds_read_b128 v[196:199], v233 offset:6144
	v_mfma_f32_16x16x32_bf16 v[34:37], v[152:155], v[144:147], v[34:37]
	v_mfma_f32_16x16x32_bf16 v[38:41], v[156:159], v[144:147], v[38:41]
	v_mfma_f32_16x16x32_bf16 v[42:45], v[160:163], v[144:147], v[42:45]
	v_mfma_f32_16x16x32_bf16 v[46:49], v[164:167], v[144:147], v[46:49]
	v_mfma_f32_16x16x32_bf16 v[50:53], v[152:155], v[148:151], v[50:53]
	v_mfma_f32_16x16x32_bf16 v[54:57], v[156:159], v[148:151], v[54:57]
	v_mfma_f32_16x16x32_bf16 v[58:61], v[160:163], v[148:151], v[58:61]
	v_mfma_f32_16x16x32_bf16 v[62:65], v[164:167], v[148:151], v[62:65]
	s_waitcnt vmcnt(6) lgkmcnt(0)
	s_barrier
	v_mfma_f32_16x16x32_bf16 v[2:5], v[184:187], v[168:171], v[2:5]
	ds_read_b128 v[136:139], v219 offset:0
	v_mfma_f32_16x16x32_bf16 v[6:9], v[188:191], v[168:171], v[6:9]
	ds_read_b128 v[140:143], v219 offset:2048
	v_mfma_f32_16x16x32_bf16 v[10:13], v[192:195], v[168:171], v[10:13]
	ds_read_b128 v[144:147], v219 offset:4096
	v_mfma_f32_16x16x32_bf16 v[14:17], v[196:199], v[168:171], v[14:17]
	ds_read_b128 v[148:151], v219 offset:6144
	v_mfma_f32_16x16x32_bf16 v[18:21], v[184:187], v[172:175], v[18:21]
	ds_read_b128 v[152:155], v231 offset:0
	v_mfma_f32_16x16x32_bf16 v[22:25], v[188:191], v[172:175], v[22:25]
	ds_read_b128 v[156:159], v231 offset:2048
	v_mfma_f32_16x16x32_bf16 v[26:29], v[192:195], v[172:175], v[26:29]
	ds_read_b128 v[160:163], v231 offset:4096
	v_mfma_f32_16x16x32_bf16 v[30:33], v[196:199], v[172:175], v[30:33]
	ds_read_b128 v[164:167], v231 offset:6144
	s_mov_b32 m0, s8
	v_mfma_f32_16x16x32_bf16 v[34:37], v[184:187], v[176:179], v[34:37]
	global_load_lds_dwordx4 v200, s[4:5]
	s_add_u32 m0, s8, 0x400
	v_mfma_f32_16x16x32_bf16 v[38:41], v[188:191], v[176:179], v[38:41]
	global_load_lds_dwordx4 v201, s[4:5]
	s_add_u32 m0, s8, 0x800
	v_mfma_f32_16x16x32_bf16 v[42:45], v[192:195], v[176:179], v[42:45]
	global_load_lds_dwordx4 v202, s[4:5]
	s_add_u32 m0, s8, 0xc00
	v_mfma_f32_16x16x32_bf16 v[46:49], v[196:199], v[176:179], v[46:49]
	global_load_lds_dwordx4 v203, s[4:5]
	s_mov_b32 m0, s9
	v_mfma_f32_16x16x32_bf16 v[50:53], v[184:187], v[180:183], v[50:53]
	global_load_lds_dwordx4 v204, s[6:7]
	s_add_u32 m0, s9, 0x400
	v_mfma_f32_16x16x32_bf16 v[54:57], v[188:191], v[180:183], v[54:57]
	global_load_lds_dwordx4 v205, s[6:7]
	v_mfma_f32_16x16x32_bf16 v[58:61], v[192:195], v[180:183], v[58:61]
	s_add_u32 s4, s4, 0x80
	s_addc_u32 s5, s5, 0
	v_mfma_f32_16x16x32_bf16 v[62:65], v[196:199], v[180:183], v[62:65]
	s_add_u32 s6, s6, 0x80
	s_addc_u32 s7, s7, 0
	s_waitcnt lgkmcnt(0)
	v_mfma_f32_16x16x32_bf16 v[2:5], v[152:155], v[136:139], v[2:5]
	ds_read_b128 v[168:171], v228 offset:0
	v_mfma_f32_16x16x32_bf16 v[6:9], v[156:159], v[136:139], v[6:9]
	ds_read_b128 v[172:175], v228 offset:2048
	v_mfma_f32_16x16x32_bf16 v[10:13], v[160:163], v[136:139], v[10:13]
	ds_read_b128 v[176:179], v228 offset:4096
	v_mfma_f32_16x16x32_bf16 v[14:17], v[164:167], v[136:139], v[14:17]
	ds_read_b128 v[180:183], v228 offset:6144
	v_mfma_f32_16x16x32_bf16 v[18:21], v[152:155], v[140:143], v[18:21]
	ds_read_b128 v[184:187], v234 offset:0
	v_mfma_f32_16x16x32_bf16 v[22:25], v[156:159], v[140:143], v[22:25]
	ds_read_b128 v[188:191], v234 offset:2048
	v_mfma_f32_16x16x32_bf16 v[26:29], v[160:163], v[140:143], v[26:29]
	ds_read_b128 v[192:195], v234 offset:4096
	v_mfma_f32_16x16x32_bf16 v[30:33], v[164:167], v[140:143], v[30:33]
	ds_read_b128 v[196:199], v234 offset:6144
	v_mfma_f32_16x16x32_bf16 v[34:37], v[152:155], v[144:147], v[34:37]
	v_mfma_f32_16x16x32_bf16 v[38:41], v[156:159], v[144:147], v[38:41]
	v_mfma_f32_16x16x32_bf16 v[42:45], v[160:163], v[144:147], v[42:45]
	v_mfma_f32_16x16x32_bf16 v[46:49], v[164:167], v[144:147], v[46:49]
	v_mfma_f32_16x16x32_bf16 v[50:53], v[152:155], v[148:151], v[50:53]
	v_mfma_f32_16x16x32_bf16 v[54:57], v[156:159], v[148:151], v[54:57]
	v_mfma_f32_16x16x32_bf16 v[58:61], v[160:163], v[148:151], v[58:61]
	v_mfma_f32_16x16x32_bf16 v[62:65], v[164:167], v[148:151], v[62:65]
	s_waitcnt vmcnt(6) lgkmcnt(0)
	s_barrier
	v_mfma_f32_16x16x32_bf16 v[2:5], v[184:187], v[168:171], v[2:5]
	ds_read_b128 v[136:139], v224 offset:0
	v_mfma_f32_16x16x32_bf16 v[6:9], v[188:191], v[168:171], v[6:9]
	ds_read_b128 v[140:143], v224 offset:2048
	v_mfma_f32_16x16x32_bf16 v[10:13], v[192:195], v[168:171], v[10:13]
	ds_read_b128 v[144:147], v224 offset:4096
	v_mfma_f32_16x16x32_bf16 v[14:17], v[196:199], v[168:171], v[14:17]
	ds_read_b128 v[148:151], v224 offset:6144
	v_mfma_f32_16x16x32_bf16 v[18:21], v[184:187], v[172:175], v[18:21]
	ds_read_b128 v[152:155], v232 offset:0
	v_mfma_f32_16x16x32_bf16 v[22:25], v[188:191], v[172:175], v[22:25]
	ds_read_b128 v[156:159], v232 offset:2048
	v_mfma_f32_16x16x32_bf16 v[26:29], v[192:195], v[172:175], v[26:29]
	ds_read_b128 v[160:163], v232 offset:4096
	v_mfma_f32_16x16x32_bf16 v[30:33], v[196:199], v[172:175], v[30:33]
	ds_read_b128 v[164:167], v232 offset:6144
	s_add_u32 m0, s8, 0xc000
	v_mfma_f32_16x16x32_bf16 v[34:37], v[184:187], v[176:179], v[34:37]
	global_load_lds_dwordx4 v200, s[4:5]
	s_add_u32 m0, s8, 0xc400
	v_mfma_f32_16x16x32_bf16 v[38:41], v[188:191], v[176:179], v[38:41]
	global_load_lds_dwordx4 v201, s[4:5]
	s_add_u32 m0, s8, 0xc800
	v_mfma_f32_16x16x32_bf16 v[42:45], v[192:195], v[176:179], v[42:45]
	global_load_lds_dwordx4 v202, s[4:5]
	s_add_u32 m0, s8, 0xcc00
	v_mfma_f32_16x16x32_bf16 v[46:49], v[196:199], v[176:179], v[46:49]
	global_load_lds_dwordx4 v203, s[4:5]
	s_add_u32 m0, s9, 0xc000
	v_mfma_f32_16x16x32_bf16 v[50:53], v[184:187], v[180:183], v[50:53]
	global_load_lds_dwordx4 v204, s[6:7]
	s_add_u32 m0, s9, 0xc400
	v_mfma_f32_16x16x32_bf16 v[54:57], v[188:191], v[180:183], v[54:57]
	global_load_lds_dwordx4 v205, s[6:7]
	v_mfma_f32_16x16x32_bf16 v[58:61], v[192:195], v[180:183], v[58:61]
	s_add_u32 s4, s4, 0x80
	s_addc_u32 s5, s5, 0
	v_mfma_f32_16x16x32_bf16 v[62:65], v[196:199], v[180:183], v[62:65]
	s_add_u32 s6, s6, 0x80
	s_addc_u32 s7, s7, 0
	s_waitcnt lgkmcnt(0)
	v_mfma_f32_16x16x32_bf16 v[2:5], v[152:155], v[136:139], v[2:5]
	ds_read_b128 v[168:171], v229 offset:0
	v_mfma_f32_16x16x32_bf16 v[6:9], v[156:159], v[136:139], v[6:9]
	ds_read_b128 v[172:175], v229 offset:2048
	v_mfma_f32_16x16x32_bf16 v[10:13], v[160:163], v[136:139], v[10:13]
	ds_read_b128 v[176:179], v229 offset:4096
	v_mfma_f32_16x16x32_bf16 v[14:17], v[164:167], v[136:139], v[14:17]
	ds_read_b128 v[180:183], v229 offset:6144
	v_mfma_f32_16x16x32_bf16 v[18:21], v[152:155], v[140:143], v[18:21]
	ds_read_b128 v[184:187], v235 offset:0
	v_mfma_f32_16x16x32_bf16 v[22:25], v[156:159], v[140:143], v[22:25]
	ds_read_b128 v[188:191], v235 offset:2048
	v_mfma_f32_16x16x32_bf16 v[26:29], v[160:163], v[140:143], v[26:29]
	ds_read_b128 v[192:195], v235 offset:4096
	v_mfma_f32_16x16x32_bf16 v[30:33], v[164:167], v[140:143], v[30:33]
	ds_read_b128 v[196:199], v235 offset:6144
	v_mfma_f32_16x16x32_bf16 v[34:37], v[152:155], v[144:147], v[34:37]
	v_mfma_f32_16x16x32_bf16 v[38:41], v[156:159], v[144:147], v[38:41]
	v_mfma_f32_16x16x32_bf16 v[42:45], v[160:163], v[144:147], v[42:45]
	v_mfma_f32_16x16x32_bf16 v[46:49], v[164:167], v[144:147], v[46:49]
	v_mfma_f32_16x16x32_bf16 v[50:53], v[152:155], v[148:151], v[50:53]
	v_mfma_f32_16x16x32_bf16 v[54:57], v[156:159], v[148:151], v[54:57]
	v_mfma_f32_16x16x32_bf16 v[58:61], v[160:163], v[148:151], v[58:61]
	v_mfma_f32_16x16x32_bf16 v[62:65], v[164:167], v[148:151], v[62:65]
	s_waitcnt vmcnt(6) lgkmcnt(0)
	s_barrier
	v_mfma_f32_16x16x32_bf16 v[2:5], v[184:187], v[168:171], v[2:5]
	ds_read_b128 v[136:139], v218 offset:0
	v_mfma_f32_16x16x32_bf16 v[6:9], v[188:191], v[168:171], v[6:9]
	ds_read_b128 v[140:143], v218 offset:2048
	v_mfma_f32_16x16x32_bf16 v[10:13], v[192:195], v[168:171], v[10:13]
	ds_read_b128 v[144:147], v218 offset:4096
	v_mfma_f32_16x16x32_bf16 v[14:17], v[196:199], v[168:171], v[14:17]
	ds_read_b128 v[148:151], v218 offset:6144
	v_mfma_f32_16x16x32_bf16 v[18:21], v[184:187], v[172:175], v[18:21]
	ds_read_b128 v[152:155], v230 offset:0
	v_mfma_f32_16x16x32_bf16 v[22:25], v[188:191], v[172:175], v[22:25]
	ds_read_b128 v[156:159], v230 offset:2048
	v_mfma_f32_16x16x32_bf16 v[26:29], v[192:195], v[172:175], v[26:29]
	ds_read_b128 v[160:163], v230 offset:4096
	v_mfma_f32_16x16x32_bf16 v[30:33], v[196:199], v[172:175], v[30:33]
	ds_read_b128 v[164:167], v230 offset:6144
	s_add_u32 m0, s8, 0x18000
	v_mfma_f32_16x16x32_bf16 v[34:37], v[184:187], v[176:179], v[34:37]
	global_load_lds_dwordx4 v200, s[4:5]
	s_add_u32 m0, s8, 0x18400
	v_mfma_f32_16x16x32_bf16 v[38:41], v[188:191], v[176:179], v[38:41]
	global_load_lds_dwordx4 v201, s[4:5]
	s_add_u32 m0, s8, 0x18800
	v_mfma_f32_16x16x32_bf16 v[42:45], v[192:195], v[176:179], v[42:45]
	global_load_lds_dwordx4 v202, s[4:5]
	s_add_u32 m0, s8, 0x18c00
	v_mfma_f32_16x16x32_bf16 v[46:49], v[196:199], v[176:179], v[46:49]
	global_load_lds_dwordx4 v203, s[4:5]
	s_add_u32 m0, s9, 0x18000
	v_mfma_f32_16x16x32_bf16 v[50:53], v[184:187], v[180:183], v[50:53]
	global_load_lds_dwordx4 v204, s[6:7]
	s_add_u32 m0, s9, 0x18400
	v_mfma_f32_16x16x32_bf16 v[54:57], v[188:191], v[180:183], v[54:57]
	global_load_lds_dwordx4 v205, s[6:7]
	v_mfma_f32_16x16x32_bf16 v[58:61], v[192:195], v[180:183], v[58:61]
	s_add_u32 s4, s4, 0x80
	s_addc_u32 s5, s5, 0
	v_mfma_f32_16x16x32_bf16 v[62:65], v[196:199], v[180:183], v[62:65]
	s_add_u32 s6, s6, 0x80
	s_addc_u32 s7, s7, 0
	s_waitcnt lgkmcnt(0)
	v_mfma_f32_16x16x32_bf16 v[2:5], v[152:155], v[136:139], v[2:5]
	ds_read_b128 v[168:171], v225 offset:0
	v_mfma_f32_16x16x32_bf16 v[6:9], v[156:159], v[136:139], v[6:9]
	ds_read_b128 v[172:175], v225 offset:2048
	v_mfma_f32_16x16x32_bf16 v[10:13], v[160:163], v[136:139], v[10:13]
	ds_read_b128 v[176:179], v225 offset:4096
	v_mfma_f32_16x16x32_bf16 v[14:17], v[164:167], v[136:139], v[14:17]
	ds_read_b128 v[180:183], v225 offset:6144
	v_mfma_f32_16x16x32_bf16 v[18:21], v[152:155], v[140:143], v[18:21]
	ds_read_b128 v[184:187], v233 offset:0
	v_mfma_f32_16x16x32_bf16 v[22:25], v[156:159], v[140:143], v[22:25]
	ds_read_b128 v[188:191], v233 offset:2048
	v_mfma_f32_16x16x32_bf16 v[26:29], v[160:163], v[140:143], v[26:29]
	ds_read_b128 v[192:195], v233 offset:4096
	v_mfma_f32_16x16x32_bf16 v[30:33], v[164:167], v[140:143], v[30:33]
	ds_read_b128 v[196:199], v233 offset:6144
	v_mfma_f32_16x16x32_bf16 v[34:37], v[152:155], v[144:147], v[34:37]
	v_mfma_f32_16x16x32_bf16 v[38:41], v[156:159], v[144:147], v[38:41]
	v_mfma_f32_16x16x32_bf16 v[42:45], v[160:163], v[144:147], v[42:45]
	v_mfma_f32_16x16x32_bf16 v[46:49], v[164:167], v[144:147], v[46:49]
	v_mfma_f32_16x16x32_bf16 v[50:53], v[152:155], v[148:151], v[50:53]
	v_mfma_f32_16x16x32_bf16 v[54:57], v[156:159], v[148:151], v[54:57]
	v_mfma_f32_16x16x32_bf16 v[58:61], v[160:163], v[148:151], v[58:61]
	v_mfma_f32_16x16x32_bf16 v[62:65], v[164:167], v[148:151], v[62:65]
	s_waitcnt vmcnt(6) lgkmcnt(0)
	s_barrier
	v_mfma_f32_16x16x32_bf16 v[2:5], v[184:187], v[168:171], v[2:5]
	ds_read_b128 v[136:139], v219 offset:0
	v_mfma_f32_16x16x32_bf16 v[6:9], v[188:191], v[168:171], v[6:9]
	ds_read_b128 v[140:143], v219 offset:2048
	v_mfma_f32_16x16x32_bf16 v[10:13], v[192:195], v[168:171], v[10:13]
	ds_read_b128 v[144:147], v219 offset:4096
	v_mfma_f32_16x16x32_bf16 v[14:17], v[196:199], v[168:171], v[14:17]
	ds_read_b128 v[148:151], v219 offset:6144
	v_mfma_f32_16x16x32_bf16 v[18:21], v[184:187], v[172:175], v[18:21]
	ds_read_b128 v[152:155], v231 offset:0
	v_mfma_f32_16x16x32_bf16 v[22:25], v[188:191], v[172:175], v[22:25]
	ds_read_b128 v[156:159], v231 offset:2048
	v_mfma_f32_16x16x32_bf16 v[26:29], v[192:195], v[172:175], v[26:29]
	ds_read_b128 v[160:163], v231 offset:4096
	v_mfma_f32_16x16x32_bf16 v[30:33], v[196:199], v[172:175], v[30:33]
	ds_read_b128 v[164:167], v231 offset:6144
	s_mov_b32 m0, s8
	v_mfma_f32_16x16x32_bf16 v[34:37], v[184:187], v[176:179], v[34:37]
	global_load_lds_dwordx4 v200, s[4:5]
	s_add_u32 m0, s8, 0x400
	v_mfma_f32_16x16x32_bf16 v[38:41], v[188:191], v[176:179], v[38:41]
	global_load_lds_dwordx4 v201, s[4:5]
	s_add_u32 m0, s8, 0x800
	v_mfma_f32_16x16x32_bf16 v[42:45], v[192:195], v[176:179], v[42:45]
	global_load_lds_dwordx4 v202, s[4:5]
	s_add_u32 m0, s8, 0xc00
	v_mfma_f32_16x16x32_bf16 v[46:49], v[196:199], v[176:179], v[46:49]
	global_load_lds_dwordx4 v203, s[4:5]
	s_mov_b32 m0, s9
	v_mfma_f32_16x16x32_bf16 v[50:53], v[184:187], v[180:183], v[50:53]
	global_load_lds_dwordx4 v204, s[6:7]
	s_add_u32 m0, s9, 0x400
	v_mfma_f32_16x16x32_bf16 v[54:57], v[188:191], v[180:183], v[54:57]
	global_load_lds_dwordx4 v205, s[6:7]
	v_mfma_f32_16x16x32_bf16 v[58:61], v[192:195], v[180:183], v[58:61]
	s_sub_u32 s4, s4, 0x780
	s_subb_u32 s5, s5, 0
	v_mfma_f32_16x16x32_bf16 v[62:65], v[196:199], v[180:183], v[62:65]
	s_add_u32 s6, s6, 0x3f880
	s_addc_u32 s7, s7, 0
	s_waitcnt lgkmcnt(0)
	v_mfma_f32_16x16x32_bf16 v[2:5], v[152:155], v[136:139], v[2:5]
	ds_read_b128 v[168:171], v228 offset:0
	v_mfma_f32_16x16x32_bf16 v[6:9], v[156:159], v[136:139], v[6:9]
	ds_read_b128 v[172:175], v228 offset:2048
	v_mfma_f32_16x16x32_bf16 v[10:13], v[160:163], v[136:139], v[10:13]
	ds_read_b128 v[176:179], v228 offset:4096
	v_mfma_f32_16x16x32_bf16 v[14:17], v[164:167], v[136:139], v[14:17]
	ds_read_b128 v[180:183], v228 offset:6144
	v_mfma_f32_16x16x32_bf16 v[18:21], v[152:155], v[140:143], v[18:21]
	ds_read_b128 v[184:187], v234 offset:0
	v_mfma_f32_16x16x32_bf16 v[22:25], v[156:159], v[140:143], v[22:25]
	ds_read_b128 v[188:191], v234 offset:2048
	v_mfma_f32_16x16x32_bf16 v[26:29], v[160:163], v[140:143], v[26:29]
	ds_read_b128 v[192:195], v234 offset:4096
	v_mfma_f32_16x16x32_bf16 v[30:33], v[164:167], v[140:143], v[30:33]
	ds_read_b128 v[196:199], v234 offset:6144
	v_mfma_f32_16x16x32_bf16 v[34:37], v[152:155], v[144:147], v[34:37]
	v_mfma_f32_16x16x32_bf16 v[38:41], v[156:159], v[144:147], v[38:41]
	v_mfma_f32_16x16x32_bf16 v[42:45], v[160:163], v[144:147], v[42:45]
	v_mfma_f32_16x16x32_bf16 v[46:49], v[164:167], v[144:147], v[46:49]
	v_mfma_f32_16x16x32_bf16 v[50:53], v[152:155], v[148:151], v[50:53]
	v_mfma_f32_16x16x32_bf16 v[54:57], v[156:159], v[148:151], v[54:57]
	v_mfma_f32_16x16x32_bf16 v[58:61], v[160:163], v[148:151], v[58:61]
	v_mfma_f32_16x16x32_bf16 v[62:65], v[164:167], v[148:151], v[62:65]
	s_waitcnt vmcnt(6) lgkmcnt(0)
	s_barrier
	v_mfma_f32_16x16x32_bf16 v[2:5], v[184:187], v[168:171], v[2:5]
	ds_read_b128 v[136:139], v224 offset:0
	v_mfma_f32_16x16x32_bf16 v[6:9], v[188:191], v[168:171], v[6:9]
	ds_read_b128 v[140:143], v224 offset:2048
	v_mfma_f32_16x16x32_bf16 v[10:13], v[192:195], v[168:171], v[10:13]
	ds_read_b128 v[144:147], v224 offset:4096
	v_mfma_f32_16x16x32_bf16 v[14:17], v[196:199], v[168:171], v[14:17]
	ds_read_b128 v[148:151], v224 offset:6144
	v_mfma_f32_16x16x32_bf16 v[18:21], v[184:187], v[172:175], v[18:21]
	ds_read_b128 v[152:155], v232 offset:0
	v_mfma_f32_16x16x32_bf16 v[22:25], v[188:191], v[172:175], v[22:25]
	ds_read_b128 v[156:159], v232 offset:2048
	v_mfma_f32_16x16x32_bf16 v[26:29], v[192:195], v[172:175], v[26:29]
	ds_read_b128 v[160:163], v232 offset:4096
	v_mfma_f32_16x16x32_bf16 v[30:33], v[196:199], v[172:175], v[30:33]
	ds_read_b128 v[164:167], v232 offset:6144
	s_add_u32 m0, s8, 0xc000
	v_mfma_f32_16x16x32_bf16 v[34:37], v[184:187], v[176:179], v[34:37]
	global_load_lds_dwordx4 v200, s[4:5]
	s_add_u32 m0, s8, 0xc400
	v_mfma_f32_16x16x32_bf16 v[38:41], v[188:191], v[176:179], v[38:41]
	global_load_lds_dwordx4 v201, s[4:5]
	s_add_u32 m0, s8, 0xc800
	v_mfma_f32_16x16x32_bf16 v[42:45], v[192:195], v[176:179], v[42:45]
	global_load_lds_dwordx4 v202, s[4:5]
	s_add_u32 m0, s8, 0xcc00
	v_mfma_f32_16x16x32_bf16 v[46:49], v[196:199], v[176:179], v[46:49]
	global_load_lds_dwordx4 v203, s[4:5]
	s_add_u32 m0, s9, 0xc000
	v_mfma_f32_16x16x32_bf16 v[50:53], v[184:187], v[180:183], v[50:53]
	global_load_lds_dwordx4 v204, s[6:7]
	s_add_u32 m0, s9, 0xc400
	v_mfma_f32_16x16x32_bf16 v[54:57], v[188:191], v[180:183], v[54:57]
	global_load_lds_dwordx4 v205, s[6:7]
	v_mfma_f32_16x16x32_bf16 v[58:61], v[192:195], v[180:183], v[58:61]
	s_add_u32 s4, s4, 0x80
	s_addc_u32 s5, s5, 0
	v_mfma_f32_16x16x32_bf16 v[62:65], v[196:199], v[180:183], v[62:65]
	s_add_u32 s6, s6, 0x80
	s_addc_u32 s7, s7, 0
	s_waitcnt lgkmcnt(0)
	v_mfma_f32_16x16x32_bf16 v[2:5], v[152:155], v[136:139], v[2:5]
	ds_read_b128 v[168:171], v229 offset:0
	v_mfma_f32_16x16x32_bf16 v[6:9], v[156:159], v[136:139], v[6:9]
	ds_read_b128 v[172:175], v229 offset:2048
	v_mfma_f32_16x16x32_bf16 v[10:13], v[160:163], v[136:139], v[10:13]
	ds_read_b128 v[176:179], v229 offset:4096
	v_mfma_f32_16x16x32_bf16 v[14:17], v[164:167], v[136:139], v[14:17]
	ds_read_b128 v[180:183], v229 offset:6144
	v_mfma_f32_16x16x32_bf16 v[18:21], v[152:155], v[140:143], v[18:21]
	ds_read_b128 v[184:187], v235 offset:0
	v_mfma_f32_16x16x32_bf16 v[22:25], v[156:159], v[140:143], v[22:25]
	ds_read_b128 v[188:191], v235 offset:2048
	v_mfma_f32_16x16x32_bf16 v[26:29], v[160:163], v[140:143], v[26:29]
	ds_read_b128 v[192:195], v235 offset:4096
	v_mfma_f32_16x16x32_bf16 v[30:33], v[164:167], v[140:143], v[30:33]
	ds_read_b128 v[196:199], v235 offset:6144
	v_mfma_f32_16x16x32_bf16 v[34:37], v[152:155], v[144:147], v[34:37]
	v_mfma_f32_16x16x32_bf16 v[38:41], v[156:159], v[144:147], v[38:41]
	v_mfma_f32_16x16x32_bf16 v[42:45], v[160:163], v[144:147], v[42:45]
	v_mfma_f32_16x16x32_bf16 v[46:49], v[164:167], v[144:147], v[46:49]
	v_mfma_f32_16x16x32_bf16 v[50:53], v[152:155], v[148:151], v[50:53]
	v_mfma_f32_16x16x32_bf16 v[54:57], v[156:159], v[148:151], v[54:57]
	v_mfma_f32_16x16x32_bf16 v[58:61], v[160:163], v[148:151], v[58:61]
	v_mfma_f32_16x16x32_bf16 v[62:65], v[164:167], v[148:151], v[62:65]
	s_waitcnt vmcnt(6) lgkmcnt(0)
	s_barrier
	v_mfma_f32_16x16x32_bf16 v[2:5], v[184:187], v[168:171], v[2:5]
	ds_read_b128 v[136:139], v218 offset:0
	v_mfma_f32_16x16x32_bf16 v[6:9], v[188:191], v[168:171], v[6:9]
	ds_read_b128 v[140:143], v218 offset:2048
	v_mfma_f32_16x16x32_bf16 v[10:13], v[192:195], v[168:171], v[10:13]
	ds_read_b128 v[144:147], v218 offset:4096
	v_mfma_f32_16x16x32_bf16 v[14:17], v[196:199], v[168:171], v[14:17]
	ds_read_b128 v[148:151], v218 offset:6144
	v_mfma_f32_16x16x32_bf16 v[18:21], v[184:187], v[172:175], v[18:21]
	ds_read_b128 v[152:155], v230 offset:0
	v_mfma_f32_16x16x32_bf16 v[22:25], v[188:191], v[172:175], v[22:25]
	ds_read_b128 v[156:159], v230 offset:2048
	v_mfma_f32_16x16x32_bf16 v[26:29], v[192:195], v[172:175], v[26:29]
	ds_read_b128 v[160:163], v230 offset:4096
	v_mfma_f32_16x16x32_bf16 v[30:33], v[196:199], v[172:175], v[30:33]
	ds_read_b128 v[164:167], v230 offset:6144
	s_add_u32 m0, s8, 0x18000
	v_mfma_f32_16x16x32_bf16 v[34:37], v[184:187], v[176:179], v[34:37]
	global_load_lds_dwordx4 v200, s[4:5]
	s_add_u32 m0, s8, 0x18400
	v_mfma_f32_16x16x32_bf16 v[38:41], v[188:191], v[176:179], v[38:41]
	global_load_lds_dwordx4 v201, s[4:5]
	s_add_u32 m0, s8, 0x18800
	v_mfma_f32_16x16x32_bf16 v[42:45], v[192:195], v[176:179], v[42:45]
	global_load_lds_dwordx4 v202, s[4:5]
	s_add_u32 m0, s8, 0x18c00
	v_mfma_f32_16x16x32_bf16 v[46:49], v[196:199], v[176:179], v[46:49]
	global_load_lds_dwordx4 v203, s[4:5]
	s_add_u32 m0, s9, 0x18000
	v_mfma_f32_16x16x32_bf16 v[50:53], v[184:187], v[180:183], v[50:53]
	global_load_lds_dwordx4 v204, s[6:7]
	s_add_u32 m0, s9, 0x18400
	v_mfma_f32_16x16x32_bf16 v[54:57], v[188:191], v[180:183], v[54:57]
	global_load_lds_dwordx4 v205, s[6:7]
	v_mfma_f32_16x16x32_bf16 v[58:61], v[192:195], v[180:183], v[58:61]
	s_add_u32 s4, s4, 0x80
	s_addc_u32 s5, s5, 0
	v_mfma_f32_16x16x32_bf16 v[62:65], v[196:199], v[180:183], v[62:65]
	s_add_u32 s6, s6, 0x80
	s_addc_u32 s7, s7, 0
	s_waitcnt lgkmcnt(0)
	v_mfma_f32_16x16x32_bf16 v[2:5], v[152:155], v[136:139], v[2:5]
	ds_read_b128 v[168:171], v225 offset:0
	v_mfma_f32_16x16x32_bf16 v[6:9], v[156:159], v[136:139], v[6:9]
	ds_read_b128 v[172:175], v225 offset:2048
	v_mfma_f32_16x16x32_bf16 v[10:13], v[160:163], v[136:139], v[10:13]
	ds_read_b128 v[176:179], v225 offset:4096
	v_mfma_f32_16x16x32_bf16 v[14:17], v[164:167], v[136:139], v[14:17]
	ds_read_b128 v[180:183], v225 offset:6144
	v_mfma_f32_16x16x32_bf16 v[18:21], v[152:155], v[140:143], v[18:21]
	ds_read_b128 v[184:187], v233 offset:0
	v_mfma_f32_16x16x32_bf16 v[22:25], v[156:159], v[140:143], v[22:25]
	ds_read_b128 v[188:191], v233 offset:2048
	v_mfma_f32_16x16x32_bf16 v[26:29], v[160:163], v[140:143], v[26:29]
	ds_read_b128 v[192:195], v233 offset:4096
	v_mfma_f32_16x16x32_bf16 v[30:33], v[164:167], v[140:143], v[30:33]
	ds_read_b128 v[196:199], v233 offset:6144
	v_mfma_f32_16x16x32_bf16 v[34:37], v[152:155], v[144:147], v[34:37]
	v_mfma_f32_16x16x32_bf16 v[38:41], v[156:159], v[144:147], v[38:41]
	v_mfma_f32_16x16x32_bf16 v[42:45], v[160:163], v[144:147], v[42:45]
	v_mfma_f32_16x16x32_bf16 v[46:49], v[164:167], v[144:147], v[46:49]
	v_mfma_f32_16x16x32_bf16 v[50:53], v[152:155], v[148:151], v[50:53]
	v_mfma_f32_16x16x32_bf16 v[54:57], v[156:159], v[148:151], v[54:57]
	v_mfma_f32_16x16x32_bf16 v[58:61], v[160:163], v[148:151], v[58:61]
	v_mfma_f32_16x16x32_bf16 v[62:65], v[164:167], v[148:151], v[62:65]
	s_waitcnt vmcnt(6) lgkmcnt(0)
	s_barrier
	v_mfma_f32_16x16x32_bf16 v[2:5], v[184:187], v[168:171], v[2:5]
	ds_read_b128 v[136:139], v219 offset:0
	v_mfma_f32_16x16x32_bf16 v[6:9], v[188:191], v[168:171], v[6:9]
	ds_read_b128 v[140:143], v219 offset:2048
	v_mfma_f32_16x16x32_bf16 v[10:13], v[192:195], v[168:171], v[10:13]
	ds_read_b128 v[144:147], v219 offset:4096
	v_mfma_f32_16x16x32_bf16 v[14:17], v[196:199], v[168:171], v[14:17]
	ds_read_b128 v[148:151], v219 offset:6144
	v_mfma_f32_16x16x32_bf16 v[18:21], v[184:187], v[172:175], v[18:21]
	ds_read_b128 v[152:155], v231 offset:0
	v_mfma_f32_16x16x32_bf16 v[22:25], v[188:191], v[172:175], v[22:25]
	ds_read_b128 v[156:159], v231 offset:2048
	v_mfma_f32_16x16x32_bf16 v[26:29], v[192:195], v[172:175], v[26:29]
	ds_read_b128 v[160:163], v231 offset:4096
	v_mfma_f32_16x16x32_bf16 v[30:33], v[196:199], v[172:175], v[30:33]
	ds_read_b128 v[164:167], v231 offset:6144
	s_mov_b32 m0, s8
	v_mfma_f32_16x16x32_bf16 v[34:37], v[184:187], v[176:179], v[34:37]
	global_load_lds_dwordx4 v200, s[4:5]
	s_add_u32 m0, s8, 0x400
	v_mfma_f32_16x16x32_bf16 v[38:41], v[188:191], v[176:179], v[38:41]
	global_load_lds_dwordx4 v201, s[4:5]
	s_add_u32 m0, s8, 0x800
	v_mfma_f32_16x16x32_bf16 v[42:45], v[192:195], v[176:179], v[42:45]
	global_load_lds_dwordx4 v202, s[4:5]
	s_add_u32 m0, s8, 0xc00
	v_mfma_f32_16x16x32_bf16 v[46:49], v[196:199], v[176:179], v[46:49]
	global_load_lds_dwordx4 v203, s[4:5]
	s_mov_b32 m0, s9
	v_mfma_f32_16x16x32_bf16 v[50:53], v[184:187], v[180:183], v[50:53]
	global_load_lds_dwordx4 v204, s[6:7]
	s_add_u32 m0, s9, 0x400
	v_mfma_f32_16x16x32_bf16 v[54:57], v[188:191], v[180:183], v[54:57]
	global_load_lds_dwordx4 v205, s[6:7]
	v_mfma_f32_16x16x32_bf16 v[58:61], v[192:195], v[180:183], v[58:61]
	s_add_u32 s4, s4, 0x80
	s_addc_u32 s5, s5, 0
	v_mfma_f32_16x16x32_bf16 v[62:65], v[196:199], v[180:183], v[62:65]
	s_add_u32 s6, s6, 0x80
	s_addc_u32 s7, s7, 0
	s_waitcnt lgkmcnt(0)
	v_mfma_f32_16x16x32_bf16 v[66:69], v[152:155], v[136:139], 0
	ds_read_b128 v[168:171], v228 offset:0
	v_mfma_f32_16x16x32_bf16 v[70:73], v[156:159], v[136:139], 0
	ds_read_b128 v[172:175], v228 offset:2048
	s_add_u32 s10, s54, 0x0
	s_addc_u32 s11, s55, 0
	v_mfma_f32_16x16x32_bf16 v[74:77], v[160:163], v[136:139], 0
	ds_read_b128 v[176:179], v228 offset:4096
	v_mul_f32_e32 v1, s12, v2
	v_mfma_f32_16x16x32_bf16 v[78:81], v[164:167], v[136:139], 0
	ds_read_b128 v[180:183], v228 offset:6144
	v_mul_f32_e32 v130, s12, v3
	v_mfma_f32_16x16x32_bf16 v[82:85], v[152:155], v[140:143], 0
	ds_read_b128 v[184:187], v234 offset:0
	v_mul_f32_e32 v238, s12, v4
	v_mfma_f32_16x16x32_bf16 v[86:89], v[156:159], v[140:143], 0
	ds_read_b128 v[188:191], v234 offset:2048
	v_mul_f32_e32 v239, s12, v5
	v_mfma_f32_16x16x32_bf16 v[90:93], v[160:163], v[140:143], 0
	ds_read_b128 v[192:195], v234 offset:4096
	v_exp_f32_e32 v1, v1
	v_mfma_f32_16x16x32_bf16 v[94:97], v[164:167], v[140:143], 0
	ds_read_b128 v[196:199], v234 offset:6144
	v_exp_f32_e32 v130, v130
	v_mfma_f32_16x16x32_bf16 v[98:101], v[152:155], v[144:147], 0
	v_mfma_f32_16x16x32_bf16 v[102:105], v[156:159], v[144:147], 0
	v_exp_f32_e32 v238, v238
	v_mfma_f32_16x16x32_bf16 v[106:109], v[160:163], v[144:147], 0
	v_exp_f32_e32 v239, v239
	v_mfma_f32_16x16x32_bf16 v[110:113], v[164:167], v[144:147], 0
	v_add_f32_e32 v1, 1.0, v1
	v_mfma_f32_16x16x32_bf16 v[114:117], v[152:155], v[148:151], 0
	v_add_f32_e32 v130, 1.0, v130
	v_mfma_f32_16x16x32_bf16 v[118:121], v[156:159], v[148:151], 0
	v_add_f32_e32 v238, 1.0, v238
	v_mfma_f32_16x16x32_bf16 v[122:125], v[160:163], v[148:151], 0
	v_add_f32_e32 v239, 1.0, v239
	v_mfma_f32_16x16x32_bf16 v[126:129], v[164:167], v[148:151], 0
	v_rcp_f32_e32 v1, v1
	s_waitcnt vmcnt(6) lgkmcnt(0)
	s_barrier
	v_mfma_f32_16x16x32_bf16 v[66:69], v[184:187], v[168:171], v[66:69]
	ds_read_b128 v[136:139], v224 offset:0
	v_mfma_f32_16x16x32_bf16 v[70:73], v[188:191], v[168:171], v[70:73]
	ds_read_b128 v[140:143], v224 offset:2048
	v_rcp_f32_e32 v130, v130
	v_mfma_f32_16x16x32_bf16 v[74:77], v[192:195], v[168:171], v[74:77]
	ds_read_b128 v[144:147], v224 offset:4096
	v_mfma_f32_16x16x32_bf16 v[78:81], v[196:199], v[168:171], v[78:81]
	ds_read_b128 v[148:151], v224 offset:6144
	v_rcp_f32_e32 v238, v238
	v_mfma_f32_16x16x32_bf16 v[82:85], v[184:187], v[172:175], v[82:85]
	ds_read_b128 v[152:155], v232 offset:0
	v_rcp_f32_e32 v239, v239
	v_mfma_f32_16x16x32_bf16 v[86:89], v[188:191], v[172:175], v[86:89]
	ds_read_b128 v[156:159], v232 offset:2048
	v_mfma_f32_16x16x32_bf16 v[90:93], v[192:195], v[172:175], v[90:93]
	ds_read_b128 v[160:163], v232 offset:4096
	v_mul_f32_e32 v2, v2, v1
	v_mfma_f32_16x16x32_bf16 v[94:97], v[196:199], v[172:175], v[94:97]
	ds_read_b128 v[164:167], v232 offset:6144
	v_mul_f32_e32 v3, v3, v130
	s_add_u32 m0, s8, 0xc000
	v_mfma_f32_16x16x32_bf16 v[98:101], v[184:187], v[176:179], v[98:101]
	global_load_lds_dwordx4 v200, s[4:5]
	s_add_u32 m0, s8, 0xc400
	v_mfma_f32_16x16x32_bf16 v[102:105], v[188:191], v[176:179], v[102:105]
	global_load_lds_dwordx4 v201, s[4:5]
	v_mul_f32_e32 v4, v4, v238
	s_add_u32 m0, s8, 0xc800
	v_mfma_f32_16x16x32_bf16 v[106:109], v[192:195], v[176:179], v[106:109]
	global_load_lds_dwordx4 v202, s[4:5]
	s_add_u32 m0, s8, 0xcc00
	v_mfma_f32_16x16x32_bf16 v[110:113], v[196:199], v[176:179], v[110:113]
	global_load_lds_dwordx4 v203, s[4:5]
	v_mul_f32_e32 v5, v5, v239
	s_add_u32 m0, s9, 0xc000
	v_mfma_f32_16x16x32_bf16 v[114:117], v[184:187], v[180:183], v[114:117]
	global_load_lds_dwordx4 v204, s[6:7]
	v_cvt_pk_bf16_f32 v2, v2, v3
	s_add_u32 m0, s9, 0xc400
	v_mfma_f32_16x16x32_bf16 v[118:121], v[188:191], v[180:183], v[118:121]
	global_load_lds_dwordx4 v205, s[6:7]
	v_mfma_f32_16x16x32_bf16 v[122:125], v[192:195], v[180:183], v[122:125]
	s_add_u32 s4, s4, 0x80
	s_addc_u32 s5, s5, 0
	v_cvt_pk_bf16_f32 v3, v4, v5
	v_mfma_f32_16x16x32_bf16 v[126:129], v[196:199], v[180:183], v[126:129]
	s_add_u32 s6, s6, 0x80
	s_addc_u32 s7, s7, 0
	global_store_dwordx2 v236, v[2:3], s[10:11] offset:0 sc1
	s_waitcnt lgkmcnt(0)
	v_mfma_f32_16x16x32_bf16 v[66:69], v[152:155], v[136:139], v[66:69]
	ds_read_b128 v[168:171], v229 offset:0
	v_mfma_f32_16x16x32_bf16 v[70:73], v[156:159], v[136:139], v[70:73]
	ds_read_b128 v[172:175], v229 offset:2048
	v_mul_f32_e32 v1, s12, v6
	v_mfma_f32_16x16x32_bf16 v[74:77], v[160:163], v[136:139], v[74:77]
	ds_read_b128 v[176:179], v229 offset:4096
	v_mul_f32_e32 v130, s12, v7
	v_mfma_f32_16x16x32_bf16 v[78:81], v[164:167], v[136:139], v[78:81]
	ds_read_b128 v[180:183], v229 offset:6144
	v_mul_f32_e32 v238, s12, v8
	v_mfma_f32_16x16x32_bf16 v[82:85], v[152:155], v[140:143], v[82:85]
	ds_read_b128 v[184:187], v235 offset:0
	v_mul_f32_e32 v239, s12, v9
	v_mfma_f32_16x16x32_bf16 v[86:89], v[156:159], v[140:143], v[86:89]
	ds_read_b128 v[188:191], v235 offset:2048
	v_exp_f32_e32 v1, v1
	v_mfma_f32_16x16x32_bf16 v[90:93], v[160:163], v[140:143], v[90:93]
	ds_read_b128 v[192:195], v235 offset:4096
	v_exp_f32_e32 v130, v130
	v_mfma_f32_16x16x32_bf16 v[94:97], v[164:167], v[140:143], v[94:97]
	ds_read_b128 v[196:199], v235 offset:6144
	v_exp_f32_e32 v238, v238
	v_mfma_f32_16x16x32_bf16 v[98:101], v[152:155], v[144:147], v[98:101]
	v_mfma_f32_16x16x32_bf16 v[102:105], v[156:159], v[144:147], v[102:105]
	v_exp_f32_e32 v239, v239
	v_mfma_f32_16x16x32_bf16 v[106:109], v[160:163], v[144:147], v[106:109]
	v_add_f32_e32 v1, 1.0, v1
	v_mfma_f32_16x16x32_bf16 v[110:113], v[164:167], v[144:147], v[110:113]
	v_add_f32_e32 v130, 1.0, v130
	v_mfma_f32_16x16x32_bf16 v[114:117], v[152:155], v[148:151], v[114:117]
	v_add_f32_e32 v238, 1.0, v238
	v_mfma_f32_16x16x32_bf16 v[118:121], v[156:159], v[148:151], v[118:121]
	v_add_f32_e32 v239, 1.0, v239
	v_mfma_f32_16x16x32_bf16 v[122:125], v[160:163], v[148:151], v[122:125]
	v_rcp_f32_e32 v1, v1
	v_mfma_f32_16x16x32_bf16 v[126:129], v[164:167], v[148:151], v[126:129]
	v_rcp_f32_e32 v130, v130
	s_waitcnt vmcnt(7) lgkmcnt(0)
	s_barrier
	v_mfma_f32_16x16x32_bf16 v[66:69], v[184:187], v[168:171], v[66:69]
	ds_read_b128 v[136:139], v218 offset:0
	v_mfma_f32_16x16x32_bf16 v[70:73], v[188:191], v[168:171], v[70:73]
	ds_read_b128 v[140:143], v218 offset:2048
	v_rcp_f32_e32 v238, v238
	v_mfma_f32_16x16x32_bf16 v[74:77], v[192:195], v[168:171], v[74:77]
	ds_read_b128 v[144:147], v218 offset:4096
	v_mfma_f32_16x16x32_bf16 v[78:81], v[196:199], v[168:171], v[78:81]
	ds_read_b128 v[148:151], v218 offset:6144
	v_rcp_f32_e32 v239, v239
	v_mfma_f32_16x16x32_bf16 v[82:85], v[184:187], v[172:175], v[82:85]
	ds_read_b128 v[152:155], v230 offset:0
	v_mul_f32_e32 v6, v6, v1
	v_mfma_f32_16x16x32_bf16 v[86:89], v[188:191], v[172:175], v[86:89]
	ds_read_b128 v[156:159], v230 offset:2048
	v_mfma_f32_16x16x32_bf16 v[90:93], v[192:195], v[172:175], v[90:93]
	ds_read_b128 v[160:163], v230 offset:4096
	v_mul_f32_e32 v7, v7, v130
	v_mfma_f32_16x16x32_bf16 v[94:97], v[196:199], v[172:175], v[94:97]
	ds_read_b128 v[164:167], v230 offset:6144
	v_mul_f32_e32 v8, v8, v238
	s_add_u32 m0, s8, 0x18000
	v_mfma_f32_16x16x32_bf16 v[98:101], v[184:187], v[176:179], v[98:101]
	global_load_lds_dwordx4 v200, s[4:5]
	s_add_u32 m0, s8, 0x18400
	v_mfma_f32_16x16x32_bf16 v[102:105], v[188:191], v[176:179], v[102:105]
	global_load_lds_dwordx4 v201, s[4:5]
	v_mul_f32_e32 v9, v9, v239
	s_add_u32 m0, s8, 0x18800
	v_mfma_f32_16x16x32_bf16 v[106:109], v[192:195], v[176:179], v[106:109]
	global_load_lds_dwordx4 v202, s[4:5]
	s_add_u32 m0, s8, 0x18c00
	v_mfma_f32_16x16x32_bf16 v[110:113], v[196:199], v[176:179], v[110:113]
	global_load_lds_dwordx4 v203, s[4:5]
	v_cvt_pk_bf16_f32 v6, v6, v7
	s_add_u32 m0, s9, 0x18000
	v_mfma_f32_16x16x32_bf16 v[114:117], v[184:187], v[180:183], v[114:117]
	global_load_lds_dwordx4 v204, s[6:7]
	v_cvt_pk_bf16_f32 v7, v8, v9
	s_add_u32 m0, s9, 0x18400
	v_mfma_f32_16x16x32_bf16 v[118:121], v[188:191], v[180:183], v[118:121]
	global_load_lds_dwordx4 v205, s[6:7]
	v_mfma_f32_16x16x32_bf16 v[122:125], v[192:195], v[180:183], v[122:125]
	s_add_u32 s4, s4, 0x80
	s_addc_u32 s5, s5, 0
	global_store_dwordx2 v236, v[6:7], s[10:11] offset:32 sc1
	v_mfma_f32_16x16x32_bf16 v[126:129], v[196:199], v[180:183], v[126:129]
	s_add_u32 s6, s6, 0x80
	s_addc_u32 s7, s7, 0
	v_mul_f32_e32 v1, s12, v10
	s_waitcnt lgkmcnt(0)
	v_mfma_f32_16x16x32_bf16 v[66:69], v[152:155], v[136:139], v[66:69]
	ds_read_b128 v[168:171], v225 offset:0
	v_mfma_f32_16x16x32_bf16 v[70:73], v[156:159], v[136:139], v[70:73]
	ds_read_b128 v[172:175], v225 offset:2048
	v_mul_f32_e32 v130, s12, v11
	v_mfma_f32_16x16x32_bf16 v[74:77], v[160:163], v[136:139], v[74:77]
	ds_read_b128 v[176:179], v225 offset:4096
	v_mul_f32_e32 v238, s12, v12
	v_mfma_f32_16x16x32_bf16 v[78:81], v[164:167], v[136:139], v[78:81]
	ds_read_b128 v[180:183], v225 offset:6144
	v_mul_f32_e32 v239, s12, v13
	v_mfma_f32_16x16x32_bf16 v[82:85], v[152:155], v[140:143], v[82:85]
	ds_read_b128 v[184:187], v233 offset:0
	v_exp_f32_e32 v1, v1
	v_mfma_f32_16x16x32_bf16 v[86:89], v[156:159], v[140:143], v[86:89]
	ds_read_b128 v[188:191], v233 offset:2048
	v_exp_f32_e32 v130, v130
	v_mfma_f32_16x16x32_bf16 v[90:93], v[160:163], v[140:143], v[90:93]
	ds_read_b128 v[192:195], v233 offset:4096
	v_exp_f32_e32 v238, v238
	v_mfma_f32_16x16x32_bf16 v[94:97], v[164:167], v[140:143], v[94:97]
	ds_read_b128 v[196:199], v233 offset:6144
	v_exp_f32_e32 v239, v239
	v_mfma_f32_16x16x32_bf16 v[98:101], v[152:155], v[144:147], v[98:101]
	v_mfma_f32_16x16x32_bf16 v[102:105], v[156:159], v[144:147], v[102:105]
	v_add_f32_e32 v1, 1.0, v1
	v_mfma_f32_16x16x32_bf16 v[106:109], v[160:163], v[144:147], v[106:109]
	v_add_f32_e32 v130, 1.0, v130
	v_mfma_f32_16x16x32_bf16 v[110:113], v[164:167], v[144:147], v[110:113]
	v_add_f32_e32 v238, 1.0, v238
	v_mfma_f32_16x16x32_bf16 v[114:117], v[152:155], v[148:151], v[114:117]
	v_add_f32_e32 v239, 1.0, v239
	v_mfma_f32_16x16x32_bf16 v[118:121], v[156:159], v[148:151], v[118:121]
	v_rcp_f32_e32 v1, v1
	v_mfma_f32_16x16x32_bf16 v[122:125], v[160:163], v[148:151], v[122:125]
	v_rcp_f32_e32 v130, v130
	v_mfma_f32_16x16x32_bf16 v[126:129], v[164:167], v[148:151], v[126:129]
	v_rcp_f32_e32 v238, v238
	s_waitcnt vmcnt(8) lgkmcnt(0)
	s_barrier
	v_mfma_f32_16x16x32_bf16 v[66:69], v[184:187], v[168:171], v[66:69]
	ds_read_b128 v[136:139], v219 offset:0
	v_mfma_f32_16x16x32_bf16 v[70:73], v[188:191], v[168:171], v[70:73]
	ds_read_b128 v[140:143], v219 offset:2048
	v_rcp_f32_e32 v239, v239
	v_mfma_f32_16x16x32_bf16 v[74:77], v[192:195], v[168:171], v[74:77]
	ds_read_b128 v[144:147], v219 offset:4096
	v_mfma_f32_16x16x32_bf16 v[78:81], v[196:199], v[168:171], v[78:81]
	ds_read_b128 v[148:151], v219 offset:6144
	v_mul_f32_e32 v10, v10, v1
	v_mfma_f32_16x16x32_bf16 v[82:85], v[184:187], v[172:175], v[82:85]
	ds_read_b128 v[152:155], v231 offset:0
	v_mul_f32_e32 v11, v11, v130
	v_mfma_f32_16x16x32_bf16 v[86:89], v[188:191], v[172:175], v[86:89]
	ds_read_b128 v[156:159], v231 offset:2048
	v_mfma_f32_16x16x32_bf16 v[90:93], v[192:195], v[172:175], v[90:93]
	ds_read_b128 v[160:163], v231 offset:4096
	v_mul_f32_e32 v12, v12, v238
	v_mfma_f32_16x16x32_bf16 v[94:97], v[196:199], v[172:175], v[94:97]
	ds_read_b128 v[164:167], v231 offset:6144
	v_mul_f32_e32 v13, v13, v239
	s_mov_b32 m0, s8
	v_mfma_f32_16x16x32_bf16 v[98:101], v[184:187], v[176:179], v[98:101]
	global_load_lds_dwordx4 v200, s[4:5]
	s_add_u32 m0, s8, 0x400
	v_mfma_f32_16x16x32_bf16 v[102:105], v[188:191], v[176:179], v[102:105]
	global_load_lds_dwordx4 v201, s[4:5]
	v_cvt_pk_bf16_f32 v10, v10, v11
	s_add_u32 m0, s8, 0x800
	v_mfma_f32_16x16x32_bf16 v[106:109], v[192:195], v[176:179], v[106:109]
	global_load_lds_dwordx4 v202, s[4:5]
	s_add_u32 m0, s8, 0xc00
	v_mfma_f32_16x16x32_bf16 v[110:113], v[196:199], v[176:179], v[110:113]
	global_load_lds_dwordx4 v203, s[4:5]
	v_cvt_pk_bf16_f32 v11, v12, v13
	s_mov_b32 m0, s9
	v_mfma_f32_16x16x32_bf16 v[114:117], v[184:187], v[180:183], v[114:117]
	global_load_lds_dwordx4 v204, s[6:7]
	global_store_dwordx2 v236, v[10:11], s[10:11] offset:64 sc1
	s_add_u32 m0, s9, 0x400
	v_mfma_f32_16x16x32_bf16 v[118:121], v[188:191], v[180:183], v[118:121]
	global_load_lds_dwordx4 v205, s[6:7]
	v_mfma_f32_16x16x32_bf16 v[122:125], v[192:195], v[180:183], v[122:125]
	s_add_u32 s4, s4, 0x80
	s_addc_u32 s5, s5, 0
	v_mul_f32_e32 v1, s12, v14
	v_mfma_f32_16x16x32_bf16 v[126:129], v[196:199], v[180:183], v[126:129]
	s_add_u32 s6, s6, 0x80
	s_addc_u32 s7, s7, 0
	v_mul_f32_e32 v130, s12, v15
	s_waitcnt lgkmcnt(0)
	v_mfma_f32_16x16x32_bf16 v[66:69], v[152:155], v[136:139], v[66:69]
	ds_read_b128 v[168:171], v228 offset:0
	v_mfma_f32_16x16x32_bf16 v[70:73], v[156:159], v[136:139], v[70:73]
	ds_read_b128 v[172:175], v228 offset:2048
	v_mul_f32_e32 v238, s12, v16
	v_mfma_f32_16x16x32_bf16 v[74:77], v[160:163], v[136:139], v[74:77]
	ds_read_b128 v[176:179], v228 offset:4096
	v_mul_f32_e32 v239, s12, v17
	v_mfma_f32_16x16x32_bf16 v[78:81], v[164:167], v[136:139], v[78:81]
	ds_read_b128 v[180:183], v228 offset:6144
	v_exp_f32_e32 v1, v1
	v_mfma_f32_16x16x32_bf16 v[82:85], v[152:155], v[140:143], v[82:85]
	ds_read_b128 v[184:187], v234 offset:0
	v_exp_f32_e32 v130, v130
	v_mfma_f32_16x16x32_bf16 v[86:89], v[156:159], v[140:143], v[86:89]
	ds_read_b128 v[188:191], v234 offset:2048
	v_exp_f32_e32 v238, v238
	v_mfma_f32_16x16x32_bf16 v[90:93], v[160:163], v[140:143], v[90:93]
	ds_read_b128 v[192:195], v234 offset:4096
	v_exp_f32_e32 v239, v239
	v_mfma_f32_16x16x32_bf16 v[94:97], v[164:167], v[140:143], v[94:97]
	ds_read_b128 v[196:199], v234 offset:6144
	v_add_f32_e32 v1, 1.0, v1
	v_mfma_f32_16x16x32_bf16 v[98:101], v[152:155], v[144:147], v[98:101]
	v_mfma_f32_16x16x32_bf16 v[102:105], v[156:159], v[144:147], v[102:105]
	v_add_f32_e32 v130, 1.0, v130
	v_mfma_f32_16x16x32_bf16 v[106:109], v[160:163], v[144:147], v[106:109]
	v_add_f32_e32 v238, 1.0, v238
	v_mfma_f32_16x16x32_bf16 v[110:113], v[164:167], v[144:147], v[110:113]
	v_add_f32_e32 v239, 1.0, v239
	v_mfma_f32_16x16x32_bf16 v[114:117], v[152:155], v[148:151], v[114:117]
	v_rcp_f32_e32 v1, v1
	v_mfma_f32_16x16x32_bf16 v[118:121], v[156:159], v[148:151], v[118:121]
	v_rcp_f32_e32 v130, v130
	v_mfma_f32_16x16x32_bf16 v[122:125], v[160:163], v[148:151], v[122:125]
	v_rcp_f32_e32 v238, v238
	v_mfma_f32_16x16x32_bf16 v[126:129], v[164:167], v[148:151], v[126:129]
	v_rcp_f32_e32 v239, v239
	s_waitcnt vmcnt(8) lgkmcnt(0)
	s_barrier
	v_mfma_f32_16x16x32_bf16 v[66:69], v[184:187], v[168:171], v[66:69]
	ds_read_b128 v[136:139], v224 offset:0
	v_mfma_f32_16x16x32_bf16 v[70:73], v[188:191], v[168:171], v[70:73]
	ds_read_b128 v[140:143], v224 offset:2048
	v_mul_f32_e32 v14, v14, v1
	v_mfma_f32_16x16x32_bf16 v[74:77], v[192:195], v[168:171], v[74:77]
	ds_read_b128 v[144:147], v224 offset:4096
	v_mfma_f32_16x16x32_bf16 v[78:81], v[196:199], v[168:171], v[78:81]
	ds_read_b128 v[148:151], v224 offset:6144
	v_mul_f32_e32 v15, v15, v130
	v_mfma_f32_16x16x32_bf16 v[82:85], v[184:187], v[172:175], v[82:85]
	ds_read_b128 v[152:155], v232 offset:0
	v_mul_f32_e32 v16, v16, v238
	v_mfma_f32_16x16x32_bf16 v[86:89], v[188:191], v[172:175], v[86:89]
	ds_read_b128 v[156:159], v232 offset:2048
	v_mfma_f32_16x16x32_bf16 v[90:93], v[192:195], v[172:175], v[90:93]
	ds_read_b128 v[160:163], v232 offset:4096
	v_mul_f32_e32 v17, v17, v239
	v_mfma_f32_16x16x32_bf16 v[94:97], v[196:199], v[172:175], v[94:97]
	ds_read_b128 v[164:167], v232 offset:6144
	v_cvt_pk_bf16_f32 v14, v14, v15
	s_add_u32 m0, s8, 0xc000
	v_mfma_f32_16x16x32_bf16 v[98:101], v[184:187], v[176:179], v[98:101]
	global_load_lds_dwordx4 v200, s[4:5]
	s_add_u32 m0, s8, 0xc400
	v_mfma_f32_16x16x32_bf16 v[102:105], v[188:191], v[176:179], v[102:105]
	global_load_lds_dwordx4 v201, s[4:5]
	v_cvt_pk_bf16_f32 v15, v16, v17
	s_add_u32 m0, s8, 0xc800
	v_mfma_f32_16x16x32_bf16 v[106:109], v[192:195], v[176:179], v[106:109]
	global_load_lds_dwordx4 v202, s[4:5]
	s_add_u32 m0, s8, 0xcc00
	v_mfma_f32_16x16x32_bf16 v[110:113], v[196:199], v[176:179], v[110:113]
	global_load_lds_dwordx4 v203, s[4:5]
	global_store_dwordx2 v236, v[14:15], s[10:11] offset:96 sc1
	s_add_u32 m0, s9, 0xc000
	v_mfma_f32_16x16x32_bf16 v[114:117], v[184:187], v[180:183], v[114:117]
	global_load_lds_dwordx4 v204, s[6:7]
	s_add_u32 s10, s10, 0x8000
	s_addc_u32 s11, s11, 0
	s_add_u32 m0, s9, 0xc400
	v_mfma_f32_16x16x32_bf16 v[118:121], v[188:191], v[180:183], v[118:121]
	global_load_lds_dwordx4 v205, s[6:7]
	v_mfma_f32_16x16x32_bf16 v[122:125], v[192:195], v[180:183], v[122:125]
	s_add_u32 s4, s4, 0x80
	s_addc_u32 s5, s5, 0
	v_mul_f32_e32 v1, s12, v18
	v_mfma_f32_16x16x32_bf16 v[126:129], v[196:199], v[180:183], v[126:129]
	s_add_u32 s6, s6, 0x80
	s_addc_u32 s7, s7, 0
	v_mul_f32_e32 v130, s12, v19
	s_waitcnt lgkmcnt(0)
	v_mfma_f32_16x16x32_bf16 v[66:69], v[152:155], v[136:139], v[66:69]
	ds_read_b128 v[168:171], v229 offset:0
	v_mfma_f32_16x16x32_bf16 v[70:73], v[156:159], v[136:139], v[70:73]
	ds_read_b128 v[172:175], v229 offset:2048
	v_mul_f32_e32 v238, s12, v20
	v_mfma_f32_16x16x32_bf16 v[74:77], v[160:163], v[136:139], v[74:77]
	ds_read_b128 v[176:179], v229 offset:4096
	v_mul_f32_e32 v239, s12, v21
	v_mfma_f32_16x16x32_bf16 v[78:81], v[164:167], v[136:139], v[78:81]
	ds_read_b128 v[180:183], v229 offset:6144
	v_exp_f32_e32 v1, v1
	v_mfma_f32_16x16x32_bf16 v[82:85], v[152:155], v[140:143], v[82:85]
	ds_read_b128 v[184:187], v235 offset:0
	v_exp_f32_e32 v130, v130
	v_mfma_f32_16x16x32_bf16 v[86:89], v[156:159], v[140:143], v[86:89]
	ds_read_b128 v[188:191], v235 offset:2048
	v_exp_f32_e32 v238, v238
	v_mfma_f32_16x16x32_bf16 v[90:93], v[160:163], v[140:143], v[90:93]
	ds_read_b128 v[192:195], v235 offset:4096
	v_exp_f32_e32 v239, v239
	v_mfma_f32_16x16x32_bf16 v[94:97], v[164:167], v[140:143], v[94:97]
	ds_read_b128 v[196:199], v235 offset:6144
	v_add_f32_e32 v1, 1.0, v1
	v_mfma_f32_16x16x32_bf16 v[98:101], v[152:155], v[144:147], v[98:101]
	v_mfma_f32_16x16x32_bf16 v[102:105], v[156:159], v[144:147], v[102:105]
	v_add_f32_e32 v130, 1.0, v130
	v_mfma_f32_16x16x32_bf16 v[106:109], v[160:163], v[144:147], v[106:109]
	v_add_f32_e32 v238, 1.0, v238
	v_mfma_f32_16x16x32_bf16 v[110:113], v[164:167], v[144:147], v[110:113]
	v_add_f32_e32 v239, 1.0, v239
	v_mfma_f32_16x16x32_bf16 v[114:117], v[152:155], v[148:151], v[114:117]
	v_rcp_f32_e32 v1, v1
	v_mfma_f32_16x16x32_bf16 v[118:121], v[156:159], v[148:151], v[118:121]
	v_rcp_f32_e32 v130, v130
	v_mfma_f32_16x16x32_bf16 v[122:125], v[160:163], v[148:151], v[122:125]
	v_rcp_f32_e32 v238, v238
	v_mfma_f32_16x16x32_bf16 v[126:129], v[164:167], v[148:151], v[126:129]
	v_rcp_f32_e32 v239, v239
	s_waitcnt vmcnt(7) lgkmcnt(0)
	s_barrier
	v_mfma_f32_16x16x32_bf16 v[66:69], v[184:187], v[168:171], v[66:69]
	ds_read_b128 v[136:139], v218 offset:0
	v_mfma_f32_16x16x32_bf16 v[70:73], v[188:191], v[168:171], v[70:73]
	ds_read_b128 v[140:143], v218 offset:2048
	v_mul_f32_e32 v18, v18, v1
	v_mfma_f32_16x16x32_bf16 v[74:77], v[192:195], v[168:171], v[74:77]
	ds_read_b128 v[144:147], v218 offset:4096
	v_mfma_f32_16x16x32_bf16 v[78:81], v[196:199], v[168:171], v[78:81]
	ds_read_b128 v[148:151], v218 offset:6144
	v_mul_f32_e32 v19, v19, v130
	v_mfma_f32_16x16x32_bf16 v[82:85], v[184:187], v[172:175], v[82:85]
	ds_read_b128 v[152:155], v230 offset:0
	v_mul_f32_e32 v20, v20, v238
	v_mfma_f32_16x16x32_bf16 v[86:89], v[188:191], v[172:175], v[86:89]
	ds_read_b128 v[156:159], v230 offset:2048
	v_mfma_f32_16x16x32_bf16 v[90:93], v[192:195], v[172:175], v[90:93]
	ds_read_b128 v[160:163], v230 offset:4096
	v_mul_f32_e32 v21, v21, v239
	v_mfma_f32_16x16x32_bf16 v[94:97], v[196:199], v[172:175], v[94:97]
	ds_read_b128 v[164:167], v230 offset:6144
	v_cvt_pk_bf16_f32 v18, v18, v19
	s_add_u32 m0, s8, 0x18000
	v_mfma_f32_16x16x32_bf16 v[98:101], v[184:187], v[176:179], v[98:101]
	global_load_lds_dwordx4 v200, s[4:5]
	s_add_u32 m0, s8, 0x18400
	v_mfma_f32_16x16x32_bf16 v[102:105], v[188:191], v[176:179], v[102:105]
	global_load_lds_dwordx4 v201, s[4:5]
	v_cvt_pk_bf16_f32 v19, v20, v21
	s_add_u32 m0, s8, 0x18800
	v_mfma_f32_16x16x32_bf16 v[106:109], v[192:195], v[176:179], v[106:109]
	global_load_lds_dwordx4 v202, s[4:5]
	s_add_u32 m0, s8, 0x18c00
	v_mfma_f32_16x16x32_bf16 v[110:113], v[196:199], v[176:179], v[110:113]
	global_load_lds_dwordx4 v203, s[4:5]
	global_store_dwordx2 v236, v[18:19], s[10:11] offset:0 sc1
	s_add_u32 m0, s9, 0x18000
	v_mfma_f32_16x16x32_bf16 v[114:117], v[184:187], v[180:183], v[114:117]
	global_load_lds_dwordx4 v204, s[6:7]
	v_mul_f32_e32 v1, s12, v22
	s_add_u32 m0, s9, 0x18400
	v_mfma_f32_16x16x32_bf16 v[118:121], v[188:191], v[180:183], v[118:121]
	global_load_lds_dwordx4 v205, s[6:7]
	v_mfma_f32_16x16x32_bf16 v[122:125], v[192:195], v[180:183], v[122:125]
	s_add_u32 s4, s4, 0x80
	s_addc_u32 s5, s5, 0
	v_mul_f32_e32 v130, s12, v23
	v_mfma_f32_16x16x32_bf16 v[126:129], v[196:199], v[180:183], v[126:129]
	s_add_u32 s6, s6, 0x80
	s_addc_u32 s7, s7, 0
	v_mul_f32_e32 v238, s12, v24
	s_waitcnt lgkmcnt(0)
	v_mfma_f32_16x16x32_bf16 v[66:69], v[152:155], v[136:139], v[66:69]
	ds_read_b128 v[168:171], v225 offset:0
	v_mfma_f32_16x16x32_bf16 v[70:73], v[156:159], v[136:139], v[70:73]
	ds_read_b128 v[172:175], v225 offset:2048
	v_mul_f32_e32 v239, s12, v25
	v_mfma_f32_16x16x32_bf16 v[74:77], v[160:163], v[136:139], v[74:77]
	ds_read_b128 v[176:179], v225 offset:4096
	v_exp_f32_e32 v1, v1
	v_mfma_f32_16x16x32_bf16 v[78:81], v[164:167], v[136:139], v[78:81]
	ds_read_b128 v[180:183], v225 offset:6144
	v_exp_f32_e32 v130, v130
	v_mfma_f32_16x16x32_bf16 v[82:85], v[152:155], v[140:143], v[82:85]
	ds_read_b128 v[184:187], v233 offset:0
	v_exp_f32_e32 v238, v238
	v_mfma_f32_16x16x32_bf16 v[86:89], v[156:159], v[140:143], v[86:89]
	ds_read_b128 v[188:191], v233 offset:2048
	v_exp_f32_e32 v239, v239
	v_mfma_f32_16x16x32_bf16 v[90:93], v[160:163], v[140:143], v[90:93]
	ds_read_b128 v[192:195], v233 offset:4096
	v_add_f32_e32 v1, 1.0, v1
	v_mfma_f32_16x16x32_bf16 v[94:97], v[164:167], v[140:143], v[94:97]
	ds_read_b128 v[196:199], v233 offset:6144
	v_add_f32_e32 v130, 1.0, v130
	v_mfma_f32_16x16x32_bf16 v[98:101], v[152:155], v[144:147], v[98:101]
	v_mfma_f32_16x16x32_bf16 v[102:105], v[156:159], v[144:147], v[102:105]
	v_add_f32_e32 v238, 1.0, v238
	v_mfma_f32_16x16x32_bf16 v[106:109], v[160:163], v[144:147], v[106:109]
	v_add_f32_e32 v239, 1.0, v239
	v_mfma_f32_16x16x32_bf16 v[110:113], v[164:167], v[144:147], v[110:113]
	v_rcp_f32_e32 v1, v1
	v_mfma_f32_16x16x32_bf16 v[114:117], v[152:155], v[148:151], v[114:117]
	v_rcp_f32_e32 v130, v130
	v_mfma_f32_16x16x32_bf16 v[118:121], v[156:159], v[148:151], v[118:121]
	v_rcp_f32_e32 v238, v238
	v_mfma_f32_16x16x32_bf16 v[122:125], v[160:163], v[148:151], v[122:125]
	v_rcp_f32_e32 v239, v239
	v_mfma_f32_16x16x32_bf16 v[126:129], v[164:167], v[148:151], v[126:129]
	v_mul_f32_e32 v22, v22, v1
	s_waitcnt vmcnt(7) lgkmcnt(0)
	s_barrier
	v_mfma_f32_16x16x32_bf16 v[66:69], v[184:187], v[168:171], v[66:69]
	ds_read_b128 v[136:139], v219 offset:0
	v_mfma_f32_16x16x32_bf16 v[70:73], v[188:191], v[168:171], v[70:73]
	ds_read_b128 v[140:143], v219 offset:2048
	v_mul_f32_e32 v23, v23, v130
	v_mfma_f32_16x16x32_bf16 v[74:77], v[192:195], v[168:171], v[74:77]
	ds_read_b128 v[144:147], v219 offset:4096
	v_mfma_f32_16x16x32_bf16 v[78:81], v[196:199], v[168:171], v[78:81]
	ds_read_b128 v[148:151], v219 offset:6144
	v_mul_f32_e32 v24, v24, v238
	v_mfma_f32_16x16x32_bf16 v[82:85], v[184:187], v[172:175], v[82:85]
	ds_read_b128 v[152:155], v231 offset:0
	v_mul_f32_e32 v25, v25, v239
	v_mfma_f32_16x16x32_bf16 v[86:89], v[188:191], v[172:175], v[86:89]
	ds_read_b128 v[156:159], v231 offset:2048
	v_mfma_f32_16x16x32_bf16 v[90:93], v[192:195], v[172:175], v[90:93]
	ds_read_b128 v[160:163], v231 offset:4096
	v_cvt_pk_bf16_f32 v22, v22, v23
	v_mfma_f32_16x16x32_bf16 v[94:97], v[196:199], v[172:175], v[94:97]
	ds_read_b128 v[164:167], v231 offset:6144
	v_cvt_pk_bf16_f32 v23, v24, v25
	s_mov_b32 m0, s8
	v_mfma_f32_16x16x32_bf16 v[98:101], v[184:187], v[176:179], v[98:101]
	global_load_lds_dwordx4 v200, s[4:5]
	s_add_u32 m0, s8, 0x400
	v_mfma_f32_16x16x32_bf16 v[102:105], v[188:191], v[176:179], v[102:105]
	global_load_lds_dwordx4 v201, s[4:5]
	global_store_dwordx2 v236, v[22:23], s[10:11] offset:32 sc1
	s_add_u32 m0, s8, 0x800
	v_mfma_f32_16x16x32_bf16 v[106:109], v[192:195], v[176:179], v[106:109]
	global_load_lds_dwordx4 v202, s[4:5]
	s_add_u32 m0, s8, 0xc00
	v_mfma_f32_16x16x32_bf16 v[110:113], v[196:199], v[176:179], v[110:113]
	global_load_lds_dwordx4 v203, s[4:5]
	v_mul_f32_e32 v1, s12, v26
	s_mov_b32 m0, s9
	v_mfma_f32_16x16x32_bf16 v[114:117], v[184:187], v[180:183], v[114:117]
	global_load_lds_dwordx4 v204, s[6:7]
	v_mul_f32_e32 v130, s12, v27
	s_add_u32 m0, s9, 0x400
	v_mfma_f32_16x16x32_bf16 v[118:121], v[188:191], v[180:183], v[118:121]
	global_load_lds_dwordx4 v205, s[6:7]
	v_mfma_f32_16x16x32_bf16 v[122:125], v[192:195], v[180:183], v[122:125]
	s_add_u32 s4, s4, 0x80
	s_addc_u32 s5, s5, 0
	v_mul_f32_e32 v238, s12, v28
	v_mfma_f32_16x16x32_bf16 v[126:129], v[196:199], v[180:183], v[126:129]
	s_add_u32 s6, s6, 0x80
	s_addc_u32 s7, s7, 0
	v_mul_f32_e32 v239, s12, v29
	s_waitcnt lgkmcnt(0)
	v_mfma_f32_16x16x32_bf16 v[66:69], v[152:155], v[136:139], v[66:69]
	ds_read_b128 v[168:171], v228 offset:0
	v_mfma_f32_16x16x32_bf16 v[70:73], v[156:159], v[136:139], v[70:73]
	ds_read_b128 v[172:175], v228 offset:2048
	v_exp_f32_e32 v1, v1
	v_mfma_f32_16x16x32_bf16 v[74:77], v[160:163], v[136:139], v[74:77]
	ds_read_b128 v[176:179], v228 offset:4096
	v_exp_f32_e32 v130, v130
	v_mfma_f32_16x16x32_bf16 v[78:81], v[164:167], v[136:139], v[78:81]
	ds_read_b128 v[180:183], v228 offset:6144
	v_exp_f32_e32 v238, v238
	v_mfma_f32_16x16x32_bf16 v[82:85], v[152:155], v[140:143], v[82:85]
	ds_read_b128 v[184:187], v234 offset:0
	v_exp_f32_e32 v239, v239
	v_mfma_f32_16x16x32_bf16 v[86:89], v[156:159], v[140:143], v[86:89]
	ds_read_b128 v[188:191], v234 offset:2048
	v_add_f32_e32 v1, 1.0, v1
	v_mfma_f32_16x16x32_bf16 v[90:93], v[160:163], v[140:143], v[90:93]
	ds_read_b128 v[192:195], v234 offset:4096
	v_add_f32_e32 v130, 1.0, v130
	v_mfma_f32_16x16x32_bf16 v[94:97], v[164:167], v[140:143], v[94:97]
	ds_read_b128 v[196:199], v234 offset:6144
	v_add_f32_e32 v238, 1.0, v238
	v_mfma_f32_16x16x32_bf16 v[98:101], v[152:155], v[144:147], v[98:101]
	v_mfma_f32_16x16x32_bf16 v[102:105], v[156:159], v[144:147], v[102:105]
	v_add_f32_e32 v239, 1.0, v239
	v_mfma_f32_16x16x32_bf16 v[106:109], v[160:163], v[144:147], v[106:109]
	v_rcp_f32_e32 v1, v1
	v_mfma_f32_16x16x32_bf16 v[110:113], v[164:167], v[144:147], v[110:113]
	v_rcp_f32_e32 v130, v130
	v_mfma_f32_16x16x32_bf16 v[114:117], v[152:155], v[148:151], v[114:117]
	v_rcp_f32_e32 v238, v238
	v_mfma_f32_16x16x32_bf16 v[118:121], v[156:159], v[148:151], v[118:121]
	v_rcp_f32_e32 v239, v239
	v_mfma_f32_16x16x32_bf16 v[122:125], v[160:163], v[148:151], v[122:125]
	v_mul_f32_e32 v26, v26, v1
	v_mfma_f32_16x16x32_bf16 v[126:129], v[164:167], v[148:151], v[126:129]
	v_mul_f32_e32 v27, v27, v130
	s_waitcnt vmcnt(7) lgkmcnt(0)
	s_barrier
	v_mfma_f32_16x16x32_bf16 v[66:69], v[184:187], v[168:171], v[66:69]
	ds_read_b128 v[136:139], v224 offset:0
	v_mfma_f32_16x16x32_bf16 v[70:73], v[188:191], v[168:171], v[70:73]
	ds_read_b128 v[140:143], v224 offset:2048
	v_mul_f32_e32 v28, v28, v238
	v_mfma_f32_16x16x32_bf16 v[74:77], v[192:195], v[168:171], v[74:77]
	ds_read_b128 v[144:147], v224 offset:4096
	v_mfma_f32_16x16x32_bf16 v[78:81], v[196:199], v[168:171], v[78:81]
	ds_read_b128 v[148:151], v224 offset:6144
	v_mul_f32_e32 v29, v29, v239
	v_mfma_f32_16x16x32_bf16 v[82:85], v[184:187], v[172:175], v[82:85]
	ds_read_b128 v[152:155], v232 offset:0
	v_cvt_pk_bf16_f32 v26, v26, v27
	v_mfma_f32_16x16x32_bf16 v[86:89], v[188:191], v[172:175], v[86:89]
	ds_read_b128 v[156:159], v232 offset:2048
	v_mfma_f32_16x16x32_bf16 v[90:93], v[192:195], v[172:175], v[90:93]
	ds_read_b128 v[160:163], v232 offset:4096
	v_cvt_pk_bf16_f32 v27, v28, v29
	v_mfma_f32_16x16x32_bf16 v[94:97], v[196:199], v[172:175], v[94:97]
	ds_read_b128 v[164:167], v232 offset:6144
	global_store_dwordx2 v236, v[26:27], s[10:11] offset:64 sc1
	s_add_u32 m0, s8, 0xc000
	v_mfma_f32_16x16x32_bf16 v[98:101], v[184:187], v[176:179], v[98:101]
	global_load_lds_dwordx4 v200, s[4:5]
	s_add_u32 m0, s8, 0xc400
	v_mfma_f32_16x16x32_bf16 v[102:105], v[188:191], v[176:179], v[102:105]
	global_load_lds_dwordx4 v201, s[4:5]
	v_mul_f32_e32 v1, s12, v30
	s_add_u32 m0, s8, 0xc800
	v_mfma_f32_16x16x32_bf16 v[106:109], v[192:195], v[176:179], v[106:109]
	global_load_lds_dwordx4 v202, s[4:5]
	s_add_u32 m0, s8, 0xcc00
	v_mfma_f32_16x16x32_bf16 v[110:113], v[196:199], v[176:179], v[110:113]
	global_load_lds_dwordx4 v203, s[4:5]
	v_mul_f32_e32 v130, s12, v31
	s_add_u32 m0, s9, 0xc000
	v_mfma_f32_16x16x32_bf16 v[114:117], v[184:187], v[180:183], v[114:117]
	global_load_lds_dwordx4 v204, s[6:7]
	v_mul_f32_e32 v238, s12, v32
	s_add_u32 m0, s9, 0xc400
	v_mfma_f32_16x16x32_bf16 v[118:121], v[188:191], v[180:183], v[118:121]
	global_load_lds_dwordx4 v205, s[6:7]
	v_mfma_f32_16x16x32_bf16 v[122:125], v[192:195], v[180:183], v[122:125]
	s_add_u32 s4, s4, 0x80
	s_addc_u32 s5, s5, 0
	v_mul_f32_e32 v239, s12, v33
	v_mfma_f32_16x16x32_bf16 v[126:129], v[196:199], v[180:183], v[126:129]
	s_add_u32 s6, s6, 0x80
	s_addc_u32 s7, s7, 0
	v_exp_f32_e32 v1, v1
	s_waitcnt lgkmcnt(0)
	v_mfma_f32_16x16x32_bf16 v[66:69], v[152:155], v[136:139], v[66:69]
	ds_read_b128 v[168:171], v229 offset:0
	v_mfma_f32_16x16x32_bf16 v[70:73], v[156:159], v[136:139], v[70:73]
	ds_read_b128 v[172:175], v229 offset:2048
	v_exp_f32_e32 v130, v130
	v_mfma_f32_16x16x32_bf16 v[74:77], v[160:163], v[136:139], v[74:77]
	ds_read_b128 v[176:179], v229 offset:4096
	v_exp_f32_e32 v238, v238
	v_mfma_f32_16x16x32_bf16 v[78:81], v[164:167], v[136:139], v[78:81]
	ds_read_b128 v[180:183], v229 offset:6144
	v_exp_f32_e32 v239, v239
	v_mfma_f32_16x16x32_bf16 v[82:85], v[152:155], v[140:143], v[82:85]
	ds_read_b128 v[184:187], v235 offset:0
	v_add_f32_e32 v1, 1.0, v1
	v_mfma_f32_16x16x32_bf16 v[86:89], v[156:159], v[140:143], v[86:89]
	ds_read_b128 v[188:191], v235 offset:2048
	v_add_f32_e32 v130, 1.0, v130
	v_mfma_f32_16x16x32_bf16 v[90:93], v[160:163], v[140:143], v[90:93]
	ds_read_b128 v[192:195], v235 offset:4096
	v_add_f32_e32 v238, 1.0, v238
	v_mfma_f32_16x16x32_bf16 v[94:97], v[164:167], v[140:143], v[94:97]
	ds_read_b128 v[196:199], v235 offset:6144
	v_add_f32_e32 v239, 1.0, v239
	v_mfma_f32_16x16x32_bf16 v[98:101], v[152:155], v[144:147], v[98:101]
	v_mfma_f32_16x16x32_bf16 v[102:105], v[156:159], v[144:147], v[102:105]
	v_rcp_f32_e32 v1, v1
	v_mfma_f32_16x16x32_bf16 v[106:109], v[160:163], v[144:147], v[106:109]
	v_rcp_f32_e32 v130, v130
	v_mfma_f32_16x16x32_bf16 v[110:113], v[164:167], v[144:147], v[110:113]
	v_rcp_f32_e32 v238, v238
	v_mfma_f32_16x16x32_bf16 v[114:117], v[152:155], v[148:151], v[114:117]
	v_rcp_f32_e32 v239, v239
	v_mfma_f32_16x16x32_bf16 v[118:121], v[156:159], v[148:151], v[118:121]
	v_mul_f32_e32 v30, v30, v1
	v_mfma_f32_16x16x32_bf16 v[122:125], v[160:163], v[148:151], v[122:125]
	v_mul_f32_e32 v31, v31, v130
	v_mfma_f32_16x16x32_bf16 v[126:129], v[164:167], v[148:151], v[126:129]
	v_mul_f32_e32 v32, v32, v238
	s_waitcnt vmcnt(7) lgkmcnt(0)
	s_barrier
	v_mfma_f32_16x16x32_bf16 v[66:69], v[184:187], v[168:171], v[66:69]
	ds_read_b128 v[136:139], v218 offset:0
	v_mfma_f32_16x16x32_bf16 v[70:73], v[188:191], v[168:171], v[70:73]
	ds_read_b128 v[140:143], v218 offset:2048
	v_mul_f32_e32 v33, v33, v239
	v_mfma_f32_16x16x32_bf16 v[74:77], v[192:195], v[168:171], v[74:77]
	ds_read_b128 v[144:147], v218 offset:4096
	v_mfma_f32_16x16x32_bf16 v[78:81], v[196:199], v[168:171], v[78:81]
	ds_read_b128 v[148:151], v218 offset:6144
	v_cvt_pk_bf16_f32 v30, v30, v31
	v_mfma_f32_16x16x32_bf16 v[82:85], v[184:187], v[172:175], v[82:85]
	ds_read_b128 v[152:155], v230 offset:0
	v_cvt_pk_bf16_f32 v31, v32, v33
	v_mfma_f32_16x16x32_bf16 v[86:89], v[188:191], v[172:175], v[86:89]
	ds_read_b128 v[156:159], v230 offset:2048
	v_mfma_f32_16x16x32_bf16 v[90:93], v[192:195], v[172:175], v[90:93]
	ds_read_b128 v[160:163], v230 offset:4096
	global_store_dwordx2 v236, v[30:31], s[10:11] offset:96 sc1
	v_mfma_f32_16x16x32_bf16 v[94:97], v[196:199], v[172:175], v[94:97]
	ds_read_b128 v[164:167], v230 offset:6144
	s_add_u32 s10, s10, 0x8000
	s_addc_u32 s11, s11, 0
	s_add_u32 m0, s8, 0x18000
	v_mfma_f32_16x16x32_bf16 v[98:101], v[184:187], v[176:179], v[98:101]
	global_load_lds_dwordx4 v200, s[4:5]
	s_add_u32 m0, s8, 0x18400
	v_mfma_f32_16x16x32_bf16 v[102:105], v[188:191], v[176:179], v[102:105]
	global_load_lds_dwordx4 v201, s[4:5]
	v_mul_f32_e32 v1, s12, v34
	s_add_u32 m0, s8, 0x18800
	v_mfma_f32_16x16x32_bf16 v[106:109], v[192:195], v[176:179], v[106:109]
	global_load_lds_dwordx4 v202, s[4:5]
	s_add_u32 m0, s8, 0x18c00
	v_mfma_f32_16x16x32_bf16 v[110:113], v[196:199], v[176:179], v[110:113]
	global_load_lds_dwordx4 v203, s[4:5]
	v_mul_f32_e32 v130, s12, v35
	s_add_u32 m0, s9, 0x18000
	v_mfma_f32_16x16x32_bf16 v[114:117], v[184:187], v[180:183], v[114:117]
	global_load_lds_dwordx4 v204, s[6:7]
	v_mul_f32_e32 v238, s12, v36
	s_add_u32 m0, s9, 0x18400
	v_mfma_f32_16x16x32_bf16 v[118:121], v[188:191], v[180:183], v[118:121]
	global_load_lds_dwordx4 v205, s[6:7]
	v_mfma_f32_16x16x32_bf16 v[122:125], v[192:195], v[180:183], v[122:125]
	s_add_u32 s4, s4, 0x80
	s_addc_u32 s5, s5, 0
	v_mul_f32_e32 v239, s12, v37
	v_mfma_f32_16x16x32_bf16 v[126:129], v[196:199], v[180:183], v[126:129]
	s_add_u32 s6, s6, 0x80
	s_addc_u32 s7, s7, 0
	v_exp_f32_e32 v1, v1
	s_waitcnt lgkmcnt(0)
	v_mfma_f32_16x16x32_bf16 v[66:69], v[152:155], v[136:139], v[66:69]
	ds_read_b128 v[168:171], v225 offset:0
	v_mfma_f32_16x16x32_bf16 v[70:73], v[156:159], v[136:139], v[70:73]
	ds_read_b128 v[172:175], v225 offset:2048
	v_exp_f32_e32 v130, v130
	v_mfma_f32_16x16x32_bf16 v[74:77], v[160:163], v[136:139], v[74:77]
	ds_read_b128 v[176:179], v225 offset:4096
	v_exp_f32_e32 v238, v238
	v_mfma_f32_16x16x32_bf16 v[78:81], v[164:167], v[136:139], v[78:81]
	ds_read_b128 v[180:183], v225 offset:6144
	v_exp_f32_e32 v239, v239
	v_mfma_f32_16x16x32_bf16 v[82:85], v[152:155], v[140:143], v[82:85]
	ds_read_b128 v[184:187], v233 offset:0
	v_add_f32_e32 v1, 1.0, v1
	v_mfma_f32_16x16x32_bf16 v[86:89], v[156:159], v[140:143], v[86:89]
	ds_read_b128 v[188:191], v233 offset:2048
	v_add_f32_e32 v130, 1.0, v130
	v_mfma_f32_16x16x32_bf16 v[90:93], v[160:163], v[140:143], v[90:93]
	ds_read_b128 v[192:195], v233 offset:4096
	v_add_f32_e32 v238, 1.0, v238
	v_mfma_f32_16x16x32_bf16 v[94:97], v[164:167], v[140:143], v[94:97]
	ds_read_b128 v[196:199], v233 offset:6144
	v_add_f32_e32 v239, 1.0, v239
	v_mfma_f32_16x16x32_bf16 v[98:101], v[152:155], v[144:147], v[98:101]
	v_mfma_f32_16x16x32_bf16 v[102:105], v[156:159], v[144:147], v[102:105]
	v_rcp_f32_e32 v1, v1
	v_mfma_f32_16x16x32_bf16 v[106:109], v[160:163], v[144:147], v[106:109]
	v_rcp_f32_e32 v130, v130
	v_mfma_f32_16x16x32_bf16 v[110:113], v[164:167], v[144:147], v[110:113]
	v_rcp_f32_e32 v238, v238
	v_mfma_f32_16x16x32_bf16 v[114:117], v[152:155], v[148:151], v[114:117]
	v_rcp_f32_e32 v239, v239
	v_mfma_f32_16x16x32_bf16 v[118:121], v[156:159], v[148:151], v[118:121]
	v_mul_f32_e32 v34, v34, v1
	v_mfma_f32_16x16x32_bf16 v[122:125], v[160:163], v[148:151], v[122:125]
	v_mul_f32_e32 v35, v35, v130
	v_mfma_f32_16x16x32_bf16 v[126:129], v[164:167], v[148:151], v[126:129]
	v_mul_f32_e32 v36, v36, v238
	s_waitcnt vmcnt(7) lgkmcnt(0)
	s_barrier
	v_mfma_f32_16x16x32_bf16 v[66:69], v[184:187], v[168:171], v[66:69]
	ds_read_b128 v[136:139], v219 offset:0
	v_mfma_f32_16x16x32_bf16 v[70:73], v[188:191], v[168:171], v[70:73]
	ds_read_b128 v[140:143], v219 offset:2048
	v_mul_f32_e32 v37, v37, v239
	v_mfma_f32_16x16x32_bf16 v[74:77], v[192:195], v[168:171], v[74:77]
	ds_read_b128 v[144:147], v219 offset:4096
	v_mfma_f32_16x16x32_bf16 v[78:81], v[196:199], v[168:171], v[78:81]
	ds_read_b128 v[148:151], v219 offset:6144
	v_cvt_pk_bf16_f32 v34, v34, v35
	v_mfma_f32_16x16x32_bf16 v[82:85], v[184:187], v[172:175], v[82:85]
	ds_read_b128 v[152:155], v231 offset:0
	v_cvt_pk_bf16_f32 v35, v36, v37
	v_mfma_f32_16x16x32_bf16 v[86:89], v[188:191], v[172:175], v[86:89]
	ds_read_b128 v[156:159], v231 offset:2048
	v_mfma_f32_16x16x32_bf16 v[90:93], v[192:195], v[172:175], v[90:93]
	ds_read_b128 v[160:163], v231 offset:4096
	global_store_dwordx2 v236, v[34:35], s[10:11] offset:0 sc1
	v_mfma_f32_16x16x32_bf16 v[94:97], v[196:199], v[172:175], v[94:97]
	ds_read_b128 v[164:167], v231 offset:6144
	v_mul_f32_e32 v1, s12, v38
	s_mov_b32 m0, s8
	v_mfma_f32_16x16x32_bf16 v[98:101], v[184:187], v[176:179], v[98:101]
	global_load_lds_dwordx4 v200, s[4:5]
	s_add_u32 m0, s8, 0x400
	v_mfma_f32_16x16x32_bf16 v[102:105], v[188:191], v[176:179], v[102:105]
	global_load_lds_dwordx4 v201, s[4:5]
	v_mul_f32_e32 v130, s12, v39
	s_add_u32 m0, s8, 0x800
	v_mfma_f32_16x16x32_bf16 v[106:109], v[192:195], v[176:179], v[106:109]
	global_load_lds_dwordx4 v202, s[4:5]
	s_add_u32 m0, s8, 0xc00
	v_mfma_f32_16x16x32_bf16 v[110:113], v[196:199], v[176:179], v[110:113]
	global_load_lds_dwordx4 v203, s[4:5]
	v_mul_f32_e32 v238, s12, v40
	s_mov_b32 m0, s9
	v_mfma_f32_16x16x32_bf16 v[114:117], v[184:187], v[180:183], v[114:117]
	global_load_lds_dwordx4 v204, s[6:7]
	v_mul_f32_e32 v239, s12, v41
	s_add_u32 m0, s9, 0x400
	v_mfma_f32_16x16x32_bf16 v[118:121], v[188:191], v[180:183], v[118:121]
	global_load_lds_dwordx4 v205, s[6:7]
	v_mfma_f32_16x16x32_bf16 v[122:125], v[192:195], v[180:183], v[122:125]
	s_add_u32 s4, s4, 0x80
	s_addc_u32 s5, s5, 0
	v_exp_f32_e32 v1, v1
	v_mfma_f32_16x16x32_bf16 v[126:129], v[196:199], v[180:183], v[126:129]
	s_add_u32 s6, s6, 0x80
	s_addc_u32 s7, s7, 0
	v_exp_f32_e32 v130, v130
	s_waitcnt lgkmcnt(0)
	v_mfma_f32_16x16x32_bf16 v[66:69], v[152:155], v[136:139], v[66:69]
	ds_read_b128 v[168:171], v228 offset:0
	v_mfma_f32_16x16x32_bf16 v[70:73], v[156:159], v[136:139], v[70:73]
	ds_read_b128 v[172:175], v228 offset:2048
	v_exp_f32_e32 v238, v238
	v_mfma_f32_16x16x32_bf16 v[74:77], v[160:163], v[136:139], v[74:77]
	ds_read_b128 v[176:179], v228 offset:4096
	v_exp_f32_e32 v239, v239
	v_mfma_f32_16x16x32_bf16 v[78:81], v[164:167], v[136:139], v[78:81]
	ds_read_b128 v[180:183], v228 offset:6144
	v_add_f32_e32 v1, 1.0, v1
	v_mfma_f32_16x16x32_bf16 v[82:85], v[152:155], v[140:143], v[82:85]
	ds_read_b128 v[184:187], v234 offset:0
	v_add_f32_e32 v130, 1.0, v130
	v_mfma_f32_16x16x32_bf16 v[86:89], v[156:159], v[140:143], v[86:89]
	ds_read_b128 v[188:191], v234 offset:2048
	v_add_f32_e32 v238, 1.0, v238
	v_mfma_f32_16x16x32_bf16 v[90:93], v[160:163], v[140:143], v[90:93]
	ds_read_b128 v[192:195], v234 offset:4096
	v_add_f32_e32 v239, 1.0, v239
	v_mfma_f32_16x16x32_bf16 v[94:97], v[164:167], v[140:143], v[94:97]
	ds_read_b128 v[196:199], v234 offset:6144
	v_rcp_f32_e32 v1, v1
	v_mfma_f32_16x16x32_bf16 v[98:101], v[152:155], v[144:147], v[98:101]
	v_mfma_f32_16x16x32_bf16 v[102:105], v[156:159], v[144:147], v[102:105]
	v_rcp_f32_e32 v130, v130
	v_mfma_f32_16x16x32_bf16 v[106:109], v[160:163], v[144:147], v[106:109]
	v_rcp_f32_e32 v238, v238
	v_mfma_f32_16x16x32_bf16 v[110:113], v[164:167], v[144:147], v[110:113]
	v_rcp_f32_e32 v239, v239
	v_mfma_f32_16x16x32_bf16 v[114:117], v[152:155], v[148:151], v[114:117]
	v_mul_f32_e32 v38, v38, v1
	v_mfma_f32_16x16x32_bf16 v[118:121], v[156:159], v[148:151], v[118:121]
	v_mul_f32_e32 v39, v39, v130
	v_mfma_f32_16x16x32_bf16 v[122:125], v[160:163], v[148:151], v[122:125]
	v_mul_f32_e32 v40, v40, v238
	v_mfma_f32_16x16x32_bf16 v[126:129], v[164:167], v[148:151], v[126:129]
	v_mul_f32_e32 v41, v41, v239
	s_waitcnt vmcnt(7) lgkmcnt(0)
	s_barrier
	v_mfma_f32_16x16x32_bf16 v[66:69], v[184:187], v[168:171], v[66:69]
	ds_read_b128 v[136:139], v224 offset:0
	v_mfma_f32_16x16x32_bf16 v[70:73], v[188:191], v[168:171], v[70:73]
	ds_read_b128 v[140:143], v224 offset:2048
	v_cvt_pk_bf16_f32 v38, v38, v39
	v_mfma_f32_16x16x32_bf16 v[74:77], v[192:195], v[168:171], v[74:77]
	ds_read_b128 v[144:147], v224 offset:4096
	v_mfma_f32_16x16x32_bf16 v[78:81], v[196:199], v[168:171], v[78:81]
	ds_read_b128 v[148:151], v224 offset:6144
	v_cvt_pk_bf16_f32 v39, v40, v41
	v_mfma_f32_16x16x32_bf16 v[82:85], v[184:187], v[172:175], v[82:85]
	ds_read_b128 v[152:155], v232 offset:0
	global_store_dwordx2 v236, v[38:39], s[10:11] offset:32 sc1
	v_mfma_f32_16x16x32_bf16 v[86:89], v[188:191], v[172:175], v[86:89]
	ds_read_b128 v[156:159], v232 offset:2048
	v_mfma_f32_16x16x32_bf16 v[90:93], v[192:195], v[172:175], v[90:93]
	ds_read_b128 v[160:163], v232 offset:4096
	v_mul_f32_e32 v1, s12, v42
	v_mfma_f32_16x16x32_bf16 v[94:97], v[196:199], v[172:175], v[94:97]
	ds_read_b128 v[164:167], v232 offset:6144
	v_mul_f32_e32 v130, s12, v43
	s_add_u32 m0, s8, 0xc000
	v_mfma_f32_16x16x32_bf16 v[98:101], v[184:187], v[176:179], v[98:101]
	global_load_lds_dwordx4 v200, s[4:5]
	s_add_u32 m0, s8, 0xc400
	v_mfma_f32_16x16x32_bf16 v[102:105], v[188:191], v[176:179], v[102:105]
	global_load_lds_dwordx4 v201, s[4:5]
	v_mul_f32_e32 v238, s12, v44
	s_add_u32 m0, s8, 0xc800
	v_mfma_f32_16x16x32_bf16 v[106:109], v[192:195], v[176:179], v[106:109]
	global_load_lds_dwordx4 v202, s[4:5]
	s_add_u32 m0, s8, 0xcc00
	v_mfma_f32_16x16x32_bf16 v[110:113], v[196:199], v[176:179], v[110:113]
	global_load_lds_dwordx4 v203, s[4:5]
	v_mul_f32_e32 v239, s12, v45
	s_add_u32 m0, s9, 0xc000
	v_mfma_f32_16x16x32_bf16 v[114:117], v[184:187], v[180:183], v[114:117]
	global_load_lds_dwordx4 v204, s[6:7]
	v_exp_f32_e32 v1, v1
	s_add_u32 m0, s9, 0xc400
	v_mfma_f32_16x16x32_bf16 v[118:121], v[188:191], v[180:183], v[118:121]
	global_load_lds_dwordx4 v205, s[6:7]
	v_mfma_f32_16x16x32_bf16 v[122:125], v[192:195], v[180:183], v[122:125]
	s_add_u32 s4, s4, 0x80
	s_addc_u32 s5, s5, 0
	v_exp_f32_e32 v130, v130
	v_mfma_f32_16x16x32_bf16 v[126:129], v[196:199], v[180:183], v[126:129]
	s_add_u32 s6, s6, 0x80
	s_addc_u32 s7, s7, 0
	v_exp_f32_e32 v238, v238
	s_waitcnt lgkmcnt(0)
	v_mfma_f32_16x16x32_bf16 v[66:69], v[152:155], v[136:139], v[66:69]
	ds_read_b128 v[168:171], v229 offset:0
	v_mfma_f32_16x16x32_bf16 v[70:73], v[156:159], v[136:139], v[70:73]
	ds_read_b128 v[172:175], v229 offset:2048
	v_exp_f32_e32 v239, v239
	v_mfma_f32_16x16x32_bf16 v[74:77], v[160:163], v[136:139], v[74:77]
	ds_read_b128 v[176:179], v229 offset:4096
	v_add_f32_e32 v1, 1.0, v1
	v_mfma_f32_16x16x32_bf16 v[78:81], v[164:167], v[136:139], v[78:81]
	ds_read_b128 v[180:183], v229 offset:6144
	v_add_f32_e32 v130, 1.0, v130
	v_mfma_f32_16x16x32_bf16 v[82:85], v[152:155], v[140:143], v[82:85]
	ds_read_b128 v[184:187], v235 offset:0
	v_add_f32_e32 v238, 1.0, v238
	v_mfma_f32_16x16x32_bf16 v[86:89], v[156:159], v[140:143], v[86:89]
	ds_read_b128 v[188:191], v235 offset:2048
	v_add_f32_e32 v239, 1.0, v239
	v_mfma_f32_16x16x32_bf16 v[90:93], v[160:163], v[140:143], v[90:93]
	ds_read_b128 v[192:195], v235 offset:4096
	v_rcp_f32_e32 v1, v1
	v_mfma_f32_16x16x32_bf16 v[94:97], v[164:167], v[140:143], v[94:97]
	ds_read_b128 v[196:199], v235 offset:6144
	v_rcp_f32_e32 v130, v130
	v_mfma_f32_16x16x32_bf16 v[98:101], v[152:155], v[144:147], v[98:101]
	v_mfma_f32_16x16x32_bf16 v[102:105], v[156:159], v[144:147], v[102:105]
	v_rcp_f32_e32 v238, v238
	v_mfma_f32_16x16x32_bf16 v[106:109], v[160:163], v[144:147], v[106:109]
	v_rcp_f32_e32 v239, v239
	v_mfma_f32_16x16x32_bf16 v[110:113], v[164:167], v[144:147], v[110:113]
	v_mul_f32_e32 v42, v42, v1
	v_mfma_f32_16x16x32_bf16 v[114:117], v[152:155], v[148:151], v[114:117]
	v_mul_f32_e32 v43, v43, v130
	v_mfma_f32_16x16x32_bf16 v[118:121], v[156:159], v[148:151], v[118:121]
	v_mul_f32_e32 v44, v44, v238
	v_mfma_f32_16x16x32_bf16 v[122:125], v[160:163], v[148:151], v[122:125]
	v_mul_f32_e32 v45, v45, v239
	v_mfma_f32_16x16x32_bf16 v[126:129], v[164:167], v[148:151], v[126:129]
	v_cvt_pk_bf16_f32 v42, v42, v43
	s_waitcnt vmcnt(7) lgkmcnt(0)
	s_barrier
	v_mfma_f32_16x16x32_bf16 v[66:69], v[184:187], v[168:171], v[66:69]
	ds_read_b128 v[136:139], v218 offset:0
	v_mfma_f32_16x16x32_bf16 v[70:73], v[188:191], v[168:171], v[70:73]
	ds_read_b128 v[140:143], v218 offset:2048
	v_cvt_pk_bf16_f32 v43, v44, v45
	v_mfma_f32_16x16x32_bf16 v[74:77], v[192:195], v[168:171], v[74:77]
	ds_read_b128 v[144:147], v218 offset:4096
	v_mfma_f32_16x16x32_bf16 v[78:81], v[196:199], v[168:171], v[78:81]
	ds_read_b128 v[148:151], v218 offset:6144
	global_store_dwordx2 v236, v[42:43], s[10:11] offset:64 sc1
	v_mfma_f32_16x16x32_bf16 v[82:85], v[184:187], v[172:175], v[82:85]
	ds_read_b128 v[152:155], v230 offset:0
	v_mul_f32_e32 v1, s12, v46
	v_mfma_f32_16x16x32_bf16 v[86:89], v[188:191], v[172:175], v[86:89]
	ds_read_b128 v[156:159], v230 offset:2048
	v_mfma_f32_16x16x32_bf16 v[90:93], v[192:195], v[172:175], v[90:93]
	ds_read_b128 v[160:163], v230 offset:4096
	v_mul_f32_e32 v130, s12, v47
	v_mfma_f32_16x16x32_bf16 v[94:97], v[196:199], v[172:175], v[94:97]
	ds_read_b128 v[164:167], v230 offset:6144
	v_mul_f32_e32 v238, s12, v48
	s_add_u32 m0, s8, 0x18000
	v_mfma_f32_16x16x32_bf16 v[98:101], v[184:187], v[176:179], v[98:101]
	global_load_lds_dwordx4 v200, s[4:5]
	s_add_u32 m0, s8, 0x18400
	v_mfma_f32_16x16x32_bf16 v[102:105], v[188:191], v[176:179], v[102:105]
	global_load_lds_dwordx4 v201, s[4:5]
	v_mul_f32_e32 v239, s12, v49
	s_add_u32 m0, s8, 0x18800
	v_mfma_f32_16x16x32_bf16 v[106:109], v[192:195], v[176:179], v[106:109]
	global_load_lds_dwordx4 v202, s[4:5]
	s_add_u32 m0, s8, 0x18c00
	v_mfma_f32_16x16x32_bf16 v[110:113], v[196:199], v[176:179], v[110:113]
	global_load_lds_dwordx4 v203, s[4:5]
	v_exp_f32_e32 v1, v1
	s_add_u32 m0, s9, 0x18000
	v_mfma_f32_16x16x32_bf16 v[114:117], v[184:187], v[180:183], v[114:117]
	global_load_lds_dwordx4 v204, s[6:7]
	v_exp_f32_e32 v130, v130
	s_add_u32 m0, s9, 0x18400
	v_mfma_f32_16x16x32_bf16 v[118:121], v[188:191], v[180:183], v[118:121]
	global_load_lds_dwordx4 v205, s[6:7]
	v_mfma_f32_16x16x32_bf16 v[122:125], v[192:195], v[180:183], v[122:125]
	s_add_u32 s4, s4, 0x80
	s_addc_u32 s5, s5, 0
	v_exp_f32_e32 v238, v238
	v_mfma_f32_16x16x32_bf16 v[126:129], v[196:199], v[180:183], v[126:129]
	s_add_u32 s6, s6, 0x80
	s_addc_u32 s7, s7, 0
	v_exp_f32_e32 v239, v239
	s_waitcnt lgkmcnt(0)
	v_mfma_f32_16x16x32_bf16 v[66:69], v[152:155], v[136:139], v[66:69]
	ds_read_b128 v[168:171], v225 offset:0
	v_mfma_f32_16x16x32_bf16 v[70:73], v[156:159], v[136:139], v[70:73]
	ds_read_b128 v[172:175], v225 offset:2048
	v_add_f32_e32 v1, 1.0, v1
	v_mfma_f32_16x16x32_bf16 v[74:77], v[160:163], v[136:139], v[74:77]
	ds_read_b128 v[176:179], v225 offset:4096
	v_add_f32_e32 v130, 1.0, v130
	v_mfma_f32_16x16x32_bf16 v[78:81], v[164:167], v[136:139], v[78:81]
	ds_read_b128 v[180:183], v225 offset:6144
	v_add_f32_e32 v238, 1.0, v238
	v_mfma_f32_16x16x32_bf16 v[82:85], v[152:155], v[140:143], v[82:85]
	ds_read_b128 v[184:187], v233 offset:0
	v_add_f32_e32 v239, 1.0, v239
	v_mfma_f32_16x16x32_bf16 v[86:89], v[156:159], v[140:143], v[86:89]
	ds_read_b128 v[188:191], v233 offset:2048
	v_rcp_f32_e32 v1, v1
	v_mfma_f32_16x16x32_bf16 v[90:93], v[160:163], v[140:143], v[90:93]
	ds_read_b128 v[192:195], v233 offset:4096
	v_rcp_f32_e32 v130, v130
	v_mfma_f32_16x16x32_bf16 v[94:97], v[164:167], v[140:143], v[94:97]
	ds_read_b128 v[196:199], v233 offset:6144
	v_rcp_f32_e32 v238, v238
	v_mfma_f32_16x16x32_bf16 v[98:101], v[152:155], v[144:147], v[98:101]
	v_mfma_f32_16x16x32_bf16 v[102:105], v[156:159], v[144:147], v[102:105]
	v_rcp_f32_e32 v239, v239
	v_mfma_f32_16x16x32_bf16 v[106:109], v[160:163], v[144:147], v[106:109]
	v_mul_f32_e32 v46, v46, v1
	v_mfma_f32_16x16x32_bf16 v[110:113], v[164:167], v[144:147], v[110:113]
	v_mul_f32_e32 v47, v47, v130
	v_mfma_f32_16x16x32_bf16 v[114:117], v[152:155], v[148:151], v[114:117]
	v_mul_f32_e32 v48, v48, v238
	v_mfma_f32_16x16x32_bf16 v[118:121], v[156:159], v[148:151], v[118:121]
	v_mul_f32_e32 v49, v49, v239
	v_mfma_f32_16x16x32_bf16 v[122:125], v[160:163], v[148:151], v[122:125]
	v_cvt_pk_bf16_f32 v46, v46, v47
	v_mfma_f32_16x16x32_bf16 v[126:129], v[164:167], v[148:151], v[126:129]
	v_cvt_pk_bf16_f32 v47, v48, v49
	s_waitcnt vmcnt(7) lgkmcnt(0)
	s_barrier
	v_mfma_f32_16x16x32_bf16 v[66:69], v[184:187], v[168:171], v[66:69]
	ds_read_b128 v[136:139], v219 offset:0
	v_mfma_f32_16x16x32_bf16 v[70:73], v[188:191], v[168:171], v[70:73]
	ds_read_b128 v[140:143], v219 offset:2048
	global_store_dwordx2 v236, v[46:47], s[10:11] offset:96 sc1
	v_mfma_f32_16x16x32_bf16 v[74:77], v[192:195], v[168:171], v[74:77]
	ds_read_b128 v[144:147], v219 offset:4096
	v_mfma_f32_16x16x32_bf16 v[78:81], v[196:199], v[168:171], v[78:81]
	ds_read_b128 v[148:151], v219 offset:6144
	s_add_u32 s10, s10, 0x8000
	s_addc_u32 s11, s11, 0
	v_mfma_f32_16x16x32_bf16 v[82:85], v[184:187], v[172:175], v[82:85]
	ds_read_b128 v[152:155], v231 offset:0
	v_mul_f32_e32 v1, s12, v50
	v_mfma_f32_16x16x32_bf16 v[86:89], v[188:191], v[172:175], v[86:89]
	ds_read_b128 v[156:159], v231 offset:2048
	v_mfma_f32_16x16x32_bf16 v[90:93], v[192:195], v[172:175], v[90:93]
	ds_read_b128 v[160:163], v231 offset:4096
	v_mul_f32_e32 v130, s12, v51
	v_mfma_f32_16x16x32_bf16 v[94:97], v[196:199], v[172:175], v[94:97]
	ds_read_b128 v[164:167], v231 offset:6144
	v_mul_f32_e32 v238, s12, v52
	s_mov_b32 m0, s8
	v_mfma_f32_16x16x32_bf16 v[98:101], v[184:187], v[176:179], v[98:101]
	global_load_lds_dwordx4 v200, s[4:5]
	s_add_u32 m0, s8, 0x400
	v_mfma_f32_16x16x32_bf16 v[102:105], v[188:191], v[176:179], v[102:105]
	global_load_lds_dwordx4 v201, s[4:5]
	v_mul_f32_e32 v239, s12, v53
	s_add_u32 m0, s8, 0x800
	v_mfma_f32_16x16x32_bf16 v[106:109], v[192:195], v[176:179], v[106:109]
	global_load_lds_dwordx4 v202, s[4:5]
	s_add_u32 m0, s8, 0xc00
	v_mfma_f32_16x16x32_bf16 v[110:113], v[196:199], v[176:179], v[110:113]
	global_load_lds_dwordx4 v203, s[4:5]
	v_exp_f32_e32 v1, v1
	s_mov_b32 m0, s9
	v_mfma_f32_16x16x32_bf16 v[114:117], v[184:187], v[180:183], v[114:117]
	global_load_lds_dwordx4 v204, s[6:7]
	v_exp_f32_e32 v130, v130
	s_add_u32 m0, s9, 0x400
	v_mfma_f32_16x16x32_bf16 v[118:121], v[188:191], v[180:183], v[118:121]
	global_load_lds_dwordx4 v205, s[6:7]
	v_mfma_f32_16x16x32_bf16 v[122:125], v[192:195], v[180:183], v[122:125]
	s_add_u32 s4, s4, 0x80
	s_addc_u32 s5, s5, 0
	v_exp_f32_e32 v238, v238
	v_mfma_f32_16x16x32_bf16 v[126:129], v[196:199], v[180:183], v[126:129]
	s_add_u32 s6, s6, 0x80
	s_addc_u32 s7, s7, 0
	v_exp_f32_e32 v239, v239
	s_waitcnt lgkmcnt(0)
	v_mfma_f32_16x16x32_bf16 v[66:69], v[152:155], v[136:139], v[66:69]
	ds_read_b128 v[168:171], v228 offset:0
	v_mfma_f32_16x16x32_bf16 v[70:73], v[156:159], v[136:139], v[70:73]
	ds_read_b128 v[172:175], v228 offset:2048
	v_add_f32_e32 v1, 1.0, v1
	v_mfma_f32_16x16x32_bf16 v[74:77], v[160:163], v[136:139], v[74:77]
	ds_read_b128 v[176:179], v228 offset:4096
	v_add_f32_e32 v130, 1.0, v130
	v_mfma_f32_16x16x32_bf16 v[78:81], v[164:167], v[136:139], v[78:81]
	ds_read_b128 v[180:183], v228 offset:6144
	v_add_f32_e32 v238, 1.0, v238
	v_mfma_f32_16x16x32_bf16 v[82:85], v[152:155], v[140:143], v[82:85]
	ds_read_b128 v[184:187], v234 offset:0
	v_add_f32_e32 v239, 1.0, v239
	v_mfma_f32_16x16x32_bf16 v[86:89], v[156:159], v[140:143], v[86:89]
	ds_read_b128 v[188:191], v234 offset:2048
	v_rcp_f32_e32 v1, v1
	v_mfma_f32_16x16x32_bf16 v[90:93], v[160:163], v[140:143], v[90:93]
	ds_read_b128 v[192:195], v234 offset:4096
	v_rcp_f32_e32 v130, v130
	v_mfma_f32_16x16x32_bf16 v[94:97], v[164:167], v[140:143], v[94:97]
	ds_read_b128 v[196:199], v234 offset:6144
	v_rcp_f32_e32 v238, v238
	v_mfma_f32_16x16x32_bf16 v[98:101], v[152:155], v[144:147], v[98:101]
	v_mfma_f32_16x16x32_bf16 v[102:105], v[156:159], v[144:147], v[102:105]
	v_rcp_f32_e32 v239, v239
	v_mfma_f32_16x16x32_bf16 v[106:109], v[160:163], v[144:147], v[106:109]
	v_mul_f32_e32 v50, v50, v1
	v_mfma_f32_16x16x32_bf16 v[110:113], v[164:167], v[144:147], v[110:113]
	v_mul_f32_e32 v51, v51, v130
	v_mfma_f32_16x16x32_bf16 v[114:117], v[152:155], v[148:151], v[114:117]
	v_mul_f32_e32 v52, v52, v238
	v_mfma_f32_16x16x32_bf16 v[118:121], v[156:159], v[148:151], v[118:121]
	v_mul_f32_e32 v53, v53, v239
	v_mfma_f32_16x16x32_bf16 v[122:125], v[160:163], v[148:151], v[122:125]
	v_cvt_pk_bf16_f32 v50, v50, v51
	v_mfma_f32_16x16x32_bf16 v[126:129], v[164:167], v[148:151], v[126:129]
	v_cvt_pk_bf16_f32 v51, v52, v53
	s_waitcnt vmcnt(7) lgkmcnt(0)
	s_barrier
	v_mfma_f32_16x16x32_bf16 v[66:69], v[184:187], v[168:171], v[66:69]
	ds_read_b128 v[136:139], v224 offset:0
	v_mfma_f32_16x16x32_bf16 v[70:73], v[188:191], v[168:171], v[70:73]
	ds_read_b128 v[140:143], v224 offset:2048
	global_store_dwordx2 v236, v[50:51], s[10:11] offset:0 sc1
	v_mfma_f32_16x16x32_bf16 v[74:77], v[192:195], v[168:171], v[74:77]
	ds_read_b128 v[144:147], v224 offset:4096
	v_mfma_f32_16x16x32_bf16 v[78:81], v[196:199], v[168:171], v[78:81]
	ds_read_b128 v[148:151], v224 offset:6144
	v_mul_f32_e32 v1, s12, v54
	v_mfma_f32_16x16x32_bf16 v[82:85], v[184:187], v[172:175], v[82:85]
	ds_read_b128 v[152:155], v232 offset:0
	v_mul_f32_e32 v130, s12, v55
	v_mfma_f32_16x16x32_bf16 v[86:89], v[188:191], v[172:175], v[86:89]
	ds_read_b128 v[156:159], v232 offset:2048
	v_mfma_f32_16x16x32_bf16 v[90:93], v[192:195], v[172:175], v[90:93]
	ds_read_b128 v[160:163], v232 offset:4096
	v_mul_f32_e32 v238, s12, v56
	v_mfma_f32_16x16x32_bf16 v[94:97], v[196:199], v[172:175], v[94:97]
	ds_read_b128 v[164:167], v232 offset:6144
	v_mul_f32_e32 v239, s12, v57
	s_add_u32 m0, s8, 0xc000
	v_mfma_f32_16x16x32_bf16 v[98:101], v[184:187], v[176:179], v[98:101]
	global_load_lds_dwordx4 v200, s[4:5]
	s_add_u32 m0, s8, 0xc400
	v_mfma_f32_16x16x32_bf16 v[102:105], v[188:191], v[176:179], v[102:105]
	global_load_lds_dwordx4 v201, s[4:5]
	v_exp_f32_e32 v1, v1
	s_add_u32 m0, s8, 0xc800
	v_mfma_f32_16x16x32_bf16 v[106:109], v[192:195], v[176:179], v[106:109]
	global_load_lds_dwordx4 v202, s[4:5]
	s_add_u32 m0, s8, 0xcc00
	v_mfma_f32_16x16x32_bf16 v[110:113], v[196:199], v[176:179], v[110:113]
	global_load_lds_dwordx4 v203, s[4:5]
	v_exp_f32_e32 v130, v130
	s_add_u32 m0, s9, 0xc000
	v_mfma_f32_16x16x32_bf16 v[114:117], v[184:187], v[180:183], v[114:117]
	global_load_lds_dwordx4 v204, s[6:7]
	v_exp_f32_e32 v238, v238
	s_add_u32 m0, s9, 0xc400
	v_mfma_f32_16x16x32_bf16 v[118:121], v[188:191], v[180:183], v[118:121]
	global_load_lds_dwordx4 v205, s[6:7]
	v_mfma_f32_16x16x32_bf16 v[122:125], v[192:195], v[180:183], v[122:125]
	s_sub_u32 s4, s4, 0x780
	s_subb_u32 s5, s5, 0
	v_exp_f32_e32 v239, v239
	v_mfma_f32_16x16x32_bf16 v[126:129], v[196:199], v[180:183], v[126:129]
	s_add_u32 s6, s6, 0x3f880
	s_addc_u32 s7, s7, 0
	v_add_f32_e32 v1, 1.0, v1
	s_waitcnt lgkmcnt(0)
	v_mfma_f32_16x16x32_bf16 v[66:69], v[152:155], v[136:139], v[66:69]
	ds_read_b128 v[168:171], v229 offset:0
	v_mfma_f32_16x16x32_bf16 v[70:73], v[156:159], v[136:139], v[70:73]
	ds_read_b128 v[172:175], v229 offset:2048
	v_add_f32_e32 v130, 1.0, v130
	v_mfma_f32_16x16x32_bf16 v[74:77], v[160:163], v[136:139], v[74:77]
	ds_read_b128 v[176:179], v229 offset:4096
	v_add_f32_e32 v238, 1.0, v238
	v_mfma_f32_16x16x32_bf16 v[78:81], v[164:167], v[136:139], v[78:81]
	ds_read_b128 v[180:183], v229 offset:6144
	v_add_f32_e32 v239, 1.0, v239
	v_mfma_f32_16x16x32_bf16 v[82:85], v[152:155], v[140:143], v[82:85]
	ds_read_b128 v[184:187], v235 offset:0
	v_rcp_f32_e32 v1, v1
	v_mfma_f32_16x16x32_bf16 v[86:89], v[156:159], v[140:143], v[86:89]
	ds_read_b128 v[188:191], v235 offset:2048
	v_rcp_f32_e32 v130, v130
	v_mfma_f32_16x16x32_bf16 v[90:93], v[160:163], v[140:143], v[90:93]
	ds_read_b128 v[192:195], v235 offset:4096
	v_rcp_f32_e32 v238, v238
	v_mfma_f32_16x16x32_bf16 v[94:97], v[164:167], v[140:143], v[94:97]
	ds_read_b128 v[196:199], v235 offset:6144
	v_rcp_f32_e32 v239, v239
	v_mfma_f32_16x16x32_bf16 v[98:101], v[152:155], v[144:147], v[98:101]
	v_mfma_f32_16x16x32_bf16 v[102:105], v[156:159], v[144:147], v[102:105]
	v_mul_f32_e32 v54, v54, v1
	v_mfma_f32_16x16x32_bf16 v[106:109], v[160:163], v[144:147], v[106:109]
	v_mul_f32_e32 v55, v55, v130
	v_mfma_f32_16x16x32_bf16 v[110:113], v[164:167], v[144:147], v[110:113]
	v_mul_f32_e32 v56, v56, v238
	v_mfma_f32_16x16x32_bf16 v[114:117], v[152:155], v[148:151], v[114:117]
	v_mul_f32_e32 v57, v57, v239
	v_mfma_f32_16x16x32_bf16 v[118:121], v[156:159], v[148:151], v[118:121]
	v_cvt_pk_bf16_f32 v54, v54, v55
	v_mfma_f32_16x16x32_bf16 v[122:125], v[160:163], v[148:151], v[122:125]
	v_cvt_pk_bf16_f32 v55, v56, v57
	v_mfma_f32_16x16x32_bf16 v[126:129], v[164:167], v[148:151], v[126:129]
	global_store_dwordx2 v236, v[54:55], s[10:11] offset:32 sc1
	s_waitcnt vmcnt(8) lgkmcnt(0)
	s_barrier
	v_mfma_f32_16x16x32_bf16 v[66:69], v[184:187], v[168:171], v[66:69]
	ds_read_b128 v[136:139], v218 offset:0
	v_mfma_f32_16x16x32_bf16 v[70:73], v[188:191], v[168:171], v[70:73]
	ds_read_b128 v[140:143], v218 offset:2048
	v_mul_f32_e32 v1, s12, v58
	v_mfma_f32_16x16x32_bf16 v[74:77], v[192:195], v[168:171], v[74:77]
	ds_read_b128 v[144:147], v218 offset:4096
	v_mfma_f32_16x16x32_bf16 v[78:81], v[196:199], v[168:171], v[78:81]
	ds_read_b128 v[148:151], v218 offset:6144
	v_mul_f32_e32 v130, s12, v59
	v_mfma_f32_16x16x32_bf16 v[82:85], v[184:187], v[172:175], v[82:85]
	ds_read_b128 v[152:155], v230 offset:0
	v_mul_f32_e32 v238, s12, v60
	v_mfma_f32_16x16x32_bf16 v[86:89], v[188:191], v[172:175], v[86:89]
	ds_read_b128 v[156:159], v230 offset:2048
	v_mfma_f32_16x16x32_bf16 v[90:93], v[192:195], v[172:175], v[90:93]
	ds_read_b128 v[160:163], v230 offset:4096
	v_mul_f32_e32 v239, s12, v61
	v_mfma_f32_16x16x32_bf16 v[94:97], v[196:199], v[172:175], v[94:97]
	ds_read_b128 v[164:167], v230 offset:6144
	v_exp_f32_e32 v1, v1
	v_mfma_f32_16x16x32_bf16 v[98:101], v[184:187], v[176:179], v[98:101]
	v_mfma_f32_16x16x32_bf16 v[102:105], v[188:191], v[176:179], v[102:105]
	v_exp_f32_e32 v130, v130
	v_mfma_f32_16x16x32_bf16 v[106:109], v[192:195], v[176:179], v[106:109]
	v_mfma_f32_16x16x32_bf16 v[110:113], v[196:199], v[176:179], v[110:113]
	v_exp_f32_e32 v238, v238
	v_mfma_f32_16x16x32_bf16 v[114:117], v[184:187], v[180:183], v[114:117]
	v_exp_f32_e32 v239, v239
	v_mfma_f32_16x16x32_bf16 v[118:121], v[188:191], v[180:183], v[118:121]
	v_mfma_f32_16x16x32_bf16 v[122:125], v[192:195], v[180:183], v[122:125]
	v_add_f32_e32 v1, 1.0, v1
	v_mfma_f32_16x16x32_bf16 v[126:129], v[196:199], v[180:183], v[126:129]
	v_add_f32_e32 v130, 1.0, v130
	s_waitcnt lgkmcnt(0)
	v_mfma_f32_16x16x32_bf16 v[66:69], v[152:155], v[136:139], v[66:69]
	ds_read_b128 v[168:171], v225 offset:0
	v_mfma_f32_16x16x32_bf16 v[70:73], v[156:159], v[136:139], v[70:73]
	ds_read_b128 v[172:175], v225 offset:2048
	v_add_f32_e32 v238, 1.0, v238
	v_mfma_f32_16x16x32_bf16 v[74:77], v[160:163], v[136:139], v[74:77]
	ds_read_b128 v[176:179], v225 offset:4096
	v_add_f32_e32 v239, 1.0, v239
	v_mfma_f32_16x16x32_bf16 v[78:81], v[164:167], v[136:139], v[78:81]
	ds_read_b128 v[180:183], v225 offset:6144
	v_rcp_f32_e32 v1, v1
	v_mfma_f32_16x16x32_bf16 v[82:85], v[152:155], v[140:143], v[82:85]
	ds_read_b128 v[184:187], v233 offset:0
	v_rcp_f32_e32 v130, v130
	v_mfma_f32_16x16x32_bf16 v[86:89], v[156:159], v[140:143], v[86:89]
	ds_read_b128 v[188:191], v233 offset:2048
	v_rcp_f32_e32 v238, v238
	v_mfma_f32_16x16x32_bf16 v[90:93], v[160:163], v[140:143], v[90:93]
	ds_read_b128 v[192:195], v233 offset:4096
	v_rcp_f32_e32 v239, v239
	v_mfma_f32_16x16x32_bf16 v[94:97], v[164:167], v[140:143], v[94:97]
	ds_read_b128 v[196:199], v233 offset:6144
	v_mul_f32_e32 v58, v58, v1
	v_mfma_f32_16x16x32_bf16 v[98:101], v[152:155], v[144:147], v[98:101]
	v_mfma_f32_16x16x32_bf16 v[102:105], v[156:159], v[144:147], v[102:105]
	v_mul_f32_e32 v59, v59, v130
	v_mfma_f32_16x16x32_bf16 v[106:109], v[160:163], v[144:147], v[106:109]
	v_mul_f32_e32 v60, v60, v238
	v_mfma_f32_16x16x32_bf16 v[110:113], v[164:167], v[144:147], v[110:113]
	v_mul_f32_e32 v61, v61, v239
	v_mfma_f32_16x16x32_bf16 v[114:117], v[152:155], v[148:151], v[114:117]
	v_cvt_pk_bf16_f32 v58, v58, v59
	v_mfma_f32_16x16x32_bf16 v[118:121], v[156:159], v[148:151], v[118:121]
	v_cvt_pk_bf16_f32 v59, v60, v61
	v_mfma_f32_16x16x32_bf16 v[122:125], v[160:163], v[148:151], v[122:125]
	global_store_dwordx2 v236, v[58:59], s[10:11] offset:64 sc1
	v_mfma_f32_16x16x32_bf16 v[126:129], v[164:167], v[148:151], v[126:129]
	v_mul_f32_e32 v1, s12, v62
	s_waitcnt vmcnt(2) lgkmcnt(0)
	s_barrier
	v_mfma_f32_16x16x32_bf16 v[66:69], v[184:187], v[168:171], v[66:69]
	ds_read_b128 v[136:139], v219 offset:0
	v_mfma_f32_16x16x32_bf16 v[70:73], v[188:191], v[168:171], v[70:73]
	ds_read_b128 v[140:143], v219 offset:2048
	v_mul_f32_e32 v130, s12, v63
	v_mfma_f32_16x16x32_bf16 v[74:77], v[192:195], v[168:171], v[74:77]
	ds_read_b128 v[144:147], v219 offset:4096
	v_mfma_f32_16x16x32_bf16 v[78:81], v[196:199], v[168:171], v[78:81]
	ds_read_b128 v[148:151], v219 offset:6144
	v_mul_f32_e32 v238, s12, v64
	v_mfma_f32_16x16x32_bf16 v[82:85], v[184:187], v[172:175], v[82:85]
	ds_read_b128 v[152:155], v231 offset:0
	v_mul_f32_e32 v239, s12, v65
	v_mfma_f32_16x16x32_bf16 v[86:89], v[188:191], v[172:175], v[86:89]
	ds_read_b128 v[156:159], v231 offset:2048
	v_mfma_f32_16x16x32_bf16 v[90:93], v[192:195], v[172:175], v[90:93]
	ds_read_b128 v[160:163], v231 offset:4096
	v_exp_f32_e32 v1, v1
	v_mfma_f32_16x16x32_bf16 v[94:97], v[196:199], v[172:175], v[94:97]
	ds_read_b128 v[164:167], v231 offset:6144
	v_exp_f32_e32 v130, v130
	v_mfma_f32_16x16x32_bf16 v[98:101], v[184:187], v[176:179], v[98:101]
	v_mfma_f32_16x16x32_bf16 v[102:105], v[188:191], v[176:179], v[102:105]
	v_exp_f32_e32 v238, v238
	v_mfma_f32_16x16x32_bf16 v[106:109], v[192:195], v[176:179], v[106:109]
	v_mfma_f32_16x16x32_bf16 v[110:113], v[196:199], v[176:179], v[110:113]
	v_exp_f32_e32 v239, v239
	v_mfma_f32_16x16x32_bf16 v[114:117], v[184:187], v[180:183], v[114:117]
	v_add_f32_e32 v1, 1.0, v1
	v_mfma_f32_16x16x32_bf16 v[118:121], v[188:191], v[180:183], v[118:121]
	v_mfma_f32_16x16x32_bf16 v[122:125], v[192:195], v[180:183], v[122:125]
	v_add_f32_e32 v130, 1.0, v130
	v_mfma_f32_16x16x32_bf16 v[126:129], v[196:199], v[180:183], v[126:129]
	v_add_f32_e32 v238, 1.0, v238
	s_waitcnt lgkmcnt(0)
	v_mfma_f32_16x16x32_bf16 v[66:69], v[152:155], v[136:139], v[66:69]
	ds_read_b128 v[168:171], v228 offset:0
	v_mfma_f32_16x16x32_bf16 v[70:73], v[156:159], v[136:139], v[70:73]
	ds_read_b128 v[172:175], v228 offset:2048
	v_add_f32_e32 v239, 1.0, v239
	v_mfma_f32_16x16x32_bf16 v[74:77], v[160:163], v[136:139], v[74:77]
	ds_read_b128 v[176:179], v228 offset:4096
	v_rcp_f32_e32 v1, v1
	v_mfma_f32_16x16x32_bf16 v[78:81], v[164:167], v[136:139], v[78:81]
	ds_read_b128 v[180:183], v228 offset:6144
	v_rcp_f32_e32 v130, v130
	v_mfma_f32_16x16x32_bf16 v[82:85], v[152:155], v[140:143], v[82:85]
	ds_read_b128 v[184:187], v234 offset:0
	v_mfma_f32_16x16x32_bf16 v[86:89], v[156:159], v[140:143], v[86:89]
	ds_read_b128 v[188:191], v234 offset:2048
	v_rcp_f32_e32 v238, v238
	v_mfma_f32_16x16x32_bf16 v[90:93], v[160:163], v[140:143], v[90:93]
	ds_read_b128 v[192:195], v234 offset:4096
	v_rcp_f32_e32 v239, v239
	v_mfma_f32_16x16x32_bf16 v[94:97], v[164:167], v[140:143], v[94:97]
	ds_read_b128 v[196:199], v234 offset:6144
	v_mul_f32_e32 v62, v62, v1
	v_mfma_f32_16x16x32_bf16 v[98:101], v[152:155], v[144:147], v[98:101]
	v_mfma_f32_16x16x32_bf16 v[102:105], v[156:159], v[144:147], v[102:105]
	v_mul_f32_e32 v63, v63, v130
	v_mfma_f32_16x16x32_bf16 v[106:109], v[160:163], v[144:147], v[106:109]
	v_mul_f32_e32 v64, v64, v238
	v_mfma_f32_16x16x32_bf16 v[110:113], v[164:167], v[144:147], v[110:113]
	v_mul_f32_e32 v65, v65, v239
	v_mfma_f32_16x16x32_bf16 v[114:117], v[152:155], v[148:151], v[114:117]
	v_mfma_f32_16x16x32_bf16 v[118:121], v[156:159], v[148:151], v[118:121]
	v_cvt_pk_bf16_f32 v62, v62, v63
	v_mfma_f32_16x16x32_bf16 v[122:125], v[160:163], v[148:151], v[122:125]
	v_cvt_pk_bf16_f32 v63, v64, v65
	v_mfma_f32_16x16x32_bf16 v[126:129], v[164:167], v[148:151], v[126:129]
	global_store_dwordx2 v236, v[62:63], s[10:11] offset:96 sc1
	s_waitcnt lgkmcnt(0)
	v_mfma_f32_16x16x32_bf16 v[66:69], v[184:187], v[168:171], v[66:69]
	v_mfma_f32_16x16x32_bf16 v[70:73], v[188:191], v[168:171], v[70:73]
	v_mfma_f32_16x16x32_bf16 v[74:77], v[192:195], v[168:171], v[74:77]
	v_mfma_f32_16x16x32_bf16 v[78:81], v[196:199], v[168:171], v[78:81]
	v_mfma_f32_16x16x32_bf16 v[82:85], v[184:187], v[172:175], v[82:85]
	v_mfma_f32_16x16x32_bf16 v[86:89], v[188:191], v[172:175], v[86:89]
	v_mfma_f32_16x16x32_bf16 v[90:93], v[192:195], v[172:175], v[90:93]
	v_mfma_f32_16x16x32_bf16 v[94:97], v[196:199], v[172:175], v[94:97]
	v_mfma_f32_16x16x32_bf16 v[98:101], v[184:187], v[176:179], v[98:101]
	v_mfma_f32_16x16x32_bf16 v[102:105], v[188:191], v[176:179], v[102:105]
	v_mfma_f32_16x16x32_bf16 v[106:109], v[192:195], v[176:179], v[106:109]
	v_mfma_f32_16x16x32_bf16 v[110:113], v[196:199], v[176:179], v[110:113]
	v_mfma_f32_16x16x32_bf16 v[114:117], v[184:187], v[180:183], v[114:117]
	v_mfma_f32_16x16x32_bf16 v[118:121], v[188:191], v[180:183], v[118:121]
	v_mfma_f32_16x16x32_bf16 v[122:125], v[192:195], v[180:183], v[122:125]
	v_mfma_f32_16x16x32_bf16 v[126:129], v[196:199], v[180:183], v[126:129]
	s_nop 7
	s_add_u32 s10, s54, 0x100
	s_addc_u32 s11, s55, 0
	v_mul_f32_e32 v1, s12, v66
	v_mul_f32_e32 v130, s12, v67
	v_mul_f32_e32 v238, s12, v68
	v_mul_f32_e32 v239, s12, v69
	v_exp_f32_e32 v1, v1
	v_exp_f32_e32 v130, v130
	v_exp_f32_e32 v238, v238
	v_exp_f32_e32 v239, v239
	v_add_f32_e32 v1, 1.0, v1
	v_add_f32_e32 v130, 1.0, v130
	v_add_f32_e32 v238, 1.0, v238
	v_add_f32_e32 v239, 1.0, v239
	v_rcp_f32_e32 v1, v1
	v_rcp_f32_e32 v130, v130
	v_rcp_f32_e32 v238, v238
	v_rcp_f32_e32 v239, v239
	v_mul_f32_e32 v66, v66, v1
	v_mul_f32_e32 v67, v67, v130
	v_mul_f32_e32 v68, v68, v238
	v_mul_f32_e32 v69, v69, v239
	v_cvt_pk_bf16_f32 v66, v66, v67
	v_cvt_pk_bf16_f32 v67, v68, v69
	global_store_dwordx2 v236, v[66:67], s[10:11] offset:0 sc1
	v_mul_f32_e32 v1, s12, v70
	v_mul_f32_e32 v130, s12, v71
	v_mul_f32_e32 v238, s12, v72
	v_mul_f32_e32 v239, s12, v73
	v_exp_f32_e32 v1, v1
	v_exp_f32_e32 v130, v130
	v_exp_f32_e32 v238, v238
	v_exp_f32_e32 v239, v239
	v_add_f32_e32 v1, 1.0, v1
	v_add_f32_e32 v130, 1.0, v130
	v_add_f32_e32 v238, 1.0, v238
	v_add_f32_e32 v239, 1.0, v239
	v_rcp_f32_e32 v1, v1
	v_rcp_f32_e32 v130, v130
	v_rcp_f32_e32 v238, v238
	v_rcp_f32_e32 v239, v239
	v_mul_f32_e32 v70, v70, v1
	v_mul_f32_e32 v71, v71, v130
	v_mul_f32_e32 v72, v72, v238
	v_mul_f32_e32 v73, v73, v239
	v_cvt_pk_bf16_f32 v70, v70, v71
	v_cvt_pk_bf16_f32 v71, v72, v73
	global_store_dwordx2 v236, v[70:71], s[10:11] offset:32 sc1
	v_mul_f32_e32 v1, s12, v74
	v_mul_f32_e32 v130, s12, v75
	v_mul_f32_e32 v238, s12, v76
	v_mul_f32_e32 v239, s12, v77
	v_exp_f32_e32 v1, v1
	v_exp_f32_e32 v130, v130
	v_exp_f32_e32 v238, v238
	v_exp_f32_e32 v239, v239
	v_add_f32_e32 v1, 1.0, v1
	v_add_f32_e32 v130, 1.0, v130
	v_add_f32_e32 v238, 1.0, v238
	v_add_f32_e32 v239, 1.0, v239
	v_rcp_f32_e32 v1, v1
	v_rcp_f32_e32 v130, v130
	v_rcp_f32_e32 v238, v238
	v_rcp_f32_e32 v239, v239
	v_mul_f32_e32 v74, v74, v1
	v_mul_f32_e32 v75, v75, v130
	v_mul_f32_e32 v76, v76, v238
	v_mul_f32_e32 v77, v77, v239
	v_cvt_pk_bf16_f32 v74, v74, v75
	v_cvt_pk_bf16_f32 v75, v76, v77
	global_store_dwordx2 v236, v[74:75], s[10:11] offset:64 sc1
	v_mul_f32_e32 v1, s12, v78
	v_mul_f32_e32 v130, s12, v79
	v_mul_f32_e32 v238, s12, v80
	v_mul_f32_e32 v239, s12, v81
	v_exp_f32_e32 v1, v1
	v_exp_f32_e32 v130, v130
	v_exp_f32_e32 v238, v238
	v_exp_f32_e32 v239, v239
	v_add_f32_e32 v1, 1.0, v1
	v_add_f32_e32 v130, 1.0, v130
	v_add_f32_e32 v238, 1.0, v238
	v_add_f32_e32 v239, 1.0, v239
	v_rcp_f32_e32 v1, v1
	v_rcp_f32_e32 v130, v130
	v_rcp_f32_e32 v238, v238
	v_rcp_f32_e32 v239, v239
	v_mul_f32_e32 v78, v78, v1
	v_mul_f32_e32 v79, v79, v130
	v_mul_f32_e32 v80, v80, v238
	v_mul_f32_e32 v81, v81, v239
	v_cvt_pk_bf16_f32 v78, v78, v79
	v_cvt_pk_bf16_f32 v79, v80, v81
	global_store_dwordx2 v236, v[78:79], s[10:11] offset:96 sc1
	s_add_u32 s10, s10, 0x8000
	s_addc_u32 s11, s11, 0
	v_mul_f32_e32 v1, s12, v82
	v_mul_f32_e32 v130, s12, v83
	v_mul_f32_e32 v238, s12, v84
	v_mul_f32_e32 v239, s12, v85
	v_exp_f32_e32 v1, v1
	v_exp_f32_e32 v130, v130
	v_exp_f32_e32 v238, v238
	v_exp_f32_e32 v239, v239
	v_add_f32_e32 v1, 1.0, v1
	v_add_f32_e32 v130, 1.0, v130
	v_add_f32_e32 v238, 1.0, v238
	v_add_f32_e32 v239, 1.0, v239
	v_rcp_f32_e32 v1, v1
	v_rcp_f32_e32 v130, v130
	v_rcp_f32_e32 v238, v238
	v_rcp_f32_e32 v239, v239
	v_mul_f32_e32 v82, v82, v1
	v_mul_f32_e32 v83, v83, v130
	v_mul_f32_e32 v84, v84, v238
	v_mul_f32_e32 v85, v85, v239
	v_cvt_pk_bf16_f32 v82, v82, v83
	v_cvt_pk_bf16_f32 v83, v84, v85
	global_store_dwordx2 v236, v[82:83], s[10:11] offset:0 sc1
	v_mul_f32_e32 v1, s12, v86
	v_mul_f32_e32 v130, s12, v87
	v_mul_f32_e32 v238, s12, v88
	v_mul_f32_e32 v239, s12, v89
	v_exp_f32_e32 v1, v1
	v_exp_f32_e32 v130, v130
	v_exp_f32_e32 v238, v238
	v_exp_f32_e32 v239, v239
	v_add_f32_e32 v1, 1.0, v1
	v_add_f32_e32 v130, 1.0, v130
	v_add_f32_e32 v238, 1.0, v238
	v_add_f32_e32 v239, 1.0, v239
	v_rcp_f32_e32 v1, v1
	v_rcp_f32_e32 v130, v130
	v_rcp_f32_e32 v238, v238
	v_rcp_f32_e32 v239, v239
	v_mul_f32_e32 v86, v86, v1
	v_mul_f32_e32 v87, v87, v130
	v_mul_f32_e32 v88, v88, v238
	v_mul_f32_e32 v89, v89, v239
	v_cvt_pk_bf16_f32 v86, v86, v87
	v_cvt_pk_bf16_f32 v87, v88, v89
	global_store_dwordx2 v236, v[86:87], s[10:11] offset:32 sc1
	v_mul_f32_e32 v1, s12, v90
	v_mul_f32_e32 v130, s12, v91
	v_mul_f32_e32 v238, s12, v92
	v_mul_f32_e32 v239, s12, v93
	v_exp_f32_e32 v1, v1
	v_exp_f32_e32 v130, v130
	v_exp_f32_e32 v238, v238
	v_exp_f32_e32 v239, v239
	v_add_f32_e32 v1, 1.0, v1
	v_add_f32_e32 v130, 1.0, v130
	v_add_f32_e32 v238, 1.0, v238
	v_add_f32_e32 v239, 1.0, v239
	v_rcp_f32_e32 v1, v1
	v_rcp_f32_e32 v130, v130
	v_rcp_f32_e32 v238, v238
	v_rcp_f32_e32 v239, v239
	v_mul_f32_e32 v90, v90, v1
	v_mul_f32_e32 v91, v91, v130
	v_mul_f32_e32 v92, v92, v238
	v_mul_f32_e32 v93, v93, v239
	v_cvt_pk_bf16_f32 v90, v90, v91
	v_cvt_pk_bf16_f32 v91, v92, v93
	global_store_dwordx2 v236, v[90:91], s[10:11] offset:64 sc1
	v_mul_f32_e32 v1, s12, v94
	v_mul_f32_e32 v130, s12, v95
	v_mul_f32_e32 v238, s12, v96
	v_mul_f32_e32 v239, s12, v97
	v_exp_f32_e32 v1, v1
	v_exp_f32_e32 v130, v130
	v_exp_f32_e32 v238, v238
	v_exp_f32_e32 v239, v239
	v_add_f32_e32 v1, 1.0, v1
	v_add_f32_e32 v130, 1.0, v130
	v_add_f32_e32 v238, 1.0, v238
	v_add_f32_e32 v239, 1.0, v239
	v_rcp_f32_e32 v1, v1
	v_rcp_f32_e32 v130, v130
	v_rcp_f32_e32 v238, v238
	v_rcp_f32_e32 v239, v239
	v_mul_f32_e32 v94, v94, v1
	v_mul_f32_e32 v95, v95, v130
	v_mul_f32_e32 v96, v96, v238
	v_mul_f32_e32 v97, v97, v239
	v_cvt_pk_bf16_f32 v94, v94, v95
	v_cvt_pk_bf16_f32 v95, v96, v97
	global_store_dwordx2 v236, v[94:95], s[10:11] offset:96 sc1
	s_add_u32 s10, s10, 0x8000
	s_addc_u32 s11, s11, 0
	v_mul_f32_e32 v1, s12, v98
	v_mul_f32_e32 v130, s12, v99
	v_mul_f32_e32 v238, s12, v100
	v_mul_f32_e32 v239, s12, v101
	v_exp_f32_e32 v1, v1
	v_exp_f32_e32 v130, v130
	v_exp_f32_e32 v238, v238
	v_exp_f32_e32 v239, v239
	v_add_f32_e32 v1, 1.0, v1
	v_add_f32_e32 v130, 1.0, v130
	v_add_f32_e32 v238, 1.0, v238
	v_add_f32_e32 v239, 1.0, v239
	v_rcp_f32_e32 v1, v1
	v_rcp_f32_e32 v130, v130
	v_rcp_f32_e32 v238, v238
	v_rcp_f32_e32 v239, v239
	v_mul_f32_e32 v98, v98, v1
	v_mul_f32_e32 v99, v99, v130
	v_mul_f32_e32 v100, v100, v238
	v_mul_f32_e32 v101, v101, v239
	v_cvt_pk_bf16_f32 v98, v98, v99
	v_cvt_pk_bf16_f32 v99, v100, v101
	global_store_dwordx2 v236, v[98:99], s[10:11] offset:0 sc1
	v_mul_f32_e32 v1, s12, v102
	v_mul_f32_e32 v130, s12, v103
	v_mul_f32_e32 v238, s12, v104
	v_mul_f32_e32 v239, s12, v105
	v_exp_f32_e32 v1, v1
	v_exp_f32_e32 v130, v130
	v_exp_f32_e32 v238, v238
	v_exp_f32_e32 v239, v239
	v_add_f32_e32 v1, 1.0, v1
	v_add_f32_e32 v130, 1.0, v130
	v_add_f32_e32 v238, 1.0, v238
	v_add_f32_e32 v239, 1.0, v239
	v_rcp_f32_e32 v1, v1
	v_rcp_f32_e32 v130, v130
	v_rcp_f32_e32 v238, v238
	v_rcp_f32_e32 v239, v239
	v_mul_f32_e32 v102, v102, v1
	v_mul_f32_e32 v103, v103, v130
	v_mul_f32_e32 v104, v104, v238
	v_mul_f32_e32 v105, v105, v239
	v_cvt_pk_bf16_f32 v102, v102, v103
	v_cvt_pk_bf16_f32 v103, v104, v105
	global_store_dwordx2 v236, v[102:103], s[10:11] offset:32 sc1
	v_mul_f32_e32 v1, s12, v106
	v_mul_f32_e32 v130, s12, v107
	v_mul_f32_e32 v238, s12, v108
	v_mul_f32_e32 v239, s12, v109
	v_exp_f32_e32 v1, v1
	v_exp_f32_e32 v130, v130
	v_exp_f32_e32 v238, v238
	v_exp_f32_e32 v239, v239
	v_add_f32_e32 v1, 1.0, v1
	v_add_f32_e32 v130, 1.0, v130
	v_add_f32_e32 v238, 1.0, v238
	v_add_f32_e32 v239, 1.0, v239
	v_rcp_f32_e32 v1, v1
	v_rcp_f32_e32 v130, v130
	v_rcp_f32_e32 v238, v238
	v_rcp_f32_e32 v239, v239
	v_mul_f32_e32 v106, v106, v1
	v_mul_f32_e32 v107, v107, v130
	v_mul_f32_e32 v108, v108, v238
	v_mul_f32_e32 v109, v109, v239
	v_cvt_pk_bf16_f32 v106, v106, v107
	v_cvt_pk_bf16_f32 v107, v108, v109
	global_store_dwordx2 v236, v[106:107], s[10:11] offset:64 sc1
	v_mul_f32_e32 v1, s12, v110
	v_mul_f32_e32 v130, s12, v111
	v_mul_f32_e32 v238, s12, v112
	v_mul_f32_e32 v239, s12, v113
	v_exp_f32_e32 v1, v1
	v_exp_f32_e32 v130, v130
	v_exp_f32_e32 v238, v238
	v_exp_f32_e32 v239, v239
	v_add_f32_e32 v1, 1.0, v1
	v_add_f32_e32 v130, 1.0, v130
	v_add_f32_e32 v238, 1.0, v238
	v_add_f32_e32 v239, 1.0, v239
	v_rcp_f32_e32 v1, v1
	v_rcp_f32_e32 v130, v130
	v_rcp_f32_e32 v238, v238
	v_rcp_f32_e32 v239, v239
	v_mul_f32_e32 v110, v110, v1
	v_mul_f32_e32 v111, v111, v130
	v_mul_f32_e32 v112, v112, v238
	v_mul_f32_e32 v113, v113, v239
	v_cvt_pk_bf16_f32 v110, v110, v111
	v_cvt_pk_bf16_f32 v111, v112, v113
	global_store_dwordx2 v236, v[110:111], s[10:11] offset:96 sc1
	s_add_u32 s10, s10, 0x8000
	s_addc_u32 s11, s11, 0
	v_mul_f32_e32 v1, s12, v114
	v_mul_f32_e32 v130, s12, v115
	v_mul_f32_e32 v238, s12, v116
	v_mul_f32_e32 v239, s12, v117
	v_exp_f32_e32 v1, v1
	v_exp_f32_e32 v130, v130
	v_exp_f32_e32 v238, v238
	v_exp_f32_e32 v239, v239
	v_add_f32_e32 v1, 1.0, v1
	v_add_f32_e32 v130, 1.0, v130
	v_add_f32_e32 v238, 1.0, v238
	v_add_f32_e32 v239, 1.0, v239
	v_rcp_f32_e32 v1, v1
	v_rcp_f32_e32 v130, v130
	v_rcp_f32_e32 v238, v238
	v_rcp_f32_e32 v239, v239
	v_mul_f32_e32 v114, v114, v1
	v_mul_f32_e32 v115, v115, v130
	v_mul_f32_e32 v116, v116, v238
	v_mul_f32_e32 v117, v117, v239
	v_cvt_pk_bf16_f32 v114, v114, v115
	v_cvt_pk_bf16_f32 v115, v116, v117
	global_store_dwordx2 v236, v[114:115], s[10:11] offset:0 sc1
	v_mul_f32_e32 v1, s12, v118
	v_mul_f32_e32 v130, s12, v119
	v_mul_f32_e32 v238, s12, v120
	v_mul_f32_e32 v239, s12, v121
	v_exp_f32_e32 v1, v1
	v_exp_f32_e32 v130, v130
	v_exp_f32_e32 v238, v238
	v_exp_f32_e32 v239, v239
	v_add_f32_e32 v1, 1.0, v1
	v_add_f32_e32 v130, 1.0, v130
	v_add_f32_e32 v238, 1.0, v238
	v_add_f32_e32 v239, 1.0, v239
	v_rcp_f32_e32 v1, v1
	v_rcp_f32_e32 v130, v130
	v_rcp_f32_e32 v238, v238
	v_rcp_f32_e32 v239, v239
	v_mul_f32_e32 v118, v118, v1
	v_mul_f32_e32 v119, v119, v130
	v_mul_f32_e32 v120, v120, v238
	v_mul_f32_e32 v121, v121, v239
	v_cvt_pk_bf16_f32 v118, v118, v119
	v_cvt_pk_bf16_f32 v119, v120, v121
	global_store_dwordx2 v236, v[118:119], s[10:11] offset:32 sc1
	v_mul_f32_e32 v1, s12, v122
	v_mul_f32_e32 v130, s12, v123
	v_mul_f32_e32 v238, s12, v124
	v_mul_f32_e32 v239, s12, v125
	v_exp_f32_e32 v1, v1
	v_exp_f32_e32 v130, v130
	v_exp_f32_e32 v238, v238
	v_exp_f32_e32 v239, v239
	v_add_f32_e32 v1, 1.0, v1
	v_add_f32_e32 v130, 1.0, v130
	v_add_f32_e32 v238, 1.0, v238
	v_add_f32_e32 v239, 1.0, v239
	v_rcp_f32_e32 v1, v1
	v_rcp_f32_e32 v130, v130
	v_rcp_f32_e32 v238, v238
	v_rcp_f32_e32 v239, v239
	v_mul_f32_e32 v122, v122, v1
	v_mul_f32_e32 v123, v123, v130
	v_mul_f32_e32 v124, v124, v238
	v_mul_f32_e32 v125, v125, v239
	v_cvt_pk_bf16_f32 v122, v122, v123
	v_cvt_pk_bf16_f32 v123, v124, v125
	global_store_dwordx2 v236, v[122:123], s[10:11] offset:64 sc1
	v_mul_f32_e32 v1, s12, v126
	v_mul_f32_e32 v130, s12, v127
	v_mul_f32_e32 v238, s12, v128
	v_mul_f32_e32 v239, s12, v129
	v_exp_f32_e32 v1, v1
	v_exp_f32_e32 v130, v130
	v_exp_f32_e32 v238, v238
	v_exp_f32_e32 v239, v239
	v_add_f32_e32 v1, 1.0, v1
	v_add_f32_e32 v130, 1.0, v130
	v_add_f32_e32 v238, 1.0, v238
	v_add_f32_e32 v239, 1.0, v239
	v_rcp_f32_e32 v1, v1
	v_rcp_f32_e32 v130, v130
	v_rcp_f32_e32 v238, v238
	v_rcp_f32_e32 v239, v239
	v_mul_f32_e32 v126, v126, v1
	v_mul_f32_e32 v127, v127, v130
	v_mul_f32_e32 v128, v128, v238
	v_mul_f32_e32 v129, v129, v239
	v_cvt_pk_bf16_f32 v126, v126, v127
	v_cvt_pk_bf16_f32 v127, v128, v129
	global_store_dwordx2 v236, v[126:127], s[10:11] offset:96 sc1
	s_branch .La1_done
.La1_p:
	s_mul_i32 s51, s1, 0x220000
	s_add_u32 s52, s28, s51
	s_addc_u32 s53, s29, 0
	s_add_u32 s52, s52, 0x2000
	s_addc_u32 s53, s53, 0
	s_mov_b32 m0, s8
	s_nop 0
	global_load_lds_dwordx4 v200, s[4:5]
	s_add_u32 m0, s8, 0x400
	s_nop 0
	global_load_lds_dwordx4 v201, s[4:5]
	s_add_u32 m0, s8, 0x800
	s_nop 0
	global_load_lds_dwordx4 v202, s[4:5]
	s_add_u32 m0, s8, 0xc00
	s_nop 0
	global_load_lds_dwordx4 v203, s[4:5]
	s_mov_b32 m0, s9
	s_nop 0
	global_load_lds_dwordx4 v204, s[6:7]
	s_add_u32 m0, s9, 0x400
	s_nop 0
	global_load_lds_dwordx4 v205, s[6:7]
	s_add_u32 s4, s4, 0x80
	s_addc_u32 s5, s5, 0
	s_add_u32 s6, s6, 0x80
	s_addc_u32 s7, s7, 0
	s_add_u32 m0, s8, 0xc000
	s_nop 0
	global_load_lds_dwordx4 v200, s[4:5]
	s_add_u32 m0, s8, 0xc400
	s_nop 0
	global_load_lds_dwordx4 v201, s[4:5]
	s_add_u32 m0, s8, 0xc800
	s_nop 0
	global_load_lds_dwordx4 v202, s[4:5]
	s_add_u32 m0, s8, 0xcc00
	s_nop 0
	global_load_lds_dwordx4 v203, s[4:5]
	s_add_u32 m0, s9, 0xc000
	s_nop 0
	global_load_lds_dwordx4 v204, s[6:7]
	s_add_u32 m0, s9, 0xc400
	s_nop 0
	global_load_lds_dwordx4 v205, s[6:7]
	s_add_u32 s4, s4, 0x80
	s_addc_u32 s5, s5, 0
	s_add_u32 s6, s6, 0x80
	s_addc_u32 s7, s7, 0
	s_add_u32 m0, s8, 0x18000
	s_nop 0
	global_load_lds_dwordx4 v200, s[4:5]
	s_add_u32 m0, s8, 0x18400
	s_nop 0
	global_load_lds_dwordx4 v201, s[4:5]
	s_add_u32 m0, s8, 0x18800
	s_nop 0
	global_load_lds_dwordx4 v202, s[4:5]
	s_add_u32 m0, s8, 0x18c00
	s_nop 0
	global_load_lds_dwordx4 v203, s[4:5]
	s_add_u32 m0, s9, 0x18000
	s_nop 0
	global_load_lds_dwordx4 v204, s[6:7]
	s_add_u32 m0, s9, 0x18400
	s_nop 0
	global_load_lds_dwordx4 v205, s[6:7]
	s_add_u32 s4, s4, 0x80
	s_addc_u32 s5, s5, 0
	s_add_u32 s6, s6, 0x80
	s_addc_u32 s7, s7, 0
	s_waitcnt vmcnt(12)
	s_barrier
	ds_read_b128 v[136:139], v218 offset:0
	ds_read_b128 v[140:143], v218 offset:2048
	ds_read_b128 v[144:147], v218 offset:4096
	ds_read_b128 v[148:151], v218 offset:6144
	ds_read_b128 v[152:155], v230 offset:0
	ds_read_b128 v[156:159], v230 offset:2048
	ds_read_b128 v[160:163], v230 offset:4096
	ds_read_b128 v[164:167], v230 offset:6144
	s_waitcnt lgkmcnt(0)
	v_mfma_f32_16x16x32_bf16 v[2:5], v[152:155], v[136:139], 0
	ds_read_b128 v[168:171], v225 offset:0
	v_mfma_f32_16x16x32_bf16 v[6:9], v[156:159], v[136:139], 0
	ds_read_b128 v[172:175], v225 offset:2048
	v_mfma_f32_16x16x32_bf16 v[10:13], v[160:163], v[136:139], 0
	ds_read_b128 v[176:179], v225 offset:4096
	v_mfma_f32_16x16x32_bf16 v[14:17], v[164:167], v[136:139], 0
	ds_read_b128 v[180:183], v225 offset:6144
	v_mfma_f32_16x16x32_bf16 v[18:21], v[152:155], v[140:143], 0
	ds_read_b128 v[184:187], v233 offset:0
	v_mfma_f32_16x16x32_bf16 v[22:25], v[156:159], v[140:143], 0
	ds_read_b128 v[188:191], v233 offset:2048
	v_mfma_f32_16x16x32_bf16 v[26:29], v[160:163], v[140:143], 0
	ds_read_b128 v[192:195], v233 offset:4096
	v_mfma_f32_16x16x32_bf16 v[30:33], v[164:167], v[140:143], 0
	ds_read_b128 v[196:199], v233 offset:6144
	v_mfma_f32_16x16x32_bf16 v[34:37], v[152:155], v[144:147], 0
	v_mfma_f32_16x16x32_bf16 v[38:41], v[156:159], v[144:147], 0
	v_mfma_f32_16x16x32_bf16 v[42:45], v[160:163], v[144:147], 0
	v_mfma_f32_16x16x32_bf16 v[46:49], v[164:167], v[144:147], 0
	v_mfma_f32_16x16x32_bf16 v[50:53], v[152:155], v[148:151], 0
	v_mfma_f32_16x16x32_bf16 v[54:57], v[156:159], v[148:151], 0
	v_mfma_f32_16x16x32_bf16 v[58:61], v[160:163], v[148:151], 0
	v_mfma_f32_16x16x32_bf16 v[62:65], v[164:167], v[148:151], 0
	s_waitcnt vmcnt(6) lgkmcnt(0)
	s_barrier
	v_mfma_f32_16x16x32_bf16 v[2:5], v[184:187], v[168:171], v[2:5]
	ds_read_b128 v[136:139], v219 offset:0
	v_mfma_f32_16x16x32_bf16 v[6:9], v[188:191], v[168:171], v[6:9]
	ds_read_b128 v[140:143], v219 offset:2048
	v_mfma_f32_16x16x32_bf16 v[10:13], v[192:195], v[168:171], v[10:13]
	ds_read_b128 v[144:147], v219 offset:4096
	v_mfma_f32_16x16x32_bf16 v[14:17], v[196:199], v[168:171], v[14:17]
	ds_read_b128 v[148:151], v219 offset:6144
	v_mfma_f32_16x16x32_bf16 v[18:21], v[184:187], v[172:175], v[18:21]
	ds_read_b128 v[152:155], v231 offset:0
	v_mfma_f32_16x16x32_bf16 v[22:25], v[188:191], v[172:175], v[22:25]
	ds_read_b128 v[156:159], v231 offset:2048
	v_mfma_f32_16x16x32_bf16 v[26:29], v[192:195], v[172:175], v[26:29]
	ds_read_b128 v[160:163], v231 offset:4096
	v_mfma_f32_16x16x32_bf16 v[30:33], v[196:199], v[172:175], v[30:33]
	ds_read_b128 v[164:167], v231 offset:6144
	s_mov_b32 m0, s8
	v_mfma_f32_16x16x32_bf16 v[34:37], v[184:187], v[176:179], v[34:37]
	global_load_lds_dwordx4 v200, s[4:5]
	s_add_u32 m0, s8, 0x400
	v_mfma_f32_16x16x32_bf16 v[38:41], v[188:191], v[176:179], v[38:41]
	global_load_lds_dwordx4 v201, s[4:5]
	s_add_u32 m0, s8, 0x800
	v_mfma_f32_16x16x32_bf16 v[42:45], v[192:195], v[176:179], v[42:45]
	global_load_lds_dwordx4 v202, s[4:5]
	s_add_u32 m0, s8, 0xc00
	v_mfma_f32_16x16x32_bf16 v[46:49], v[196:199], v[176:179], v[46:49]
	global_load_lds_dwordx4 v203, s[4:5]
	s_mov_b32 m0, s9
	v_mfma_f32_16x16x32_bf16 v[50:53], v[184:187], v[180:183], v[50:53]
	global_load_lds_dwordx4 v204, s[6:7]
	s_add_u32 m0, s9, 0x400
	v_mfma_f32_16x16x32_bf16 v[54:57], v[188:191], v[180:183], v[54:57]
	global_load_lds_dwordx4 v205, s[6:7]
	v_mfma_f32_16x16x32_bf16 v[58:61], v[192:195], v[180:183], v[58:61]
	s_add_u32 s4, s4, 0x80
	s_addc_u32 s5, s5, 0
	v_mfma_f32_16x16x32_bf16 v[62:65], v[196:199], v[180:183], v[62:65]
	s_add_u32 s6, s6, 0x80
	s_addc_u32 s7, s7, 0
	s_waitcnt lgkmcnt(0)
	v_mfma_f32_16x16x32_bf16 v[2:5], v[152:155], v[136:139], v[2:5]
	ds_read_b128 v[168:171], v228 offset:0
	v_mfma_f32_16x16x32_bf16 v[6:9], v[156:159], v[136:139], v[6:9]
	ds_read_b128 v[172:175], v228 offset:2048
	v_mfma_f32_16x16x32_bf16 v[10:13], v[160:163], v[136:139], v[10:13]
	ds_read_b128 v[176:179], v228 offset:4096
	v_mfma_f32_16x16x32_bf16 v[14:17], v[164:167], v[136:139], v[14:17]
	ds_read_b128 v[180:183], v228 offset:6144
	v_mfma_f32_16x16x32_bf16 v[18:21], v[152:155], v[140:143], v[18:21]
	ds_read_b128 v[184:187], v234 offset:0
	v_mfma_f32_16x16x32_bf16 v[22:25], v[156:159], v[140:143], v[22:25]
	ds_read_b128 v[188:191], v234 offset:2048
	v_mfma_f32_16x16x32_bf16 v[26:29], v[160:163], v[140:143], v[26:29]
	ds_read_b128 v[192:195], v234 offset:4096
	v_mfma_f32_16x16x32_bf16 v[30:33], v[164:167], v[140:143], v[30:33]
	ds_read_b128 v[196:199], v234 offset:6144
	v_mfma_f32_16x16x32_bf16 v[34:37], v[152:155], v[144:147], v[34:37]
	v_mfma_f32_16x16x32_bf16 v[38:41], v[156:159], v[144:147], v[38:41]
	v_mfma_f32_16x16x32_bf16 v[42:45], v[160:163], v[144:147], v[42:45]
	v_mfma_f32_16x16x32_bf16 v[46:49], v[164:167], v[144:147], v[46:49]
	v_mfma_f32_16x16x32_bf16 v[50:53], v[152:155], v[148:151], v[50:53]
	v_mfma_f32_16x16x32_bf16 v[54:57], v[156:159], v[148:151], v[54:57]
	v_mfma_f32_16x16x32_bf16 v[58:61], v[160:163], v[148:151], v[58:61]
	v_mfma_f32_16x16x32_bf16 v[62:65], v[164:167], v[148:151], v[62:65]
	s_waitcnt vmcnt(6) lgkmcnt(0)
	s_barrier
	v_mfma_f32_16x16x32_bf16 v[2:5], v[184:187], v[168:171], v[2:5]
	ds_read_b128 v[136:139], v224 offset:0
	v_mfma_f32_16x16x32_bf16 v[6:9], v[188:191], v[168:171], v[6:9]
	ds_read_b128 v[140:143], v224 offset:2048
	v_mfma_f32_16x16x32_bf16 v[10:13], v[192:195], v[168:171], v[10:13]
	ds_read_b128 v[144:147], v224 offset:4096
	v_mfma_f32_16x16x32_bf16 v[14:17], v[196:199], v[168:171], v[14:17]
	ds_read_b128 v[148:151], v224 offset:6144
	v_mfma_f32_16x16x32_bf16 v[18:21], v[184:187], v[172:175], v[18:21]
	ds_read_b128 v[152:155], v232 offset:0
	v_mfma_f32_16x16x32_bf16 v[22:25], v[188:191], v[172:175], v[22:25]
	ds_read_b128 v[156:159], v232 offset:2048
	v_mfma_f32_16x16x32_bf16 v[26:29], v[192:195], v[172:175], v[26:29]
	ds_read_b128 v[160:163], v232 offset:4096
	v_mfma_f32_16x16x32_bf16 v[30:33], v[196:199], v[172:175], v[30:33]
	ds_read_b128 v[164:167], v232 offset:6144
	s_add_u32 m0, s8, 0xc000
	v_mfma_f32_16x16x32_bf16 v[34:37], v[184:187], v[176:179], v[34:37]
	global_load_lds_dwordx4 v200, s[4:5]
	s_add_u32 m0, s8, 0xc400
	v_mfma_f32_16x16x32_bf16 v[38:41], v[188:191], v[176:179], v[38:41]
	global_load_lds_dwordx4 v201, s[4:5]
	s_add_u32 m0, s8, 0xc800
	v_mfma_f32_16x16x32_bf16 v[42:45], v[192:195], v[176:179], v[42:45]
	global_load_lds_dwordx4 v202, s[4:5]
	s_add_u32 m0, s8, 0xcc00
	v_mfma_f32_16x16x32_bf16 v[46:49], v[196:199], v[176:179], v[46:49]
	global_load_lds_dwordx4 v203, s[4:5]
	s_add_u32 m0, s9, 0xc000
	v_mfma_f32_16x16x32_bf16 v[50:53], v[184:187], v[180:183], v[50:53]
	global_load_lds_dwordx4 v204, s[6:7]
	s_add_u32 m0, s9, 0xc400
	v_mfma_f32_16x16x32_bf16 v[54:57], v[188:191], v[180:183], v[54:57]
	global_load_lds_dwordx4 v205, s[6:7]
	v_mfma_f32_16x16x32_bf16 v[58:61], v[192:195], v[180:183], v[58:61]
	s_add_u32 s4, s4, 0x80
	s_addc_u32 s5, s5, 0
	v_mfma_f32_16x16x32_bf16 v[62:65], v[196:199], v[180:183], v[62:65]
	s_add_u32 s6, s6, 0x80
	s_addc_u32 s7, s7, 0
	s_waitcnt lgkmcnt(0)
	v_mfma_f32_16x16x32_bf16 v[2:5], v[152:155], v[136:139], v[2:5]
	ds_read_b128 v[168:171], v229 offset:0
	v_mfma_f32_16x16x32_bf16 v[6:9], v[156:159], v[136:139], v[6:9]
	ds_read_b128 v[172:175], v229 offset:2048
	v_mfma_f32_16x16x32_bf16 v[10:13], v[160:163], v[136:139], v[10:13]
	ds_read_b128 v[176:179], v229 offset:4096
	v_mfma_f32_16x16x32_bf16 v[14:17], v[164:167], v[136:139], v[14:17]
	ds_read_b128 v[180:183], v229 offset:6144
	v_mfma_f32_16x16x32_bf16 v[18:21], v[152:155], v[140:143], v[18:21]
	ds_read_b128 v[184:187], v235 offset:0
	v_mfma_f32_16x16x32_bf16 v[22:25], v[156:159], v[140:143], v[22:25]
	ds_read_b128 v[188:191], v235 offset:2048
	v_mfma_f32_16x16x32_bf16 v[26:29], v[160:163], v[140:143], v[26:29]
	ds_read_b128 v[192:195], v235 offset:4096
	v_mfma_f32_16x16x32_bf16 v[30:33], v[164:167], v[140:143], v[30:33]
	ds_read_b128 v[196:199], v235 offset:6144
	v_mfma_f32_16x16x32_bf16 v[34:37], v[152:155], v[144:147], v[34:37]
	v_mfma_f32_16x16x32_bf16 v[38:41], v[156:159], v[144:147], v[38:41]
	v_mfma_f32_16x16x32_bf16 v[42:45], v[160:163], v[144:147], v[42:45]
	v_mfma_f32_16x16x32_bf16 v[46:49], v[164:167], v[144:147], v[46:49]
	v_mfma_f32_16x16x32_bf16 v[50:53], v[152:155], v[148:151], v[50:53]
	v_mfma_f32_16x16x32_bf16 v[54:57], v[156:159], v[148:151], v[54:57]
	v_mfma_f32_16x16x32_bf16 v[58:61], v[160:163], v[148:151], v[58:61]
	v_mfma_f32_16x16x32_bf16 v[62:65], v[164:167], v[148:151], v[62:65]
	s_waitcnt vmcnt(6) lgkmcnt(0)
	s_barrier
	v_mfma_f32_16x16x32_bf16 v[2:5], v[184:187], v[168:171], v[2:5]
	ds_read_b128 v[136:139], v218 offset:0
	v_mfma_f32_16x16x32_bf16 v[6:9], v[188:191], v[168:171], v[6:9]
	ds_read_b128 v[140:143], v218 offset:2048
	v_mfma_f32_16x16x32_bf16 v[10:13], v[192:195], v[168:171], v[10:13]
	ds_read_b128 v[144:147], v218 offset:4096
	v_mfma_f32_16x16x32_bf16 v[14:17], v[196:199], v[168:171], v[14:17]
	ds_read_b128 v[148:151], v218 offset:6144
	v_mfma_f32_16x16x32_bf16 v[18:21], v[184:187], v[172:175], v[18:21]
	ds_read_b128 v[152:155], v230 offset:0
	v_mfma_f32_16x16x32_bf16 v[22:25], v[188:191], v[172:175], v[22:25]
	ds_read_b128 v[156:159], v230 offset:2048
	v_mfma_f32_16x16x32_bf16 v[26:29], v[192:195], v[172:175], v[26:29]
	ds_read_b128 v[160:163], v230 offset:4096
	v_mfma_f32_16x16x32_bf16 v[30:33], v[196:199], v[172:175], v[30:33]
	ds_read_b128 v[164:167], v230 offset:6144
	s_add_u32 m0, s8, 0x18000
	v_mfma_f32_16x16x32_bf16 v[34:37], v[184:187], v[176:179], v[34:37]
	global_load_lds_dwordx4 v200, s[4:5]
	s_add_u32 m0, s8, 0x18400
	v_mfma_f32_16x16x32_bf16 v[38:41], v[188:191], v[176:179], v[38:41]
	global_load_lds_dwordx4 v201, s[4:5]
	s_add_u32 m0, s8, 0x18800
	v_mfma_f32_16x16x32_bf16 v[42:45], v[192:195], v[176:179], v[42:45]
	global_load_lds_dwordx4 v202, s[4:5]
	s_add_u32 m0, s8, 0x18c00
	v_mfma_f32_16x16x32_bf16 v[46:49], v[196:199], v[176:179], v[46:49]
	global_load_lds_dwordx4 v203, s[4:5]
	s_add_u32 m0, s9, 0x18000
	v_mfma_f32_16x16x32_bf16 v[50:53], v[184:187], v[180:183], v[50:53]
	global_load_lds_dwordx4 v204, s[6:7]
	s_add_u32 m0, s9, 0x18400
	v_mfma_f32_16x16x32_bf16 v[54:57], v[188:191], v[180:183], v[54:57]
	global_load_lds_dwordx4 v205, s[6:7]
	v_mfma_f32_16x16x32_bf16 v[58:61], v[192:195], v[180:183], v[58:61]
	s_add_u32 s4, s4, 0x80
	s_addc_u32 s5, s5, 0
	v_mfma_f32_16x16x32_bf16 v[62:65], v[196:199], v[180:183], v[62:65]
	s_add_u32 s6, s6, 0x80
	s_addc_u32 s7, s7, 0
	s_waitcnt lgkmcnt(0)
	v_mfma_f32_16x16x32_bf16 v[2:5], v[152:155], v[136:139], v[2:5]
	ds_read_b128 v[168:171], v225 offset:0
	v_mfma_f32_16x16x32_bf16 v[6:9], v[156:159], v[136:139], v[6:9]
	ds_read_b128 v[172:175], v225 offset:2048
	v_mfma_f32_16x16x32_bf16 v[10:13], v[160:163], v[136:139], v[10:13]
	ds_read_b128 v[176:179], v225 offset:4096
	v_mfma_f32_16x16x32_bf16 v[14:17], v[164:167], v[136:139], v[14:17]
	ds_read_b128 v[180:183], v225 offset:6144
	v_mfma_f32_16x16x32_bf16 v[18:21], v[152:155], v[140:143], v[18:21]
	ds_read_b128 v[184:187], v233 offset:0
	v_mfma_f32_16x16x32_bf16 v[22:25], v[156:159], v[140:143], v[22:25]
	ds_read_b128 v[188:191], v233 offset:2048
	v_mfma_f32_16x16x32_bf16 v[26:29], v[160:163], v[140:143], v[26:29]
	ds_read_b128 v[192:195], v233 offset:4096
	v_mfma_f32_16x16x32_bf16 v[30:33], v[164:167], v[140:143], v[30:33]
	ds_read_b128 v[196:199], v233 offset:6144
	v_mfma_f32_16x16x32_bf16 v[34:37], v[152:155], v[144:147], v[34:37]
	v_mfma_f32_16x16x32_bf16 v[38:41], v[156:159], v[144:147], v[38:41]
	v_mfma_f32_16x16x32_bf16 v[42:45], v[160:163], v[144:147], v[42:45]
	v_mfma_f32_16x16x32_bf16 v[46:49], v[164:167], v[144:147], v[46:49]
	v_mfma_f32_16x16x32_bf16 v[50:53], v[152:155], v[148:151], v[50:53]
	v_mfma_f32_16x16x32_bf16 v[54:57], v[156:159], v[148:151], v[54:57]
	v_mfma_f32_16x16x32_bf16 v[58:61], v[160:163], v[148:151], v[58:61]
	v_mfma_f32_16x16x32_bf16 v[62:65], v[164:167], v[148:151], v[62:65]
	s_waitcnt vmcnt(6) lgkmcnt(0)
	s_barrier
	v_mfma_f32_16x16x32_bf16 v[2:5], v[184:187], v[168:171], v[2:5]
	ds_read_b128 v[136:139], v219 offset:0
	v_mfma_f32_16x16x32_bf16 v[6:9], v[188:191], v[168:171], v[6:9]
	ds_read_b128 v[140:143], v219 offset:2048
	v_mfma_f32_16x16x32_bf16 v[10:13], v[192:195], v[168:171], v[10:13]
	ds_read_b128 v[144:147], v219 offset:4096
	v_mfma_f32_16x16x32_bf16 v[14:17], v[196:199], v[168:171], v[14:17]
	ds_read_b128 v[148:151], v219 offset:6144
	v_mfma_f32_16x16x32_bf16 v[18:21], v[184:187], v[172:175], v[18:21]
	ds_read_b128 v[152:155], v231 offset:0
	v_mfma_f32_16x16x32_bf16 v[22:25], v[188:191], v[172:175], v[22:25]
	ds_read_b128 v[156:159], v231 offset:2048
	v_mfma_f32_16x16x32_bf16 v[26:29], v[192:195], v[172:175], v[26:29]
	ds_read_b128 v[160:163], v231 offset:4096
	v_mfma_f32_16x16x32_bf16 v[30:33], v[196:199], v[172:175], v[30:33]
	ds_read_b128 v[164:167], v231 offset:6144
	s_mov_b32 m0, s8
	v_mfma_f32_16x16x32_bf16 v[34:37], v[184:187], v[176:179], v[34:37]
	global_load_lds_dwordx4 v200, s[4:5]
	s_add_u32 m0, s8, 0x400
	v_mfma_f32_16x16x32_bf16 v[38:41], v[188:191], v[176:179], v[38:41]
	global_load_lds_dwordx4 v201, s[4:5]
	s_add_u32 m0, s8, 0x800
	v_mfma_f32_16x16x32_bf16 v[42:45], v[192:195], v[176:179], v[42:45]
	global_load_lds_dwordx4 v202, s[4:5]
	s_add_u32 m0, s8, 0xc00
	v_mfma_f32_16x16x32_bf16 v[46:49], v[196:199], v[176:179], v[46:49]
	global_load_lds_dwordx4 v203, s[4:5]
	s_mov_b32 m0, s9
	v_mfma_f32_16x16x32_bf16 v[50:53], v[184:187], v[180:183], v[50:53]
	global_load_lds_dwordx4 v204, s[6:7]
	s_add_u32 m0, s9, 0x400
	v_mfma_f32_16x16x32_bf16 v[54:57], v[188:191], v[180:183], v[54:57]
	global_load_lds_dwordx4 v205, s[6:7]
	v_mfma_f32_16x16x32_bf16 v[58:61], v[192:195], v[180:183], v[58:61]
	s_add_u32 s4, s4, 0x80
	s_addc_u32 s5, s5, 0
	v_mfma_f32_16x16x32_bf16 v[62:65], v[196:199], v[180:183], v[62:65]
	s_add_u32 s6, s6, 0x80
	s_addc_u32 s7, s7, 0
	s_waitcnt lgkmcnt(0)
	v_mfma_f32_16x16x32_bf16 v[2:5], v[152:155], v[136:139], v[2:5]
	ds_read_b128 v[168:171], v228 offset:0
	v_mfma_f32_16x16x32_bf16 v[6:9], v[156:159], v[136:139], v[6:9]
	ds_read_b128 v[172:175], v228 offset:2048
	v_mfma_f32_16x16x32_bf16 v[10:13], v[160:163], v[136:139], v[10:13]
	ds_read_b128 v[176:179], v228 offset:4096
	v_mfma_f32_16x16x32_bf16 v[14:17], v[164:167], v[136:139], v[14:17]
	ds_read_b128 v[180:183], v228 offset:6144
	v_mfma_f32_16x16x32_bf16 v[18:21], v[152:155], v[140:143], v[18:21]
	ds_read_b128 v[184:187], v234 offset:0
	v_mfma_f32_16x16x32_bf16 v[22:25], v[156:159], v[140:143], v[22:25]
	ds_read_b128 v[188:191], v234 offset:2048
	v_mfma_f32_16x16x32_bf16 v[26:29], v[160:163], v[140:143], v[26:29]
	ds_read_b128 v[192:195], v234 offset:4096
	v_mfma_f32_16x16x32_bf16 v[30:33], v[164:167], v[140:143], v[30:33]
	ds_read_b128 v[196:199], v234 offset:6144
	v_mfma_f32_16x16x32_bf16 v[34:37], v[152:155], v[144:147], v[34:37]
	v_mfma_f32_16x16x32_bf16 v[38:41], v[156:159], v[144:147], v[38:41]
	v_mfma_f32_16x16x32_bf16 v[42:45], v[160:163], v[144:147], v[42:45]
	v_mfma_f32_16x16x32_bf16 v[46:49], v[164:167], v[144:147], v[46:49]
	v_mfma_f32_16x16x32_bf16 v[50:53], v[152:155], v[148:151], v[50:53]
	v_mfma_f32_16x16x32_bf16 v[54:57], v[156:159], v[148:151], v[54:57]
	v_mfma_f32_16x16x32_bf16 v[58:61], v[160:163], v[148:151], v[58:61]
	v_mfma_f32_16x16x32_bf16 v[62:65], v[164:167], v[148:151], v[62:65]
	s_waitcnt vmcnt(6) lgkmcnt(0)
	s_barrier
	v_mfma_f32_16x16x32_bf16 v[2:5], v[184:187], v[168:171], v[2:5]
	ds_read_b128 v[136:139], v224 offset:0
	v_mfma_f32_16x16x32_bf16 v[6:9], v[188:191], v[168:171], v[6:9]
	ds_read_b128 v[140:143], v224 offset:2048
	v_mfma_f32_16x16x32_bf16 v[10:13], v[192:195], v[168:171], v[10:13]
	ds_read_b128 v[144:147], v224 offset:4096
	v_mfma_f32_16x16x32_bf16 v[14:17], v[196:199], v[168:171], v[14:17]
	ds_read_b128 v[148:151], v224 offset:6144
	v_mfma_f32_16x16x32_bf16 v[18:21], v[184:187], v[172:175], v[18:21]
	ds_read_b128 v[152:155], v232 offset:0
	v_mfma_f32_16x16x32_bf16 v[22:25], v[188:191], v[172:175], v[22:25]
	ds_read_b128 v[156:159], v232 offset:2048
	v_mfma_f32_16x16x32_bf16 v[26:29], v[192:195], v[172:175], v[26:29]
	ds_read_b128 v[160:163], v232 offset:4096
	v_mfma_f32_16x16x32_bf16 v[30:33], v[196:199], v[172:175], v[30:33]
	ds_read_b128 v[164:167], v232 offset:6144
	s_add_u32 m0, s8, 0xc000
	v_mfma_f32_16x16x32_bf16 v[34:37], v[184:187], v[176:179], v[34:37]
	global_load_lds_dwordx4 v200, s[4:5]
	s_add_u32 m0, s8, 0xc400
	v_mfma_f32_16x16x32_bf16 v[38:41], v[188:191], v[176:179], v[38:41]
	global_load_lds_dwordx4 v201, s[4:5]
	s_add_u32 m0, s8, 0xc800
	v_mfma_f32_16x16x32_bf16 v[42:45], v[192:195], v[176:179], v[42:45]
	global_load_lds_dwordx4 v202, s[4:5]
	s_add_u32 m0, s8, 0xcc00
	v_mfma_f32_16x16x32_bf16 v[46:49], v[196:199], v[176:179], v[46:49]
	global_load_lds_dwordx4 v203, s[4:5]
	s_add_u32 m0, s9, 0xc000
	v_mfma_f32_16x16x32_bf16 v[50:53], v[184:187], v[180:183], v[50:53]
	global_load_lds_dwordx4 v204, s[6:7]
	s_add_u32 m0, s9, 0xc400
	v_mfma_f32_16x16x32_bf16 v[54:57], v[188:191], v[180:183], v[54:57]
	global_load_lds_dwordx4 v205, s[6:7]
	v_mfma_f32_16x16x32_bf16 v[58:61], v[192:195], v[180:183], v[58:61]
	s_add_u32 s4, s4, 0x80
	s_addc_u32 s5, s5, 0
	v_mfma_f32_16x16x32_bf16 v[62:65], v[196:199], v[180:183], v[62:65]
	s_add_u32 s6, s6, 0x80
	s_addc_u32 s7, s7, 0
	s_waitcnt lgkmcnt(0)
	v_mfma_f32_16x16x32_bf16 v[2:5], v[152:155], v[136:139], v[2:5]
	ds_read_b128 v[168:171], v229 offset:0
	v_mfma_f32_16x16x32_bf16 v[6:9], v[156:159], v[136:139], v[6:9]
	ds_read_b128 v[172:175], v229 offset:2048
	v_mfma_f32_16x16x32_bf16 v[10:13], v[160:163], v[136:139], v[10:13]
	ds_read_b128 v[176:179], v229 offset:4096
	v_mfma_f32_16x16x32_bf16 v[14:17], v[164:167], v[136:139], v[14:17]
	ds_read_b128 v[180:183], v229 offset:6144
	v_mfma_f32_16x16x32_bf16 v[18:21], v[152:155], v[140:143], v[18:21]
	ds_read_b128 v[184:187], v235 offset:0
	v_mfma_f32_16x16x32_bf16 v[22:25], v[156:159], v[140:143], v[22:25]
	ds_read_b128 v[188:191], v235 offset:2048
	v_mfma_f32_16x16x32_bf16 v[26:29], v[160:163], v[140:143], v[26:29]
	ds_read_b128 v[192:195], v235 offset:4096
	v_mfma_f32_16x16x32_bf16 v[30:33], v[164:167], v[140:143], v[30:33]
	ds_read_b128 v[196:199], v235 offset:6144
	v_mfma_f32_16x16x32_bf16 v[34:37], v[152:155], v[144:147], v[34:37]
	v_mfma_f32_16x16x32_bf16 v[38:41], v[156:159], v[144:147], v[38:41]
	v_mfma_f32_16x16x32_bf16 v[42:45], v[160:163], v[144:147], v[42:45]
	v_mfma_f32_16x16x32_bf16 v[46:49], v[164:167], v[144:147], v[46:49]
	v_mfma_f32_16x16x32_bf16 v[50:53], v[152:155], v[148:151], v[50:53]
	v_mfma_f32_16x16x32_bf16 v[54:57], v[156:159], v[148:151], v[54:57]
	v_mfma_f32_16x16x32_bf16 v[58:61], v[160:163], v[148:151], v[58:61]
	v_mfma_f32_16x16x32_bf16 v[62:65], v[164:167], v[148:151], v[62:65]
	s_waitcnt vmcnt(6) lgkmcnt(0)
	s_barrier
	v_mfma_f32_16x16x32_bf16 v[2:5], v[184:187], v[168:171], v[2:5]
	ds_read_b128 v[136:139], v218 offset:0
	v_mfma_f32_16x16x32_bf16 v[6:9], v[188:191], v[168:171], v[6:9]
	ds_read_b128 v[140:143], v218 offset:2048
	v_mfma_f32_16x16x32_bf16 v[10:13], v[192:195], v[168:171], v[10:13]
	ds_read_b128 v[144:147], v218 offset:4096
	v_mfma_f32_16x16x32_bf16 v[14:17], v[196:199], v[168:171], v[14:17]
	ds_read_b128 v[148:151], v218 offset:6144
	v_mfma_f32_16x16x32_bf16 v[18:21], v[184:187], v[172:175], v[18:21]
	ds_read_b128 v[152:155], v230 offset:0
	v_mfma_f32_16x16x32_bf16 v[22:25], v[188:191], v[172:175], v[22:25]
	ds_read_b128 v[156:159], v230 offset:2048
	v_mfma_f32_16x16x32_bf16 v[26:29], v[192:195], v[172:175], v[26:29]
	ds_read_b128 v[160:163], v230 offset:4096
	v_mfma_f32_16x16x32_bf16 v[30:33], v[196:199], v[172:175], v[30:33]
	ds_read_b128 v[164:167], v230 offset:6144
	s_add_u32 m0, s8, 0x18000
	v_mfma_f32_16x16x32_bf16 v[34:37], v[184:187], v[176:179], v[34:37]
	global_load_lds_dwordx4 v200, s[4:5]
	s_add_u32 m0, s8, 0x18400
	v_mfma_f32_16x16x32_bf16 v[38:41], v[188:191], v[176:179], v[38:41]
	global_load_lds_dwordx4 v201, s[4:5]
	s_add_u32 m0, s8, 0x18800
	v_mfma_f32_16x16x32_bf16 v[42:45], v[192:195], v[176:179], v[42:45]
	global_load_lds_dwordx4 v202, s[4:5]
	s_add_u32 m0, s8, 0x18c00
	v_mfma_f32_16x16x32_bf16 v[46:49], v[196:199], v[176:179], v[46:49]
	global_load_lds_dwordx4 v203, s[4:5]
	s_add_u32 m0, s9, 0x18000
	v_mfma_f32_16x16x32_bf16 v[50:53], v[184:187], v[180:183], v[50:53]
	global_load_lds_dwordx4 v204, s[6:7]
	s_add_u32 m0, s9, 0x18400
	v_mfma_f32_16x16x32_bf16 v[54:57], v[188:191], v[180:183], v[54:57]
	global_load_lds_dwordx4 v205, s[6:7]
	v_mfma_f32_16x16x32_bf16 v[58:61], v[192:195], v[180:183], v[58:61]
	s_add_u32 s4, s4, 0x80
	s_addc_u32 s5, s5, 0
	v_mfma_f32_16x16x32_bf16 v[62:65], v[196:199], v[180:183], v[62:65]
	s_add_u32 s6, s6, 0x80
	s_addc_u32 s7, s7, 0
	s_waitcnt lgkmcnt(0)
	v_mfma_f32_16x16x32_bf16 v[2:5], v[152:155], v[136:139], v[2:5]
	ds_read_b128 v[168:171], v225 offset:0
	v_mfma_f32_16x16x32_bf16 v[6:9], v[156:159], v[136:139], v[6:9]
	ds_read_b128 v[172:175], v225 offset:2048
	v_mfma_f32_16x16x32_bf16 v[10:13], v[160:163], v[136:139], v[10:13]
	ds_read_b128 v[176:179], v225 offset:4096
	v_mfma_f32_16x16x32_bf16 v[14:17], v[164:167], v[136:139], v[14:17]
	ds_read_b128 v[180:183], v225 offset:6144
	v_mfma_f32_16x16x32_bf16 v[18:21], v[152:155], v[140:143], v[18:21]
	ds_read_b128 v[184:187], v233 offset:0
	v_mfma_f32_16x16x32_bf16 v[22:25], v[156:159], v[140:143], v[22:25]
	ds_read_b128 v[188:191], v233 offset:2048
	v_mfma_f32_16x16x32_bf16 v[26:29], v[160:163], v[140:143], v[26:29]
	ds_read_b128 v[192:195], v233 offset:4096
	v_mfma_f32_16x16x32_bf16 v[30:33], v[164:167], v[140:143], v[30:33]
	ds_read_b128 v[196:199], v233 offset:6144
	v_mfma_f32_16x16x32_bf16 v[34:37], v[152:155], v[144:147], v[34:37]
	v_mfma_f32_16x16x32_bf16 v[38:41], v[156:159], v[144:147], v[38:41]
	v_mfma_f32_16x16x32_bf16 v[42:45], v[160:163], v[144:147], v[42:45]
	v_mfma_f32_16x16x32_bf16 v[46:49], v[164:167], v[144:147], v[46:49]
	v_mfma_f32_16x16x32_bf16 v[50:53], v[152:155], v[148:151], v[50:53]
	v_mfma_f32_16x16x32_bf16 v[54:57], v[156:159], v[148:151], v[54:57]
	v_mfma_f32_16x16x32_bf16 v[58:61], v[160:163], v[148:151], v[58:61]
	v_mfma_f32_16x16x32_bf16 v[62:65], v[164:167], v[148:151], v[62:65]
	s_waitcnt vmcnt(6) lgkmcnt(0)
	s_barrier
	v_mfma_f32_16x16x32_bf16 v[2:5], v[184:187], v[168:171], v[2:5]
	ds_read_b128 v[136:139], v219 offset:0
	v_mfma_f32_16x16x32_bf16 v[6:9], v[188:191], v[168:171], v[6:9]
	ds_read_b128 v[140:143], v219 offset:2048
	v_mfma_f32_16x16x32_bf16 v[10:13], v[192:195], v[168:171], v[10:13]
	ds_read_b128 v[144:147], v219 offset:4096
	v_mfma_f32_16x16x32_bf16 v[14:17], v[196:199], v[168:171], v[14:17]
	ds_read_b128 v[148:151], v219 offset:6144
	v_mfma_f32_16x16x32_bf16 v[18:21], v[184:187], v[172:175], v[18:21]
	ds_read_b128 v[152:155], v231 offset:0
	v_mfma_f32_16x16x32_bf16 v[22:25], v[188:191], v[172:175], v[22:25]
	ds_read_b128 v[156:159], v231 offset:2048
	v_mfma_f32_16x16x32_bf16 v[26:29], v[192:195], v[172:175], v[26:29]
	ds_read_b128 v[160:163], v231 offset:4096
	v_mfma_f32_16x16x32_bf16 v[30:33], v[196:199], v[172:175], v[30:33]
	ds_read_b128 v[164:167], v231 offset:6144
	s_mov_b32 m0, s8
	v_mfma_f32_16x16x32_bf16 v[34:37], v[184:187], v[176:179], v[34:37]
	global_load_lds_dwordx4 v200, s[4:5]
	s_add_u32 m0, s8, 0x400
	v_mfma_f32_16x16x32_bf16 v[38:41], v[188:191], v[176:179], v[38:41]
	global_load_lds_dwordx4 v201, s[4:5]
	s_add_u32 m0, s8, 0x800
	v_mfma_f32_16x16x32_bf16 v[42:45], v[192:195], v[176:179], v[42:45]
	global_load_lds_dwordx4 v202, s[4:5]
	s_add_u32 m0, s8, 0xc00
	v_mfma_f32_16x16x32_bf16 v[46:49], v[196:199], v[176:179], v[46:49]
	global_load_lds_dwordx4 v203, s[4:5]
	s_mov_b32 m0, s9
	v_mfma_f32_16x16x32_bf16 v[50:53], v[184:187], v[180:183], v[50:53]
	global_load_lds_dwordx4 v204, s[6:7]
	s_add_u32 m0, s9, 0x400
	v_mfma_f32_16x16x32_bf16 v[54:57], v[188:191], v[180:183], v[54:57]
	global_load_lds_dwordx4 v205, s[6:7]
	v_mfma_f32_16x16x32_bf16 v[58:61], v[192:195], v[180:183], v[58:61]
	s_add_u32 s4, s4, 0x80
	s_addc_u32 s5, s5, 0
	v_mfma_f32_16x16x32_bf16 v[62:65], v[196:199], v[180:183], v[62:65]
	s_add_u32 s6, s6, 0x80
	s_addc_u32 s7, s7, 0
	s_waitcnt lgkmcnt(0)
	v_mfma_f32_16x16x32_bf16 v[2:5], v[152:155], v[136:139], v[2:5]
	ds_read_b128 v[168:171], v228 offset:0
	v_mfma_f32_16x16x32_bf16 v[6:9], v[156:159], v[136:139], v[6:9]
	ds_read_b128 v[172:175], v228 offset:2048
	v_mfma_f32_16x16x32_bf16 v[10:13], v[160:163], v[136:139], v[10:13]
	ds_read_b128 v[176:179], v228 offset:4096
	v_mfma_f32_16x16x32_bf16 v[14:17], v[164:167], v[136:139], v[14:17]
	ds_read_b128 v[180:183], v228 offset:6144
	v_mfma_f32_16x16x32_bf16 v[18:21], v[152:155], v[140:143], v[18:21]
	ds_read_b128 v[184:187], v234 offset:0
	v_mfma_f32_16x16x32_bf16 v[22:25], v[156:159], v[140:143], v[22:25]
	ds_read_b128 v[188:191], v234 offset:2048
	v_mfma_f32_16x16x32_bf16 v[26:29], v[160:163], v[140:143], v[26:29]
	ds_read_b128 v[192:195], v234 offset:4096
	v_mfma_f32_16x16x32_bf16 v[30:33], v[164:167], v[140:143], v[30:33]
	ds_read_b128 v[196:199], v234 offset:6144
	v_mfma_f32_16x16x32_bf16 v[34:37], v[152:155], v[144:147], v[34:37]
	v_mfma_f32_16x16x32_bf16 v[38:41], v[156:159], v[144:147], v[38:41]
	v_mfma_f32_16x16x32_bf16 v[42:45], v[160:163], v[144:147], v[42:45]
	v_mfma_f32_16x16x32_bf16 v[46:49], v[164:167], v[144:147], v[46:49]
	v_mfma_f32_16x16x32_bf16 v[50:53], v[152:155], v[148:151], v[50:53]
	v_mfma_f32_16x16x32_bf16 v[54:57], v[156:159], v[148:151], v[54:57]
	v_mfma_f32_16x16x32_bf16 v[58:61], v[160:163], v[148:151], v[58:61]
	v_mfma_f32_16x16x32_bf16 v[62:65], v[164:167], v[148:151], v[62:65]
	s_waitcnt vmcnt(6) lgkmcnt(0)
	s_barrier
	v_mfma_f32_16x16x32_bf16 v[2:5], v[184:187], v[168:171], v[2:5]
	ds_read_b128 v[136:139], v224 offset:0
	v_mfma_f32_16x16x32_bf16 v[6:9], v[188:191], v[168:171], v[6:9]
	ds_read_b128 v[140:143], v224 offset:2048
	v_mfma_f32_16x16x32_bf16 v[10:13], v[192:195], v[168:171], v[10:13]
	ds_read_b128 v[144:147], v224 offset:4096
	v_mfma_f32_16x16x32_bf16 v[14:17], v[196:199], v[168:171], v[14:17]
	ds_read_b128 v[148:151], v224 offset:6144
	v_mfma_f32_16x16x32_bf16 v[18:21], v[184:187], v[172:175], v[18:21]
	ds_read_b128 v[152:155], v232 offset:0
	v_mfma_f32_16x16x32_bf16 v[22:25], v[188:191], v[172:175], v[22:25]
	ds_read_b128 v[156:159], v232 offset:2048
	v_mfma_f32_16x16x32_bf16 v[26:29], v[192:195], v[172:175], v[26:29]
	ds_read_b128 v[160:163], v232 offset:4096
	v_mfma_f32_16x16x32_bf16 v[30:33], v[196:199], v[172:175], v[30:33]
	ds_read_b128 v[164:167], v232 offset:6144
	s_add_u32 m0, s8, 0xc000
	v_mfma_f32_16x16x32_bf16 v[34:37], v[184:187], v[176:179], v[34:37]
	global_load_lds_dwordx4 v200, s[4:5]
	s_add_u32 m0, s8, 0xc400
	v_mfma_f32_16x16x32_bf16 v[38:41], v[188:191], v[176:179], v[38:41]
	global_load_lds_dwordx4 v201, s[4:5]
	s_add_u32 m0, s8, 0xc800
	v_mfma_f32_16x16x32_bf16 v[42:45], v[192:195], v[176:179], v[42:45]
	global_load_lds_dwordx4 v202, s[4:5]
	s_add_u32 m0, s8, 0xcc00
	v_mfma_f32_16x16x32_bf16 v[46:49], v[196:199], v[176:179], v[46:49]
	global_load_lds_dwordx4 v203, s[4:5]
	s_add_u32 m0, s9, 0xc000
	v_mfma_f32_16x16x32_bf16 v[50:53], v[184:187], v[180:183], v[50:53]
	global_load_lds_dwordx4 v204, s[6:7]
	s_add_u32 m0, s9, 0xc400
	v_mfma_f32_16x16x32_bf16 v[54:57], v[188:191], v[180:183], v[54:57]
	global_load_lds_dwordx4 v205, s[6:7]
	v_mfma_f32_16x16x32_bf16 v[58:61], v[192:195], v[180:183], v[58:61]
	s_add_u32 s4, s4, 0x80
	s_addc_u32 s5, s5, 0
	v_mfma_f32_16x16x32_bf16 v[62:65], v[196:199], v[180:183], v[62:65]
	s_add_u32 s6, s6, 0x80
	s_addc_u32 s7, s7, 0
	s_waitcnt lgkmcnt(0)
	v_mfma_f32_16x16x32_bf16 v[2:5], v[152:155], v[136:139], v[2:5]
	ds_read_b128 v[168:171], v229 offset:0
	v_mfma_f32_16x16x32_bf16 v[6:9], v[156:159], v[136:139], v[6:9]
	ds_read_b128 v[172:175], v229 offset:2048
	v_mfma_f32_16x16x32_bf16 v[10:13], v[160:163], v[136:139], v[10:13]
	ds_read_b128 v[176:179], v229 offset:4096
	v_mfma_f32_16x16x32_bf16 v[14:17], v[164:167], v[136:139], v[14:17]
	ds_read_b128 v[180:183], v229 offset:6144
	v_mfma_f32_16x16x32_bf16 v[18:21], v[152:155], v[140:143], v[18:21]
	ds_read_b128 v[184:187], v235 offset:0
	v_mfma_f32_16x16x32_bf16 v[22:25], v[156:159], v[140:143], v[22:25]
	ds_read_b128 v[188:191], v235 offset:2048
	v_mfma_f32_16x16x32_bf16 v[26:29], v[160:163], v[140:143], v[26:29]
	ds_read_b128 v[192:195], v235 offset:4096
	v_mfma_f32_16x16x32_bf16 v[30:33], v[164:167], v[140:143], v[30:33]
	ds_read_b128 v[196:199], v235 offset:6144
	v_mfma_f32_16x16x32_bf16 v[34:37], v[152:155], v[144:147], v[34:37]
	v_mfma_f32_16x16x32_bf16 v[38:41], v[156:159], v[144:147], v[38:41]
	v_mfma_f32_16x16x32_bf16 v[42:45], v[160:163], v[144:147], v[42:45]
	v_mfma_f32_16x16x32_bf16 v[46:49], v[164:167], v[144:147], v[46:49]
	v_mfma_f32_16x16x32_bf16 v[50:53], v[152:155], v[148:151], v[50:53]
	v_mfma_f32_16x16x32_bf16 v[54:57], v[156:159], v[148:151], v[54:57]
	v_mfma_f32_16x16x32_bf16 v[58:61], v[160:163], v[148:151], v[58:61]
	v_mfma_f32_16x16x32_bf16 v[62:65], v[164:167], v[148:151], v[62:65]
	s_waitcnt vmcnt(6) lgkmcnt(0)
	s_barrier
	v_mfma_f32_16x16x32_bf16 v[2:5], v[184:187], v[168:171], v[2:5]
	ds_read_b128 v[136:139], v218 offset:0
	v_mfma_f32_16x16x32_bf16 v[6:9], v[188:191], v[168:171], v[6:9]
	ds_read_b128 v[140:143], v218 offset:2048
	v_mfma_f32_16x16x32_bf16 v[10:13], v[192:195], v[168:171], v[10:13]
	ds_read_b128 v[144:147], v218 offset:4096
	v_mfma_f32_16x16x32_bf16 v[14:17], v[196:199], v[168:171], v[14:17]
	ds_read_b128 v[148:151], v218 offset:6144
	v_mfma_f32_16x16x32_bf16 v[18:21], v[184:187], v[172:175], v[18:21]
	ds_read_b128 v[152:155], v230 offset:0
	v_mfma_f32_16x16x32_bf16 v[22:25], v[188:191], v[172:175], v[22:25]
	ds_read_b128 v[156:159], v230 offset:2048
	v_mfma_f32_16x16x32_bf16 v[26:29], v[192:195], v[172:175], v[26:29]
	ds_read_b128 v[160:163], v230 offset:4096
	v_mfma_f32_16x16x32_bf16 v[30:33], v[196:199], v[172:175], v[30:33]
	ds_read_b128 v[164:167], v230 offset:6144
	s_add_u32 m0, s8, 0x18000
	v_mfma_f32_16x16x32_bf16 v[34:37], v[184:187], v[176:179], v[34:37]
	global_load_lds_dwordx4 v200, s[4:5]
	s_add_u32 m0, s8, 0x18400
	v_mfma_f32_16x16x32_bf16 v[38:41], v[188:191], v[176:179], v[38:41]
	global_load_lds_dwordx4 v201, s[4:5]
	s_add_u32 m0, s8, 0x18800
	v_mfma_f32_16x16x32_bf16 v[42:45], v[192:195], v[176:179], v[42:45]
	global_load_lds_dwordx4 v202, s[4:5]
	s_add_u32 m0, s8, 0x18c00
	v_mfma_f32_16x16x32_bf16 v[46:49], v[196:199], v[176:179], v[46:49]
	global_load_lds_dwordx4 v203, s[4:5]
	s_add_u32 m0, s9, 0x18000
	v_mfma_f32_16x16x32_bf16 v[50:53], v[184:187], v[180:183], v[50:53]
	global_load_lds_dwordx4 v204, s[6:7]
	s_add_u32 m0, s9, 0x18400
	v_mfma_f32_16x16x32_bf16 v[54:57], v[188:191], v[180:183], v[54:57]
	global_load_lds_dwordx4 v205, s[6:7]
	v_mfma_f32_16x16x32_bf16 v[58:61], v[192:195], v[180:183], v[58:61]
	s_add_u32 s4, s4, 0x80
	s_addc_u32 s5, s5, 0
	v_mfma_f32_16x16x32_bf16 v[62:65], v[196:199], v[180:183], v[62:65]
	s_add_u32 s6, s6, 0x80
	s_addc_u32 s7, s7, 0
	s_waitcnt lgkmcnt(0)
	v_mfma_f32_16x16x32_bf16 v[2:5], v[152:155], v[136:139], v[2:5]
	ds_read_b128 v[168:171], v225 offset:0
	v_mfma_f32_16x16x32_bf16 v[6:9], v[156:159], v[136:139], v[6:9]
	ds_read_b128 v[172:175], v225 offset:2048
	v_mfma_f32_16x16x32_bf16 v[10:13], v[160:163], v[136:139], v[10:13]
	ds_read_b128 v[176:179], v225 offset:4096
	v_mfma_f32_16x16x32_bf16 v[14:17], v[164:167], v[136:139], v[14:17]
	ds_read_b128 v[180:183], v225 offset:6144
	v_mfma_f32_16x16x32_bf16 v[18:21], v[152:155], v[140:143], v[18:21]
	ds_read_b128 v[184:187], v233 offset:0
	v_mfma_f32_16x16x32_bf16 v[22:25], v[156:159], v[140:143], v[22:25]
	ds_read_b128 v[188:191], v233 offset:2048
	v_mfma_f32_16x16x32_bf16 v[26:29], v[160:163], v[140:143], v[26:29]
	ds_read_b128 v[192:195], v233 offset:4096
	v_mfma_f32_16x16x32_bf16 v[30:33], v[164:167], v[140:143], v[30:33]
	ds_read_b128 v[196:199], v233 offset:6144
	v_mfma_f32_16x16x32_bf16 v[34:37], v[152:155], v[144:147], v[34:37]
	v_mfma_f32_16x16x32_bf16 v[38:41], v[156:159], v[144:147], v[38:41]
	v_mfma_f32_16x16x32_bf16 v[42:45], v[160:163], v[144:147], v[42:45]
	v_mfma_f32_16x16x32_bf16 v[46:49], v[164:167], v[144:147], v[46:49]
	v_mfma_f32_16x16x32_bf16 v[50:53], v[152:155], v[148:151], v[50:53]
	v_mfma_f32_16x16x32_bf16 v[54:57], v[156:159], v[148:151], v[54:57]
	v_mfma_f32_16x16x32_bf16 v[58:61], v[160:163], v[148:151], v[58:61]
	v_mfma_f32_16x16x32_bf16 v[62:65], v[164:167], v[148:151], v[62:65]
	s_waitcnt vmcnt(6) lgkmcnt(0)
	s_barrier
	v_mfma_f32_16x16x32_bf16 v[2:5], v[184:187], v[168:171], v[2:5]
	ds_read_b128 v[136:139], v219 offset:0
	v_mfma_f32_16x16x32_bf16 v[6:9], v[188:191], v[168:171], v[6:9]
	ds_read_b128 v[140:143], v219 offset:2048
	v_mfma_f32_16x16x32_bf16 v[10:13], v[192:195], v[168:171], v[10:13]
	ds_read_b128 v[144:147], v219 offset:4096
	v_mfma_f32_16x16x32_bf16 v[14:17], v[196:199], v[168:171], v[14:17]
	ds_read_b128 v[148:151], v219 offset:6144
	v_mfma_f32_16x16x32_bf16 v[18:21], v[184:187], v[172:175], v[18:21]
	ds_read_b128 v[152:155], v231 offset:0
	v_mfma_f32_16x16x32_bf16 v[22:25], v[188:191], v[172:175], v[22:25]
	ds_read_b128 v[156:159], v231 offset:2048
	v_mfma_f32_16x16x32_bf16 v[26:29], v[192:195], v[172:175], v[26:29]
	ds_read_b128 v[160:163], v231 offset:4096
	v_mfma_f32_16x16x32_bf16 v[30:33], v[196:199], v[172:175], v[30:33]
	ds_read_b128 v[164:167], v231 offset:6144
	s_mov_b32 m0, s8
	v_mfma_f32_16x16x32_bf16 v[34:37], v[184:187], v[176:179], v[34:37]
	global_load_lds_dwordx4 v200, s[4:5]
	s_add_u32 m0, s8, 0x400
	v_mfma_f32_16x16x32_bf16 v[38:41], v[188:191], v[176:179], v[38:41]
	global_load_lds_dwordx4 v201, s[4:5]
	s_add_u32 m0, s8, 0x800
	v_mfma_f32_16x16x32_bf16 v[42:45], v[192:195], v[176:179], v[42:45]
	global_load_lds_dwordx4 v202, s[4:5]
	s_add_u32 m0, s8, 0xc00
	v_mfma_f32_16x16x32_bf16 v[46:49], v[196:199], v[176:179], v[46:49]
	global_load_lds_dwordx4 v203, s[4:5]
	s_mov_b32 m0, s9
	v_mfma_f32_16x16x32_bf16 v[50:53], v[184:187], v[180:183], v[50:53]
	global_load_lds_dwordx4 v204, s[6:7]
	s_add_u32 m0, s9, 0x400
	v_mfma_f32_16x16x32_bf16 v[54:57], v[188:191], v[180:183], v[54:57]
	global_load_lds_dwordx4 v205, s[6:7]
	v_mfma_f32_16x16x32_bf16 v[58:61], v[192:195], v[180:183], v[58:61]
	s_add_u32 s4, s4, 0x80
	s_addc_u32 s5, s5, 0
	v_mfma_f32_16x16x32_bf16 v[62:65], v[196:199], v[180:183], v[62:65]
	s_add_u32 s6, s6, 0x80
	s_addc_u32 s7, s7, 0
	s_waitcnt lgkmcnt(0)
	v_mfma_f32_16x16x32_bf16 v[2:5], v[152:155], v[136:139], v[2:5]
	ds_read_b128 v[168:171], v228 offset:0
	v_mfma_f32_16x16x32_bf16 v[6:9], v[156:159], v[136:139], v[6:9]
	ds_read_b128 v[172:175], v228 offset:2048
	v_mfma_f32_16x16x32_bf16 v[10:13], v[160:163], v[136:139], v[10:13]
	ds_read_b128 v[176:179], v228 offset:4096
	v_mfma_f32_16x16x32_bf16 v[14:17], v[164:167], v[136:139], v[14:17]
	ds_read_b128 v[180:183], v228 offset:6144
	v_mfma_f32_16x16x32_bf16 v[18:21], v[152:155], v[140:143], v[18:21]
	ds_read_b128 v[184:187], v234 offset:0
	v_mfma_f32_16x16x32_bf16 v[22:25], v[156:159], v[140:143], v[22:25]
	ds_read_b128 v[188:191], v234 offset:2048
	v_mfma_f32_16x16x32_bf16 v[26:29], v[160:163], v[140:143], v[26:29]
	ds_read_b128 v[192:195], v234 offset:4096
	v_mfma_f32_16x16x32_bf16 v[30:33], v[164:167], v[140:143], v[30:33]
	ds_read_b128 v[196:199], v234 offset:6144
	v_mfma_f32_16x16x32_bf16 v[34:37], v[152:155], v[144:147], v[34:37]
	v_mfma_f32_16x16x32_bf16 v[38:41], v[156:159], v[144:147], v[38:41]
	v_mfma_f32_16x16x32_bf16 v[42:45], v[160:163], v[144:147], v[42:45]
	v_mfma_f32_16x16x32_bf16 v[46:49], v[164:167], v[144:147], v[46:49]
	v_mfma_f32_16x16x32_bf16 v[50:53], v[152:155], v[148:151], v[50:53]
	v_mfma_f32_16x16x32_bf16 v[54:57], v[156:159], v[148:151], v[54:57]
	v_mfma_f32_16x16x32_bf16 v[58:61], v[160:163], v[148:151], v[58:61]
	v_mfma_f32_16x16x32_bf16 v[62:65], v[164:167], v[148:151], v[62:65]
	s_waitcnt vmcnt(6) lgkmcnt(0)
	s_barrier
	v_mfma_f32_16x16x32_bf16 v[2:5], v[184:187], v[168:171], v[2:5]
	ds_read_b128 v[136:139], v224 offset:0
	v_mfma_f32_16x16x32_bf16 v[6:9], v[188:191], v[168:171], v[6:9]
	ds_read_b128 v[140:143], v224 offset:2048
	v_mfma_f32_16x16x32_bf16 v[10:13], v[192:195], v[168:171], v[10:13]
	ds_read_b128 v[144:147], v224 offset:4096
	v_mfma_f32_16x16x32_bf16 v[14:17], v[196:199], v[168:171], v[14:17]
	ds_read_b128 v[148:151], v224 offset:6144
	v_mfma_f32_16x16x32_bf16 v[18:21], v[184:187], v[172:175], v[18:21]
	ds_read_b128 v[152:155], v232 offset:0
	v_mfma_f32_16x16x32_bf16 v[22:25], v[188:191], v[172:175], v[22:25]
	ds_read_b128 v[156:159], v232 offset:2048
	v_mfma_f32_16x16x32_bf16 v[26:29], v[192:195], v[172:175], v[26:29]
	ds_read_b128 v[160:163], v232 offset:4096
	v_mfma_f32_16x16x32_bf16 v[30:33], v[196:199], v[172:175], v[30:33]
	ds_read_b128 v[164:167], v232 offset:6144
	s_add_u32 m0, s8, 0xc000
	v_mfma_f32_16x16x32_bf16 v[34:37], v[184:187], v[176:179], v[34:37]
	global_load_lds_dwordx4 v200, s[4:5]
	s_add_u32 m0, s8, 0xc400
	v_mfma_f32_16x16x32_bf16 v[38:41], v[188:191], v[176:179], v[38:41]
	global_load_lds_dwordx4 v201, s[4:5]
	s_add_u32 m0, s8, 0xc800
	v_mfma_f32_16x16x32_bf16 v[42:45], v[192:195], v[176:179], v[42:45]
	global_load_lds_dwordx4 v202, s[4:5]
	s_add_u32 m0, s8, 0xcc00
	v_mfma_f32_16x16x32_bf16 v[46:49], v[196:199], v[176:179], v[46:49]
	global_load_lds_dwordx4 v203, s[4:5]
	s_add_u32 m0, s9, 0xc000
	v_mfma_f32_16x16x32_bf16 v[50:53], v[184:187], v[180:183], v[50:53]
	global_load_lds_dwordx4 v204, s[6:7]
	s_add_u32 m0, s9, 0xc400
	v_mfma_f32_16x16x32_bf16 v[54:57], v[188:191], v[180:183], v[54:57]
	global_load_lds_dwordx4 v205, s[6:7]
	v_mfma_f32_16x16x32_bf16 v[58:61], v[192:195], v[180:183], v[58:61]
	s_add_u32 s4, s4, 0x80
	s_addc_u32 s5, s5, 0
	v_mfma_f32_16x16x32_bf16 v[62:65], v[196:199], v[180:183], v[62:65]
	s_add_u32 s6, s6, 0x80
	s_addc_u32 s7, s7, 0
	s_waitcnt lgkmcnt(0)
	v_mfma_f32_16x16x32_bf16 v[2:5], v[152:155], v[136:139], v[2:5]
	ds_read_b128 v[168:171], v229 offset:0
	v_mfma_f32_16x16x32_bf16 v[6:9], v[156:159], v[136:139], v[6:9]
	ds_read_b128 v[172:175], v229 offset:2048
	v_mfma_f32_16x16x32_bf16 v[10:13], v[160:163], v[136:139], v[10:13]
	ds_read_b128 v[176:179], v229 offset:4096
	v_mfma_f32_16x16x32_bf16 v[14:17], v[164:167], v[136:139], v[14:17]
	ds_read_b128 v[180:183], v229 offset:6144
	v_mfma_f32_16x16x32_bf16 v[18:21], v[152:155], v[140:143], v[18:21]
	ds_read_b128 v[184:187], v235 offset:0
	v_mfma_f32_16x16x32_bf16 v[22:25], v[156:159], v[140:143], v[22:25]
	ds_read_b128 v[188:191], v235 offset:2048
	v_mfma_f32_16x16x32_bf16 v[26:29], v[160:163], v[140:143], v[26:29]
	ds_read_b128 v[192:195], v235 offset:4096
	v_mfma_f32_16x16x32_bf16 v[30:33], v[164:167], v[140:143], v[30:33]
	ds_read_b128 v[196:199], v235 offset:6144
	v_mfma_f32_16x16x32_bf16 v[34:37], v[152:155], v[144:147], v[34:37]
	v_mfma_f32_16x16x32_bf16 v[38:41], v[156:159], v[144:147], v[38:41]
	v_mfma_f32_16x16x32_bf16 v[42:45], v[160:163], v[144:147], v[42:45]
	v_mfma_f32_16x16x32_bf16 v[46:49], v[164:167], v[144:147], v[46:49]
	v_mfma_f32_16x16x32_bf16 v[50:53], v[152:155], v[148:151], v[50:53]
	v_mfma_f32_16x16x32_bf16 v[54:57], v[156:159], v[148:151], v[54:57]
	v_mfma_f32_16x16x32_bf16 v[58:61], v[160:163], v[148:151], v[58:61]
	v_mfma_f32_16x16x32_bf16 v[62:65], v[164:167], v[148:151], v[62:65]
	s_waitcnt vmcnt(6) lgkmcnt(0)
	s_barrier
	v_mfma_f32_16x16x32_bf16 v[2:5], v[184:187], v[168:171], v[2:5]
	ds_read_b128 v[136:139], v218 offset:0
	v_mfma_f32_16x16x32_bf16 v[6:9], v[188:191], v[168:171], v[6:9]
	ds_read_b128 v[140:143], v218 offset:2048
	v_mfma_f32_16x16x32_bf16 v[10:13], v[192:195], v[168:171], v[10:13]
	ds_read_b128 v[144:147], v218 offset:4096
	v_mfma_f32_16x16x32_bf16 v[14:17], v[196:199], v[168:171], v[14:17]
	ds_read_b128 v[148:151], v218 offset:6144
	v_mfma_f32_16x16x32_bf16 v[18:21], v[184:187], v[172:175], v[18:21]
	ds_read_b128 v[152:155], v230 offset:0
	v_mfma_f32_16x16x32_bf16 v[22:25], v[188:191], v[172:175], v[22:25]
	ds_read_b128 v[156:159], v230 offset:2048
	v_mfma_f32_16x16x32_bf16 v[26:29], v[192:195], v[172:175], v[26:29]
	ds_read_b128 v[160:163], v230 offset:4096
	v_mfma_f32_16x16x32_bf16 v[30:33], v[196:199], v[172:175], v[30:33]
	ds_read_b128 v[164:167], v230 offset:6144
	s_add_u32 m0, s8, 0x18000
	v_mfma_f32_16x16x32_bf16 v[34:37], v[184:187], v[176:179], v[34:37]
	global_load_lds_dwordx4 v200, s[4:5]
	s_add_u32 m0, s8, 0x18400
	v_mfma_f32_16x16x32_bf16 v[38:41], v[188:191], v[176:179], v[38:41]
	global_load_lds_dwordx4 v201, s[4:5]
	s_add_u32 m0, s8, 0x18800
	v_mfma_f32_16x16x32_bf16 v[42:45], v[192:195], v[176:179], v[42:45]
	global_load_lds_dwordx4 v202, s[4:5]
	s_add_u32 m0, s8, 0x18c00
	v_mfma_f32_16x16x32_bf16 v[46:49], v[196:199], v[176:179], v[46:49]
	global_load_lds_dwordx4 v203, s[4:5]
	s_add_u32 m0, s9, 0x18000
	v_mfma_f32_16x16x32_bf16 v[50:53], v[184:187], v[180:183], v[50:53]
	global_load_lds_dwordx4 v204, s[6:7]
	s_add_u32 m0, s9, 0x18400
	v_mfma_f32_16x16x32_bf16 v[54:57], v[188:191], v[180:183], v[54:57]
	global_load_lds_dwordx4 v205, s[6:7]
	v_mfma_f32_16x16x32_bf16 v[58:61], v[192:195], v[180:183], v[58:61]
	s_add_u32 s4, s4, 0x80
	s_addc_u32 s5, s5, 0
	v_mfma_f32_16x16x32_bf16 v[62:65], v[196:199], v[180:183], v[62:65]
	s_add_u32 s6, s6, 0x80
	s_addc_u32 s7, s7, 0
	s_waitcnt lgkmcnt(0)
	v_mfma_f32_16x16x32_bf16 v[2:5], v[152:155], v[136:139], v[2:5]
	ds_read_b128 v[168:171], v225 offset:0
	v_mfma_f32_16x16x32_bf16 v[6:9], v[156:159], v[136:139], v[6:9]
	ds_read_b128 v[172:175], v225 offset:2048
	v_mfma_f32_16x16x32_bf16 v[10:13], v[160:163], v[136:139], v[10:13]
	ds_read_b128 v[176:179], v225 offset:4096
	v_mfma_f32_16x16x32_bf16 v[14:17], v[164:167], v[136:139], v[14:17]
	ds_read_b128 v[180:183], v225 offset:6144
	v_mfma_f32_16x16x32_bf16 v[18:21], v[152:155], v[140:143], v[18:21]
	ds_read_b128 v[184:187], v233 offset:0
	v_mfma_f32_16x16x32_bf16 v[22:25], v[156:159], v[140:143], v[22:25]
	ds_read_b128 v[188:191], v233 offset:2048
	v_mfma_f32_16x16x32_bf16 v[26:29], v[160:163], v[140:143], v[26:29]
	ds_read_b128 v[192:195], v233 offset:4096
	v_mfma_f32_16x16x32_bf16 v[30:33], v[164:167], v[140:143], v[30:33]
	ds_read_b128 v[196:199], v233 offset:6144
	v_mfma_f32_16x16x32_bf16 v[34:37], v[152:155], v[144:147], v[34:37]
	v_mfma_f32_16x16x32_bf16 v[38:41], v[156:159], v[144:147], v[38:41]
	v_mfma_f32_16x16x32_bf16 v[42:45], v[160:163], v[144:147], v[42:45]
	v_mfma_f32_16x16x32_bf16 v[46:49], v[164:167], v[144:147], v[46:49]
	v_mfma_f32_16x16x32_bf16 v[50:53], v[152:155], v[148:151], v[50:53]
	v_mfma_f32_16x16x32_bf16 v[54:57], v[156:159], v[148:151], v[54:57]
	v_mfma_f32_16x16x32_bf16 v[58:61], v[160:163], v[148:151], v[58:61]
	v_mfma_f32_16x16x32_bf16 v[62:65], v[164:167], v[148:151], v[62:65]
	s_waitcnt vmcnt(6) lgkmcnt(0)
	s_barrier
	v_mfma_f32_16x16x32_bf16 v[2:5], v[184:187], v[168:171], v[2:5]
	ds_read_b128 v[136:139], v219 offset:0
	v_mfma_f32_16x16x32_bf16 v[6:9], v[188:191], v[168:171], v[6:9]
	ds_read_b128 v[140:143], v219 offset:2048
	v_mfma_f32_16x16x32_bf16 v[10:13], v[192:195], v[168:171], v[10:13]
	ds_read_b128 v[144:147], v219 offset:4096
	v_mfma_f32_16x16x32_bf16 v[14:17], v[196:199], v[168:171], v[14:17]
	ds_read_b128 v[148:151], v219 offset:6144
	v_mfma_f32_16x16x32_bf16 v[18:21], v[184:187], v[172:175], v[18:21]
	ds_read_b128 v[152:155], v231 offset:0
	v_mfma_f32_16x16x32_bf16 v[22:25], v[188:191], v[172:175], v[22:25]
	ds_read_b128 v[156:159], v231 offset:2048
	v_mfma_f32_16x16x32_bf16 v[26:29], v[192:195], v[172:175], v[26:29]
	ds_read_b128 v[160:163], v231 offset:4096
	v_mfma_f32_16x16x32_bf16 v[30:33], v[196:199], v[172:175], v[30:33]
	ds_read_b128 v[164:167], v231 offset:6144
	s_mov_b32 m0, s8
	v_mfma_f32_16x16x32_bf16 v[34:37], v[184:187], v[176:179], v[34:37]
	global_load_lds_dwordx4 v200, s[4:5]
	s_add_u32 m0, s8, 0x400
	v_mfma_f32_16x16x32_bf16 v[38:41], v[188:191], v[176:179], v[38:41]
	global_load_lds_dwordx4 v201, s[4:5]
	s_add_u32 m0, s8, 0x800
	v_mfma_f32_16x16x32_bf16 v[42:45], v[192:195], v[176:179], v[42:45]
	global_load_lds_dwordx4 v202, s[4:5]
	s_add_u32 m0, s8, 0xc00
	v_mfma_f32_16x16x32_bf16 v[46:49], v[196:199], v[176:179], v[46:49]
	global_load_lds_dwordx4 v203, s[4:5]
	s_mov_b32 m0, s9
	v_mfma_f32_16x16x32_bf16 v[50:53], v[184:187], v[180:183], v[50:53]
	global_load_lds_dwordx4 v204, s[6:7]
	s_add_u32 m0, s9, 0x400
	v_mfma_f32_16x16x32_bf16 v[54:57], v[188:191], v[180:183], v[54:57]
	global_load_lds_dwordx4 v205, s[6:7]
	v_mfma_f32_16x16x32_bf16 v[58:61], v[192:195], v[180:183], v[58:61]
	s_sub_u32 s4, s4, 0x780
	s_subb_u32 s5, s5, 0
	v_mfma_f32_16x16x32_bf16 v[62:65], v[196:199], v[180:183], v[62:65]
	s_add_u32 s6, s6, 0x3f880
	s_addc_u32 s7, s7, 0
	s_waitcnt lgkmcnt(0)
	v_mfma_f32_16x16x32_bf16 v[2:5], v[152:155], v[136:139], v[2:5]
	ds_read_b128 v[168:171], v228 offset:0
	v_mfma_f32_16x16x32_bf16 v[6:9], v[156:159], v[136:139], v[6:9]
	ds_read_b128 v[172:175], v228 offset:2048
	v_mfma_f32_16x16x32_bf16 v[10:13], v[160:163], v[136:139], v[10:13]
	ds_read_b128 v[176:179], v228 offset:4096
	v_mfma_f32_16x16x32_bf16 v[14:17], v[164:167], v[136:139], v[14:17]
	ds_read_b128 v[180:183], v228 offset:6144
	v_mfma_f32_16x16x32_bf16 v[18:21], v[152:155], v[140:143], v[18:21]
	ds_read_b128 v[184:187], v234 offset:0
	v_mfma_f32_16x16x32_bf16 v[22:25], v[156:159], v[140:143], v[22:25]
	ds_read_b128 v[188:191], v234 offset:2048
	v_mfma_f32_16x16x32_bf16 v[26:29], v[160:163], v[140:143], v[26:29]
	ds_read_b128 v[192:195], v234 offset:4096
	v_mfma_f32_16x16x32_bf16 v[30:33], v[164:167], v[140:143], v[30:33]
	ds_read_b128 v[196:199], v234 offset:6144
	v_mfma_f32_16x16x32_bf16 v[34:37], v[152:155], v[144:147], v[34:37]
	v_mfma_f32_16x16x32_bf16 v[38:41], v[156:159], v[144:147], v[38:41]
	v_mfma_f32_16x16x32_bf16 v[42:45], v[160:163], v[144:147], v[42:45]
	v_mfma_f32_16x16x32_bf16 v[46:49], v[164:167], v[144:147], v[46:49]
	v_mfma_f32_16x16x32_bf16 v[50:53], v[152:155], v[148:151], v[50:53]
	v_mfma_f32_16x16x32_bf16 v[54:57], v[156:159], v[148:151], v[54:57]
	v_mfma_f32_16x16x32_bf16 v[58:61], v[160:163], v[148:151], v[58:61]
	v_mfma_f32_16x16x32_bf16 v[62:65], v[164:167], v[148:151], v[62:65]
	s_waitcnt vmcnt(6) lgkmcnt(0)
	s_barrier
	v_mfma_f32_16x16x32_bf16 v[2:5], v[184:187], v[168:171], v[2:5]
	ds_read_b128 v[136:139], v224 offset:0
	v_mfma_f32_16x16x32_bf16 v[6:9], v[188:191], v[168:171], v[6:9]
	ds_read_b128 v[140:143], v224 offset:2048
	v_mfma_f32_16x16x32_bf16 v[10:13], v[192:195], v[168:171], v[10:13]
	ds_read_b128 v[144:147], v224 offset:4096
	v_mfma_f32_16x16x32_bf16 v[14:17], v[196:199], v[168:171], v[14:17]
	ds_read_b128 v[148:151], v224 offset:6144
	v_mfma_f32_16x16x32_bf16 v[18:21], v[184:187], v[172:175], v[18:21]
	ds_read_b128 v[152:155], v232 offset:0
	v_mfma_f32_16x16x32_bf16 v[22:25], v[188:191], v[172:175], v[22:25]
	ds_read_b128 v[156:159], v232 offset:2048
	v_mfma_f32_16x16x32_bf16 v[26:29], v[192:195], v[172:175], v[26:29]
	ds_read_b128 v[160:163], v232 offset:4096
	v_mfma_f32_16x16x32_bf16 v[30:33], v[196:199], v[172:175], v[30:33]
	ds_read_b128 v[164:167], v232 offset:6144
	v_mfma_f32_16x16x32_bf16 v[34:37], v[184:187], v[176:179], v[34:37]
	v_mfma_f32_16x16x32_bf16 v[38:41], v[188:191], v[176:179], v[38:41]
	v_mfma_f32_16x16x32_bf16 v[42:45], v[192:195], v[176:179], v[42:45]
	v_mfma_f32_16x16x32_bf16 v[46:49], v[196:199], v[176:179], v[46:49]
	v_mfma_f32_16x16x32_bf16 v[50:53], v[184:187], v[180:183], v[50:53]
	v_mfma_f32_16x16x32_bf16 v[54:57], v[188:191], v[180:183], v[54:57]
	v_mfma_f32_16x16x32_bf16 v[58:61], v[192:195], v[180:183], v[58:61]
	v_mfma_f32_16x16x32_bf16 v[62:65], v[196:199], v[180:183], v[62:65]
	s_waitcnt lgkmcnt(0)
	v_mfma_f32_16x16x32_bf16 v[2:5], v[152:155], v[136:139], v[2:5]
	ds_read_b128 v[168:171], v229 offset:0
	v_mfma_f32_16x16x32_bf16 v[6:9], v[156:159], v[136:139], v[6:9]
	ds_read_b128 v[172:175], v229 offset:2048
	v_mfma_f32_16x16x32_bf16 v[10:13], v[160:163], v[136:139], v[10:13]
	ds_read_b128 v[176:179], v229 offset:4096
	v_mfma_f32_16x16x32_bf16 v[14:17], v[164:167], v[136:139], v[14:17]
	ds_read_b128 v[180:183], v229 offset:6144
	v_mfma_f32_16x16x32_bf16 v[18:21], v[152:155], v[140:143], v[18:21]
	ds_read_b128 v[184:187], v235 offset:0
	v_mfma_f32_16x16x32_bf16 v[22:25], v[156:159], v[140:143], v[22:25]
	ds_read_b128 v[188:191], v235 offset:2048
	v_mfma_f32_16x16x32_bf16 v[26:29], v[160:163], v[140:143], v[26:29]
	ds_read_b128 v[192:195], v235 offset:4096
	v_mfma_f32_16x16x32_bf16 v[30:33], v[164:167], v[140:143], v[30:33]
	ds_read_b128 v[196:199], v235 offset:6144
	v_mfma_f32_16x16x32_bf16 v[34:37], v[152:155], v[144:147], v[34:37]
	v_mfma_f32_16x16x32_bf16 v[38:41], v[156:159], v[144:147], v[38:41]
	v_mfma_f32_16x16x32_bf16 v[42:45], v[160:163], v[144:147], v[42:45]
	v_mfma_f32_16x16x32_bf16 v[46:49], v[164:167], v[144:147], v[46:49]
	v_mfma_f32_16x16x32_bf16 v[50:53], v[152:155], v[148:151], v[50:53]
	v_mfma_f32_16x16x32_bf16 v[54:57], v[156:159], v[148:151], v[54:57]
	v_mfma_f32_16x16x32_bf16 v[58:61], v[160:163], v[148:151], v[58:61]
	v_mfma_f32_16x16x32_bf16 v[62:65], v[164:167], v[148:151], v[62:65]
	s_waitcnt vmcnt(0) lgkmcnt(0)
	s_barrier
	v_mfma_f32_16x16x32_bf16 v[2:5], v[184:187], v[168:171], v[2:5]
	ds_read_b128 v[136:139], v218 offset:0
	v_mfma_f32_16x16x32_bf16 v[6:9], v[188:191], v[168:171], v[6:9]
	ds_read_b128 v[140:143], v218 offset:2048
	v_mfma_f32_16x16x32_bf16 v[10:13], v[192:195], v[168:171], v[10:13]
	ds_read_b128 v[144:147], v218 offset:4096
	v_mfma_f32_16x16x32_bf16 v[14:17], v[196:199], v[168:171], v[14:17]
	ds_read_b128 v[148:151], v218 offset:6144
	v_mfma_f32_16x16x32_bf16 v[18:21], v[184:187], v[172:175], v[18:21]
	ds_read_b128 v[152:155], v230 offset:0
	v_mfma_f32_16x16x32_bf16 v[22:25], v[188:191], v[172:175], v[22:25]
	ds_read_b128 v[156:159], v230 offset:2048
	v_mfma_f32_16x16x32_bf16 v[26:29], v[192:195], v[172:175], v[26:29]
	ds_read_b128 v[160:163], v230 offset:4096
	v_mfma_f32_16x16x32_bf16 v[30:33], v[196:199], v[172:175], v[30:33]
	ds_read_b128 v[164:167], v230 offset:6144
	v_mfma_f32_16x16x32_bf16 v[34:37], v[184:187], v[176:179], v[34:37]
	v_mfma_f32_16x16x32_bf16 v[38:41], v[188:191], v[176:179], v[38:41]
	v_mfma_f32_16x16x32_bf16 v[42:45], v[192:195], v[176:179], v[42:45]
	v_mfma_f32_16x16x32_bf16 v[46:49], v[196:199], v[176:179], v[46:49]
	v_mfma_f32_16x16x32_bf16 v[50:53], v[184:187], v[180:183], v[50:53]
	v_mfma_f32_16x16x32_bf16 v[54:57], v[188:191], v[180:183], v[54:57]
	v_mfma_f32_16x16x32_bf16 v[58:61], v[192:195], v[180:183], v[58:61]
	v_mfma_f32_16x16x32_bf16 v[62:65], v[196:199], v[180:183], v[62:65]
	s_waitcnt lgkmcnt(0)
	v_mfma_f32_16x16x32_bf16 v[2:5], v[152:155], v[136:139], v[2:5]
	ds_read_b128 v[168:171], v225 offset:0
	v_mfma_f32_16x16x32_bf16 v[6:9], v[156:159], v[136:139], v[6:9]
	ds_read_b128 v[172:175], v225 offset:2048
	v_mfma_f32_16x16x32_bf16 v[10:13], v[160:163], v[136:139], v[10:13]
	ds_read_b128 v[176:179], v225 offset:4096
	v_mfma_f32_16x16x32_bf16 v[14:17], v[164:167], v[136:139], v[14:17]
	ds_read_b128 v[180:183], v225 offset:6144
	v_mfma_f32_16x16x32_bf16 v[18:21], v[152:155], v[140:143], v[18:21]
	ds_read_b128 v[184:187], v233 offset:0
	v_mfma_f32_16x16x32_bf16 v[22:25], v[156:159], v[140:143], v[22:25]
	ds_read_b128 v[188:191], v233 offset:2048
	v_mfma_f32_16x16x32_bf16 v[26:29], v[160:163], v[140:143], v[26:29]
	ds_read_b128 v[192:195], v233 offset:4096
	v_mfma_f32_16x16x32_bf16 v[30:33], v[164:167], v[140:143], v[30:33]
	ds_read_b128 v[196:199], v233 offset:6144
	v_mfma_f32_16x16x32_bf16 v[34:37], v[152:155], v[144:147], v[34:37]
	v_mfma_f32_16x16x32_bf16 v[38:41], v[156:159], v[144:147], v[38:41]
	v_mfma_f32_16x16x32_bf16 v[42:45], v[160:163], v[144:147], v[42:45]
	v_mfma_f32_16x16x32_bf16 v[46:49], v[164:167], v[144:147], v[46:49]
	v_mfma_f32_16x16x32_bf16 v[50:53], v[152:155], v[148:151], v[50:53]
	v_mfma_f32_16x16x32_bf16 v[54:57], v[156:159], v[148:151], v[54:57]
	v_mfma_f32_16x16x32_bf16 v[58:61], v[160:163], v[148:151], v[58:61]
	v_mfma_f32_16x16x32_bf16 v[62:65], v[164:167], v[148:151], v[62:65]
	s_waitcnt lgkmcnt(0)
	v_mfma_f32_16x16x32_bf16 v[2:5], v[184:187], v[168:171], v[2:5]
	v_mfma_f32_16x16x32_bf16 v[6:9], v[188:191], v[168:171], v[6:9]
	v_mfma_f32_16x16x32_bf16 v[10:13], v[192:195], v[168:171], v[10:13]
	v_mfma_f32_16x16x32_bf16 v[14:17], v[196:199], v[168:171], v[14:17]
	v_mfma_f32_16x16x32_bf16 v[18:21], v[184:187], v[172:175], v[18:21]
	v_mfma_f32_16x16x32_bf16 v[22:25], v[188:191], v[172:175], v[22:25]
	v_mfma_f32_16x16x32_bf16 v[26:29], v[192:195], v[172:175], v[26:29]
	v_mfma_f32_16x16x32_bf16 v[30:33], v[196:199], v[172:175], v[30:33]
	v_mfma_f32_16x16x32_bf16 v[34:37], v[184:187], v[176:179], v[34:37]
	v_mfma_f32_16x16x32_bf16 v[38:41], v[188:191], v[176:179], v[38:41]
	v_mfma_f32_16x16x32_bf16 v[42:45], v[192:195], v[176:179], v[42:45]
	v_mfma_f32_16x16x32_bf16 v[46:49], v[196:199], v[176:179], v[46:49]
	v_mfma_f32_16x16x32_bf16 v[50:53], v[184:187], v[180:183], v[50:53]
	v_mfma_f32_16x16x32_bf16 v[54:57], v[188:191], v[180:183], v[54:57]
	v_mfma_f32_16x16x32_bf16 v[58:61], v[192:195], v[180:183], v[58:61]
	v_mfma_f32_16x16x32_bf16 v[62:65], v[196:199], v[180:183], v[62:65]
	s_nop 7
	s_add_u32 s10, s52, 0x0
	s_addc_u32 s11, s53, 0
	global_store_dwordx4 v237, v[2:5], s[10:11] offset:0 sc1
	global_store_dwordx4 v237, v[6:9], s[10:11] offset:64 sc1
	global_store_dwordx4 v237, v[10:13], s[10:11] offset:128 sc1
	global_store_dwordx4 v237, v[14:17], s[10:11] offset:192 sc1
	s_add_u32 s10, s10, 0x22000
	s_addc_u32 s11, s11, 0
	global_store_dwordx4 v237, v[18:21], s[10:11] offset:0 sc1
	global_store_dwordx4 v237, v[22:25], s[10:11] offset:64 sc1
	global_store_dwordx4 v237, v[26:29], s[10:11] offset:128 sc1
	global_store_dwordx4 v237, v[30:33], s[10:11] offset:192 sc1
	s_add_u32 s10, s10, 0x22000
	s_addc_u32 s11, s11, 0
	global_store_dwordx4 v237, v[34:37], s[10:11] offset:0 sc1
	global_store_dwordx4 v237, v[38:41], s[10:11] offset:64 sc1
	global_store_dwordx4 v237, v[42:45], s[10:11] offset:128 sc1
	global_store_dwordx4 v237, v[46:49], s[10:11] offset:192 sc1
	s_add_u32 s10, s10, 0x22000
	s_addc_u32 s11, s11, 0
	global_store_dwordx4 v237, v[50:53], s[10:11] offset:0 sc1
	global_store_dwordx4 v237, v[54:57], s[10:11] offset:64 sc1
	global_store_dwordx4 v237, v[58:61], s[10:11] offset:128 sc1
	global_store_dwordx4 v237, v[62:65], s[10:11] offset:192 sc1
	s_waitcnt lgkmcnt(0)
	s_barrier
	s_branch .La1_zz

.Ldf_qpoll:
	global_load_dword v2, v131, s[4:5] sc1
	s_waitcnt vmcnt(0)
	v_readfirstlane_b32 s1, v2
	s_cmpk_ge_u32 s1, 0x80
	s_cbranch_scc1 .Ldf_qok
	s_sleep 16
	s_add_u32 s6, s6, 1
	s_cmp_lt_u32 s6, 0x1388
	s_cbranch_scc1 .Ldf_qpoll
